# P5 chunk precompute: pre-conv row loads software-pipelined one token group ahead (fresh registers by lifetime, counted waits); on top of v19
# speedup vs baseline: 1.0085x; 1.0005x over previous
.LBB0_1066:
	v_lshl_add_u64 v[44:45], v[22:23], 1, s[6:7]
	s_movk_i32 s2, 0xfc00
	v_add_co_u32_e32 v30, vcc, s2, v44
	s_movk_i32 s4, 0x1000
	s_nop 0
	v_addc_co_u32_e32 v31, vcc, -1, v45, vcc
	global_load_ushort v17, v[30:31], off
	v_add_co_u32_e32 v30, vcc, s4, v44
	s_waitcnt vmcnt(0)
	v_mul_f32_e32 v16, v5, v16
	v_addc_co_u32_e32 v31, vcc, 0, v45, vcc
	v_add_co_u32_e32 v48, vcc, s14, v44
	v_fmac_f32_e32 v16, v9, v70
	s_nop 0
	v_addc_co_u32_e32 v49, vcc, 0, v45, vcc
	global_load_ushort v54, v[30:31], off offset:3072
	global_load_ushort v71, v[30:31], off
	global_load_ushort v47, v[48:49], off
	global_load_ushort v50, v[30:31], off offset:1024
	global_load_ushort v52, v[44:45], off offset:3072
	global_load_ushort v55, v[48:49], off offset:3072
	global_load_ushort v72, v[44:45], off
	v_fmac_f32_e32 v16, v7, v46
	v_mov_b32_e32 v57, 0
	v_mul_f32_e32 v32, 0xbfb8aa3b, v14
	v_exp_f32_e32 v62, v32
	v_mov_b32_e32 v60, 0
	v_add_co_u32_e32 v58, vcc, s12, v44
	s_mov_b64 s[2:3], 0x4000
	s_nop 0
	v_addc_co_u32_e32 v59, vcc, 0, v45, vcc
	global_load_ushort v56, v[44:45], off offset:1024
	global_load_ushort v69, v[58:59], off
	global_load_ushort v53, v[58:59], off offset:1024
	global_load_ushort v51, v[48:49], off offset:1024
	v_add_f32_e32 v48, 1.0, v62
	v_mov_b32_e32 v61, 0
	v_lshl_add_u64 v[32:33], v[44:45], 0, s[2:3]
	v_add_co_u32_e32 v36, vcc, s13, v44
	v_div_scale_f32 v49, s[2:3], v48, v48, 1.0
	s_movk_i32 s4, 0x5000
	v_addc_co_u32_e32 v37, vcc, 0, v45, vcc
	v_rcp_f32_e32 v62, v49
	v_add_co_u32_e32 v42, vcc, s4, v44
	s_movk_i32 s18, 0x6000
	s_nop 0
	v_addc_co_u32_e32 v43, vcc, 0, v45, vcc
	v_add_co_u32_e32 v38, vcc, s18, v44
	v_fma_f32 v67, -v49, v62, 1.0
	s_nop 0
	v_addc_co_u32_e32 v39, vcc, 0, v45, vcc
	v_div_scale_f32 v66, vcc, 1.0, v48, 1.0
	v_fmac_f32_e32 v62, v67, v62
	v_mul_f32_e32 v67, v66, v62
	v_fma_f32 v73, -v49, v67, v66
	v_lshrrev_b32_e32 v21, 3, v22
	v_lshlrev_b32_e32 v87, 1, v22
	v_fmac_f32_e32 v67, v73, v62
	s_mov_b64 s[6:7], 0x5000
	v_and_b32_e32 v64, 14, v87
	v_lshlrev_b32_e32 v65, 4, v21
	v_fma_f32 v49, -v49, v67, v66
	s_mov_b64 s[8:9], 0x6000
	s_mov_b64 s[16:17], 0x7000
	v_lshl_add_u64 v[34:35], v[44:45], 0, s[6:7]
	v_or_b32_e32 v63, v65, v64
	v_div_fmas_f32 v49, v49, v62, v67
	v_mov_b32_e32 v14, v28
	v_lshl_add_u64 v[40:41], v[44:45], 0, s[8:9]
	v_lshl_add_u64 v[30:31], v[44:45], 0, s[16:17]
	v_div_fixup_f32 v102, v49, v48, 1.0
	v_add_u32_e32 v114, s51, v63
	v_pk_mul_f32 v[14:15], v[12:13], v[14:15]
	v_readlane_b32 s6, v102, 0
	v_add_f32_e32 v14, v14, v15
	v_mov_b32_e32 v15, v12
	v_readlane_b32 s7, v102, 1
	v_readlane_b32 s8, v102, 2
	v_readlane_b32 s9, v102, 3
	v_pk_mul_f32 v[26:27], v[2:3], v[26:27] op_sel_hi:[0,1]
	v_pk_fma_f32 v[26:27], v[4:5], v[24:25], v[26:27] op_sel_hi:[0,1,1]
	v_ashrrev_i32_e32 v109, 5, v22
	v_lshlrev_b32_e32 v108, 4, v96
	s_waitcnt lgkmcnt(0)
	v_lshlrev_b32_e32 v68, 16, v17
	v_fmac_f32_e32 v16, v105, v68
	v_mul_f32_e32 v17, 0xbfb8aa3b, v16
	v_exp_f32_e32 v17, v17
	s_mov_b64 s[98:99], 0x4000
	v_lshl_add_u64 v[150:151], v[44:45], 0, s[98:99]
	global_load_ushort v156, v[150:151], off offset:-1024
	global_load_ushort v159, v[150:151], off
	global_load_ushort v160, v[150:151], off offset:1024
	s_mov_b64 s[98:99], 0x5000
	v_lshl_add_u64 v[150:151], v[44:45], 0, s[98:99]
	global_load_ushort v157, v[150:151], off offset:-1024
	global_load_ushort v158, v[150:151], off
	global_load_ushort v154, v[150:151], off offset:1024
	s_mov_b64 s[98:99], 0x6000
	v_lshl_add_u64 v[150:151], v[44:45], 0, s[98:99]
	global_load_ushort v152, v[150:151], off offset:-1024
	global_load_ushort v162, v[150:151], off offset:1024
	global_load_ushort v161, v[150:151], off
	s_mov_b64 s[98:99], 0x7000
	v_lshl_add_u64 v[150:151], v[44:45], 0, s[98:99]
	global_load_ushort v153, v[150:151], off offset:-1024
	global_load_ushort v155, v[150:151], off
	global_load_ushort v163, v[150:151], off offset:1024
	s_waitcnt vmcnt(15)
	v_lshlrev_b32_e32 v54, 16, v54
	v_add_f32_e32 v17, 1.0, v17
	v_rcp_f32_e32 v17, v17
	v_lshlrev_b32_e32 v52, 16, v52
	v_mul_f32_e32 v16, v16, v17
	v_mul_f32_e32 v17, v16, v16
	v_lshlrev_b32_e32 v56, 16, v56
	s_nop 0
	v_mov_b32_dpp v57, v17 quad_perm:[1,0,3,2] row_mask:0xf bank_mask:0xf
	v_fmac_f32_e32 v57, v16, v16
	s_nop 1
	v_add_f32_dpp v17, v57, v57 quad_perm:[2,3,0,1] row_mask:0xf bank_mask:0xf bound_ctrl:1
	s_nop 1
	v_add_f32_dpp v17, v17, v17 row_half_mirror row_mask:0xf bank_mask:0xf bound_ctrl:1
	s_nop 1
	v_add_f32_dpp v17, v17, v17 row_mirror row_mask:0xf bank_mask:0xf bound_ctrl:1
	s_nop 1
	v_mov_b32_dpp v60, v17 row_bcast:15 row_mask:0xa bank_mask:0xf
	v_add_f32_e32 v17, v17, v60
	v_lshlrev_b32_e32 v60, 16, v55
	s_nop 0
	v_mov_b32_dpp v61, v17 row_bcast:31 row_mask:0xc bank_mask:0xf
	v_add_f32_e32 v17, v17, v61
	s_nop 0
	v_readlane_b32 s2, v17, 63
	s_nop 1
	v_add_f32_e32 v17, s2, v86
	v_rsq_f32_e32 v17, v17
	s_movk_i32 s2, 0x7000
	v_mul_f32_e32 v16, v16, v17
	v_mul_f32_e32 v16, 0x3e000000, v16
	v_cvt_pk_bf16_f32 v73, v16, s0
	v_add_co_u32_e32 v16, vcc, s2, v44
	v_readlane_b32 s2, v3, 0
	s_nop 0
	v_addc_co_u32_e32 v17, vcc, 0, v45, vcc
	s_nop 0
	s_nop 0
	v_lshlrev_b32_e32 v33, 16, v71
	v_lshlrev_b32_e32 v32, 16, v72
	v_pk_mov_b32 v[30:31], v[28:29], v[32:33] op_sel:[1,0]
	v_mov_b32_e32 v38, 0
	v_pk_mul_f32 v[36:37], v[10:11], v[30:31]
	v_mul_f32_e32 v35, v5, v70
	v_add_f32_e32 v14, v36, v14
	v_add_f32_e32 v36, v14, v37
	v_mul_f32_e32 v14, 0xbfb8aa3b, v36
	v_exp_f32_e32 v14, v14
	v_fmac_f32_e32 v35, v9, v46
	v_fmac_f32_e32 v35, v7, v68
	v_pk_mul_f32 v[40:41], v[10:11], v[32:33]
	v_add_f32_e32 v14, 1.0, v14
	v_rcp_f32_e32 v37, v14
	v_mov_b32_e32 v14, v13
	v_pk_mul_f32 v[28:29], v[14:15], v[28:29]
	v_fmac_f32_e32 v35, v105, v52
	v_mul_f32_e32 v36, v36, v37
	v_mul_f32_e32 v37, v36, v36
	v_add_f32_e32 v28, v29, v28
	v_add_f32_e32 v28, v28, v40
	v_mov_b32_dpp v38, v37 quad_perm:[1,0,3,2] row_mask:0xf bank_mask:0xf
	v_fmac_f32_e32 v38, v36, v36
	v_add_f32_e32 v28, v28, v41
	v_mul_f32_e32 v29, 0xbfb8aa3b, v35
	v_add_f32_dpp v37, v38, v38 quad_perm:[2,3,0,1] row_mask:0xf bank_mask:0xf bound_ctrl:1
	v_mov_b32_e32 v38, 0
	v_exp_f32_e32 v29, v29
	v_add_f32_dpp v37, v37, v37 row_half_mirror row_mask:0xf bank_mask:0xf bound_ctrl:1
	v_mul_f32_e32 v40, 0xbfb8aa3b, v28
	v_exp_f32_e32 v40, v40
	v_add_f32_dpp v37, v37, v37 row_mirror row_mask:0xf bank_mask:0xf bound_ctrl:1
	v_mov_b32_e32 v39, s2
	v_add_f32_e32 v29, 1.0, v29
	v_mov_b32_dpp v38, v37 row_bcast:15 row_mask:0xa bank_mask:0xf
	v_add_f32_e32 v37, v37, v38
	v_mov_b32_e32 v38, 0
	v_rcp_f32_e32 v29, v29
	ds_write_b16 v114, v73
	v_mov_b32_dpp v38, v37 row_bcast:31 row_mask:0xc bank_mask:0xf
	v_add_f32_e32 v37, v37, v38
	v_mul_f32_e32 v29, v35, v29
	v_readlane_b32 s3, v37, 63
	v_mul_f32_e32 v35, v29, v29
	s_mov_b64 s[98:99], 0x8000
	v_lshl_add_u64 v[150:151], v[44:45], 0, s[98:99]
	global_load_ushort v164, v[150:151], off offset:-1024
	global_load_ushort v165, v[150:151], off
	global_load_ushort v176, v[150:151], off offset:1024
	s_mov_b64 s[98:99], 0x9000
	v_lshl_add_u64 v[150:151], v[44:45], 0, s[98:99]
	global_load_ushort v166, v[150:151], off offset:-1024
	global_load_ushort v175, v[150:151], off offset:1024
	global_load_ushort v173, v[150:151], off
	s_mov_b64 s[98:99], 0xa000
	v_lshl_add_u64 v[150:151], v[44:45], 0, s[98:99]
	global_load_ushort v167, v[150:151], off offset:-1024
	global_load_ushort v174, v[150:151], off
	s_mov_b64 s[98:99], 0xb000
	v_lshl_add_u64 v[150:151], v[44:45], 0, s[98:99]
	global_load_ushort v172, v[150:151], off offset:-1024
	s_waitcnt vmcnt(10) lgkmcnt(0)
	v_lshlrev_b32_e32 v103, 16, v152
	v_add_f32_e32 v37, s3, v86
	v_rsq_f32_e32 v38, v37
	v_mov_b32_e32 v37, s6
	v_lshlrev_b32_e32 v57, 16, v50
	v_pk_mov_b32 v[24:25], v[24:25], v[56:57] op_sel:[1,0]
	v_pk_mul_f32 v[36:37], v[36:37], v[38:39]
	v_add_f32_e32 v38, 1.0, v40
	v_rcp_f32_e32 v38, v38
	v_cvt_pk_bf16_f32 v39, v36, s0
	ds_write_b16 v114, v39 offset:4096
	v_pk_fma_f32 v[26:27], v[6:7], v[24:25], v[26:27] op_sel_hi:[0,1,1]
	v_mul_f32_e32 v28, v28, v38
	v_mov_b32_e32 v38, 0
	v_pk_fma_f32 v[26:27], v[8:9], v[56:57], v[26:27] op_sel_hi:[0,1,1]
	v_lshlrev_b32_e32 v98, 16, v153
	v_mov_b32_dpp v38, v35 quad_perm:[1,0,3,2] row_mask:0xf bank_mask:0xf
	v_fmac_f32_e32 v38, v29, v29
	v_mul_f32_e32 v34, 0xbfb8aa3b, v26
	v_exp_f32_e32 v34, v34
	v_add_f32_dpp v35, v38, v38 quad_perm:[2,3,0,1] row_mask:0xf bank_mask:0xf bound_ctrl:1
	v_mov_b32_e32 v38, 0
	v_mul_f32_e32 v88, v36, v37
	v_add_f32_dpp v35, v35, v35 row_half_mirror row_mask:0xf bank_mask:0xf bound_ctrl:1
	v_add_f32_e32 v34, 1.0, v34
	v_rcp_f32_e32 v74, v34
	v_add_f32_dpp v35, v35, v35 row_mirror row_mask:0xf bank_mask:0xf bound_ctrl:1
	v_lshlrev_b32_e32 v55, 16, v154
	v_lshlrev_b32_e32 v61, 16, v155
	v_mov_b32_dpp v38, v35 row_bcast:15 row_mask:0xa bank_mask:0xf
	v_add_f32_e32 v35, v35, v38
	v_mov_b32_e32 v38, 0
	v_mul_f32_e32 v123, v9, v98
	v_fmac_f32_e32 v123, v5, v103
	v_mov_b32_dpp v38, v35 row_bcast:31 row_mask:0xc bank_mask:0xf
	v_add_f32_e32 v35, v35, v38
	v_mov_b32_e32 v38, 0
	v_readlane_b32 s2, v35, 63
	v_mul_f32_e32 v35, v28, v28
	s_nop 0
	v_add_f32_e32 v39, s2, v86
	v_mov_b32_dpp v38, v35 quad_perm:[1,0,3,2] row_mask:0xf bank_mask:0xf
	v_fmac_f32_e32 v38, v28, v28
	v_rsq_f32_e32 v39, v39
	s_nop 0
	v_add_f32_dpp v35, v38, v38 quad_perm:[2,3,0,1] row_mask:0xf bank_mask:0xf bound_ctrl:1
	v_mov_b32_e32 v38, 0
	v_mul_f32_e32 v29, v29, v39
	v_add_f32_dpp v35, v35, v35 row_half_mirror row_mask:0xf bank_mask:0xf bound_ctrl:1
	v_mul_f32_e32 v29, 0x3e000000, v29
	v_cvt_pk_bf16_f32 v29, v29, s0
	v_add_f32_dpp v35, v35, v35 row_mirror row_mask:0xf bank_mask:0xf bound_ctrl:1
	s_nop 1
	v_mov_b32_dpp v38, v35 row_bcast:15 row_mask:0xa bank_mask:0xf
	v_add_f32_e32 v35, v35, v38
	v_mov_b32_e32 v38, 0
	s_nop 1
	v_mov_b32_dpp v38, v35 row_bcast:31 row_mask:0xc bank_mask:0xf
	v_add_f32_e32 v35, v35, v38
	s_nop 0
	v_readlane_b32 s2, v35, 63
	s_nop 1
	v_add_f32_e32 v35, s2, v86
	v_rsq_f32_e32 v38, v35
	v_xor_b32_e32 v35, 16, v65
	v_or_b32_e32 v35, v35, v64
	v_add_u32_e32 v116, s51, v35
	v_mul_f32_e32 v35, v9, v68
	v_fmac_f32_e32 v35, v5, v46
	v_fmac_f32_e32 v35, v7, v52
	v_fmac_f32_e32 v35, v105, v54
	v_mul_f32_e32 v39, 0xbfb8aa3b, v35
	v_exp_f32_e32 v39, v39
	ds_write_b16 v116, v29 offset:128
	v_readlane_b32 s2, v3, 1
	v_add_f32_e32 v29, 1.0, v39
	v_rcp_f32_e32 v40, v29
	v_mov_b32_e32 v29, s7
	v_mov_b32_e32 v39, s2
	v_pk_mul_f32 v[38:39], v[28:29], v[38:39]
	v_mul_f32_e32 v28, v35, v40
	v_mul_f32_e32 v29, v28, v28
	v_mov_b32_e32 v35, 0
	v_pk_mul_f32 v[40:41], v[14:15], v[30:31]
	v_mul_f32_e32 v90, v38, v39
	v_mov_b32_dpp v35, v29 quad_perm:[1,0,3,2] row_mask:0xf bank_mask:0xf
	v_fmac_f32_e32 v35, v28, v28
	v_cvt_pk_bf16_f32 v36, v36, v38
	s_nop 0
	v_add_f32_dpp v29, v35, v35 quad_perm:[2,3,0,1] row_mask:0xf bank_mask:0xf bound_ctrl:1
	v_mov_b32_e32 v35, 0
	s_nop 0
	v_add_f32_dpp v29, v29, v29 row_half_mirror row_mask:0xf bank_mask:0xf bound_ctrl:1
	s_nop 1
	v_add_f32_dpp v29, v29, v29 row_mirror row_mask:0xf bank_mask:0xf bound_ctrl:1
	s_nop 1
	v_mov_b32_dpp v35, v29 row_bcast:15 row_mask:0xa bank_mask:0xf
	v_add_f32_e32 v29, v29, v35
	v_mov_b32_e32 v35, 0
	s_nop 1
	v_mov_b32_dpp v35, v29 row_bcast:31 row_mask:0xc bank_mask:0xf
	v_add_f32_e32 v29, v29, v35
	v_cvt_pk_bf16_f32 v35, v38, s0
	v_readlane_b32 s2, v29, 63
	ds_write_b16 v116, v35 offset:4224
	v_add_f32_e32 v35, v40, v41
	v_add_f32_e32 v29, s2, v86
	v_rsq_f32_e32 v29, v29
	v_mov_b32_e32 v41, 0
	v_readlane_b32 s2, v3, 2
	v_mul_f32_e32 v28, v28, v29
	v_xor_b32_e32 v29, 32, v65
	v_mul_f32_e32 v28, 0x3e000000, v28
	v_or_b32_e32 v29, v29, v64
	v_cvt_pk_bf16_f32 v28, v28, s0
	v_add_u32_e32 v115, s51, v29
	ds_write_b16 v115, v28 offset:256
	v_lshlrev_b32_e32 v29, 16, v69
	v_lshlrev_b32_e32 v28, 16, v47
	v_pk_mov_b32 v[30:31], v[32:33], v[28:29] op_sel:[1,0]
	v_mul_f32_e32 v69, v9, v52
	v_pk_mul_f32 v[42:43], v[10:11], v[30:31]
	v_fmac_f32_e32 v69, v5, v68
	v_add_f32_e32 v35, v35, v42
	v_add_f32_e32 v35, v35, v43
	v_mul_f32_e32 v40, 0xbfb8aa3b, v35
	v_exp_f32_e32 v40, v40
	v_pk_mul_f32 v[32:33], v[14:15], v[32:33]
	v_fmac_f32_e32 v69, v7, v54
	v_pk_mul_f32 v[46:47], v[10:11], v[28:29]
	v_add_f32_e32 v40, 1.0, v40
	v_rcp_f32_e32 v40, v40
	v_add_f32_e32 v32, v32, v33
	v_fmac_f32_e32 v69, v105, v60
	v_add_f32_e32 v32, v32, v46
	v_mul_f32_e32 v40, v35, v40
	v_mul_f32_e32 v35, v40, v40
	v_add_f32_e32 v32, v32, v47
	v_mul_f32_e32 v33, 0xbfb8aa3b, v69
	v_mov_b32_dpp v41, v35 quad_perm:[1,0,3,2] row_mask:0xf bank_mask:0xf
	v_fmac_f32_e32 v41, v40, v40
	v_exp_f32_e32 v33, v33
	v_mov_b32_e32 v43, s2
	v_add_f32_dpp v35, v41, v41 quad_perm:[2,3,0,1] row_mask:0xf bank_mask:0xf bound_ctrl:1
	v_mov_b32_e32 v41, 0
	v_add_f32_e32 v33, 1.0, v33
	v_add_f32_dpp v35, v35, v35 row_half_mirror row_mask:0xf bank_mask:0xf bound_ctrl:1
	v_rcp_f32_e32 v33, v33
	v_lshlrev_b32_e32 v68, 16, v156
	v_add_f32_dpp v35, v35, v35 row_mirror row_mask:0xf bank_mask:0xf bound_ctrl:1
	v_mul_f32_e32 v33, v69, v33
	s_nop 0
	v_mov_b32_dpp v41, v35 row_bcast:15 row_mask:0xa bank_mask:0xf
	v_add_f32_e32 v35, v35, v41
	v_mov_b32_e32 v41, 0
	s_nop 1
	v_mov_b32_dpp v41, v35 row_bcast:31 row_mask:0xc bank_mask:0xf
	v_add_f32_e32 v35, v35, v41
	v_mov_b32_e32 v41, s8
	v_readlane_b32 s3, v35, 63
	s_nop 1
	v_add_f32_e32 v35, s3, v86
	v_rsq_f32_e32 v42, v35
	v_mul_f32_e32 v35, 0xbfb8aa3b, v32
	v_exp_f32_e32 v35, v35
	v_pk_mul_f32 v[40:41], v[40:41], v[42:43]
	s_nop 0
	v_cvt_pk_bf16_f32 v42, v40, s0
	v_add_f32_e32 v35, 1.0, v35
	v_rcp_f32_e32 v35, v35
	ds_write_b16 v115, v42 offset:4352
	v_mov_b32_e32 v42, 0
	v_mul_f32_e32 v89, v40, v41
	v_mul_f32_e32 v32, v32, v35
	v_mul_f32_e32 v35, v33, v33
	s_nop 1
	v_mov_b32_dpp v42, v35 quad_perm:[1,0,3,2] row_mask:0xf bank_mask:0xf
	v_fmac_f32_e32 v42, v33, v33
	s_nop 1
	v_add_f32_dpp v35, v42, v42 quad_perm:[2,3,0,1] row_mask:0xf bank_mask:0xf bound_ctrl:1
	v_mov_b32_e32 v42, 0
	s_nop 0
	v_add_f32_dpp v35, v35, v35 row_half_mirror row_mask:0xf bank_mask:0xf bound_ctrl:1
	s_nop 1
	v_add_f32_dpp v35, v35, v35 row_mirror row_mask:0xf bank_mask:0xf bound_ctrl:1
	s_nop 1
	v_mov_b32_dpp v42, v35 row_bcast:15 row_mask:0xa bank_mask:0xf
	v_add_f32_e32 v35, v35, v42
	v_mov_b32_e32 v42, 0
	s_nop 1
	v_mov_b32_dpp v42, v35 row_bcast:31 row_mask:0xc bank_mask:0xf
	v_add_f32_e32 v35, v35, v42
	v_mov_b32_e32 v42, 0
	v_readlane_b32 s2, v35, 63
	v_mul_f32_e32 v35, v32, v32
	s_nop 0
	v_add_f32_e32 v43, s2, v86
	v_mov_b32_dpp v42, v35 quad_perm:[1,0,3,2] row_mask:0xf bank_mask:0xf
	v_fmac_f32_e32 v42, v32, v32
	v_rsq_f32_e32 v43, v43
	s_nop 0
	v_add_f32_dpp v35, v42, v42 quad_perm:[2,3,0,1] row_mask:0xf bank_mask:0xf bound_ctrl:1
	v_mov_b32_e32 v42, 0
	v_mul_f32_e32 v33, v33, v43
	v_add_f32_dpp v35, v35, v35 row_half_mirror row_mask:0xf bank_mask:0xf bound_ctrl:1
	v_mul_f32_e32 v33, 0x3e000000, v33
	v_cvt_pk_bf16_f32 v33, v33, s0
	v_add_f32_dpp v35, v35, v35 row_mirror row_mask:0xf bank_mask:0xf bound_ctrl:1
	s_nop 1
	v_mov_b32_dpp v42, v35 row_bcast:15 row_mask:0xa bank_mask:0xf
	v_add_f32_e32 v35, v35, v42
	v_mov_b32_e32 v42, 0
	s_nop 1
	v_mov_b32_dpp v42, v35 row_bcast:31 row_mask:0xc bank_mask:0xf
	v_add_f32_e32 v35, v35, v42
	s_nop 0
	v_readlane_b32 s2, v35, 63
	s_nop 1
	v_add_f32_e32 v35, s2, v86
	v_rsq_f32_e32 v42, v35
	v_xor_b32_e32 v35, 48, v65
	v_or_b32_e32 v35, v35, v64
	v_add_u32_e32 v117, s51, v35
	v_readlane_b32 s2, v3, 3
	ds_write_b16 v117, v33 offset:384
	v_mov_b32_e32 v33, s9
	v_mov_b32_e32 v43, s2
	v_pk_mul_f32 v[46:47], v[32:33], v[42:43]
	v_mul_f32_e32 v35, 0xbfb8aa3b, v27
	v_cvt_pk_bf16_f32 v32, v46, s0
	ds_write_b16 v117, v32 offset:4480
	v_exp_f32_e32 v35, v35
	s_mov_b32 s2, 0x8000
	v_add_co_u32_e32 v70, vcc, s2, v44
	v_add_f32_e32 v34, 1.0, v35
	v_rcp_f32_e32 v75, v34
	v_lshlrev_b32_e32 v35, 16, v53
	v_lshlrev_b32_e32 v34, 16, v51
	v_pk_mul_f32 v[50:51], v[4:5], v[56:57] op_sel_hi:[0,1]
	v_pk_fma_f32 v[24:25], v[2:3], v[24:25], v[50:51] op_sel_hi:[0,1,1]
	v_pk_mov_b32 v[50:51], v[56:57], v[34:35] op_sel:[1,0]
	v_lshl_or_b32 v16, v109, 11, v108
	v_pk_fma_f32 v[24:25], v[6:7], v[50:51], v[24:25] op_sel_hi:[0,1,1]
	v_addc_co_u32_e32 v71, vcc, 0, v45, vcc
	s_mov_b32 s2, 0x9000
	v_ashrrev_i32_e32 v17, 31, v16
	v_pk_fma_f32 v[56:57], v[8:9], v[34:35], v[24:25] op_sel_hi:[0,1,1]
	v_add_co_u32_e32 v72, vcc, s2, v44
	v_lshl_add_u64 v[42:43], s[0:1], 0, v[16:17]
	s_mov_b64 s[2:3], 0x2800
	v_mul_f32_e32 v24, 0xbfb8aa3b, v56
	v_addc_co_u32_e32 v73, vcc, 0, v45, vcc
	v_lshl_add_u64 v[16:17], v[42:43], 0, s[2:3]
	s_mov_b32 s2, 0xa000
	v_exp_f32_e32 v37, v24
	v_add_co_u32_e32 v48, vcc, s2, v44
	v_lshlrev_b32_e32 v32, 16, v157
	s_nop 0
	v_addc_co_u32_e32 v49, vcc, 0, v45, vcc
	v_mul_f32_e32 v24, 0xbfb8aa3b, v57
	v_exp_f32_e32 v53, v24
	v_pk_mul_f32 v[24:25], v[26:27], v[74:75]
	v_add_f32_e32 v26, 1.0, v37
	v_mul_f32_e32 v37, v9, v54
	v_fmac_f32_e32 v37, v5, v52
	v_fmac_f32_e32 v37, v7, v60
	v_fmac_f32_e32 v37, v105, v68
	v_mul_f32_e32 v39, 0xbfb8aa3b, v37
	v_exp_f32_e32 v39, v39
	v_add_f32_e32 v27, 1.0, v53
	v_mov_b32_e32 v53, 0
	v_rcp_f32_e32 v26, v26
	v_rcp_f32_e32 v27, v27
	v_mul_f32_e32 v91, v46, v47
	v_pk_mul_f32 v[24:25], v[24:25], s[6:7]
	v_pk_mul_f32 v[26:27], v[56:57], v[26:27]
	v_readlane_b32 s6, v102, 4
	v_readlane_b32 s7, v102, 5
	v_pk_mul_f32 v[26:27], v[26:27], s[8:9]
	s_mov_b64 s[98:99], 0xa000
	v_lshl_add_u64 v[150:151], v[44:45], 0, s[98:99]
	global_load_ushort v183, v[150:151], off offset:1024
	s_mov_b64 s[98:99], 0xb000
	v_lshl_add_u64 v[150:151], v[44:45], 0, s[98:99]
	global_load_ushort v182, v[150:151], off offset:1024
	global_load_ushort v181, v[150:151], off
	s_mov_b64 s[98:99], 0xc000
	v_lshl_add_u64 v[150:151], v[44:45], 0, s[98:99]
	global_load_ushort v179, v[150:151], off offset:-1024
	global_load_ushort v184, v[150:151], off
	global_load_ushort v186, v[150:151], off offset:1024
	s_mov_b64 s[98:99], 0xd000
	v_lshl_add_u64 v[150:151], v[44:45], 0, s[98:99]
	global_load_ushort v177, v[150:151], off offset:-1024
	global_load_ushort v187, v[150:151], off
	global_load_ushort v185, v[150:151], off offset:1024
	s_mov_b64 s[98:99], 0xe000
	v_lshl_add_u64 v[150:151], v[44:45], 0, s[98:99]
	global_load_ushort v178, v[150:151], off offset:-1024
	global_load_ushort v191, v[150:151], off offset:1024
	global_load_ushort v188, v[150:151], off
	s_mov_b64 s[98:99], 0xf000
	v_lshl_add_u64 v[150:151], v[44:45], 0, s[98:99]
	global_load_ushort v180, v[150:151], off offset:-1024
	global_load_ushort v189, v[150:151], off
	global_load_ushort v190, v[150:151], off offset:1024
	s_waitcnt vmcnt(15) lgkmcnt(0)
	v_lshlrev_b32_e32 v100, 16, v164
	v_add_f32_e32 v33, 1.0, v39
	v_rcp_f32_e32 v52, v33
	v_fmac_f32_e32 v123, v7, v100
	v_mul_f32_e32 v52, v37, v52
	v_mul_f32_e32 v37, v52, v52
	v_lshlrev_b32_e32 v33, 16, v165
	s_nop 0
	v_mov_b32_dpp v53, v37 quad_perm:[1,0,3,2] row_mask:0xf bank_mask:0xf
	v_fmac_f32_e32 v53, v52, v52
	v_lshlrev_b32_e32 v41, 16, v166
	v_fmac_f32_e32 v123, v105, v41
	v_add_f32_dpp v37, v53, v53 quad_perm:[2,3,0,1] row_mask:0xf bank_mask:0xf bound_ctrl:1
	v_mov_b32_e32 v53, 0
	v_lshlrev_b32_e32 v39, 16, v167
	v_add_f32_dpp v37, v37, v37 row_half_mirror row_mask:0xf bank_mask:0xf bound_ctrl:1
	v_mul_f32_e32 v132, v9, v39
	v_fmac_f32_e32 v132, v5, v41
	v_add_f32_dpp v37, v37, v37 row_mirror row_mask:0xf bank_mask:0xf bound_ctrl:1
	s_nop 1
	v_mov_b32_dpp v53, v37 row_bcast:15 row_mask:0xa bank_mask:0xf
	v_add_f32_e32 v37, v37, v53
	v_mov_b32_e32 v53, 0
	s_nop 1
	v_mov_b32_dpp v53, v37 row_bcast:31 row_mask:0xc bank_mask:0xf
	v_add_f32_e32 v37, v37, v53
	s_nop 0
	v_readlane_b32 s2, v37, 63
	s_nop 1
	v_add_f32_e32 v37, s2, v86
	v_rsq_f32_e32 v53, v37
	s_mov_b32 s2, 0xb000
	v_add_co_u32_e32 v56, vcc, s2, v44
	v_readlane_b32 s2, v3, 4
	s_nop 0
	v_addc_co_u32_e32 v57, vcc, 0, v45, vcc
	v_pk_mul_f32 v[48:49], v[14:15], v[30:31]
	v_mul_f32_e32 v30, v52, v53
	v_xor_b32_e32 v31, 64, v65
	v_mul_f32_e32 v30, 0x3e000000, v30
	v_or_b32_e32 v31, v31, v64
	v_cvt_pk_bf16_f32 v30, v30, s0
	v_add_u32_e32 v118, s51, v31
	ds_write_b16 v118, v30 offset:512
	v_lshlrev_b32_e32 v31, 16, v158
	v_lshlrev_b32_e32 v30, 16, v159
	v_pk_mov_b32 v[52:53], v[28:29], v[30:31] op_sel:[1,0]
	v_add_f32_e32 v48, v48, v49
	v_pk_mul_f32 v[70:71], v[10:11], v[52:53]
	v_mul_f32_e32 v59, v9, v60
	v_add_f32_e32 v48, v48, v70
	v_add_f32_e32 v48, v48, v71
	v_mul_f32_e32 v49, 0xbfb8aa3b, v48
	v_exp_f32_e32 v49, v49
	v_fmac_f32_e32 v59, v5, v54
	v_mov_b32_e32 v54, 0
	v_pk_mul_f32 v[28:29], v[14:15], v[28:29]
	v_add_f32_e32 v49, 1.0, v49
	v_rcp_f32_e32 v49, v49
	v_mov_b32_e32 v71, s2
	v_fmac_f32_e32 v59, v7, v68
	v_add_f32_e32 v28, v28, v29
	v_mul_f32_e32 v48, v48, v49
	v_mul_f32_e32 v49, v48, v48
	v_fmac_f32_e32 v59, v105, v32
	v_mul_f32_e32 v29, 0xbfb8aa3b, v59
	v_mov_b32_dpp v54, v49 quad_perm:[1,0,3,2] row_mask:0xf bank_mask:0xf
	v_fmac_f32_e32 v54, v48, v48
	v_exp_f32_e32 v29, v29
	v_lshlrev_b32_e32 v37, 16, v172
	v_add_f32_dpp v49, v54, v54 quad_perm:[2,3,0,1] row_mask:0xf bank_mask:0xf bound_ctrl:1
	v_mov_b32_e32 v54, 0
	v_add_f32_e32 v29, 1.0, v29
	v_add_f32_dpp v49, v49, v49 row_half_mirror row_mask:0xf bank_mask:0xf bound_ctrl:1
	v_rcp_f32_e32 v29, v29
	v_fmac_f32_e32 v132, v7, v37
	v_add_f32_dpp v49, v49, v49 row_mirror row_mask:0xf bank_mask:0xf bound_ctrl:1
	v_mul_f32_e32 v29, v59, v29
	s_nop 0
	v_mov_b32_dpp v54, v49 row_bcast:15 row_mask:0xa bank_mask:0xf
	v_add_f32_e32 v49, v49, v54
	v_mov_b32_e32 v54, 0
	s_nop 1
	v_mov_b32_dpp v54, v49 row_bcast:31 row_mask:0xc bank_mask:0xf
	v_add_f32_e32 v49, v49, v54
	s_nop 0
	v_readlane_b32 s3, v49, 63
	s_nop 1
	v_add_f32_e32 v49, s3, v86
	v_rsq_f32_e32 v70, v49
	v_mov_b32_e32 v49, s6
	v_readlane_b32 s3, v3, 6
	v_pk_mul_f32 v[48:49], v[48:49], v[70:71]
	v_pk_mul_f32 v[70:71], v[10:11], v[30:31]
	v_mul_f32_e32 v92, v48, v49
	v_add_f32_e32 v28, v28, v70
	v_add_f32_e32 v28, v28, v71
	v_mul_f32_e32 v54, 0xbfb8aa3b, v28
	v_exp_f32_e32 v54, v54
	v_mov_b32_e32 v49, 0
	v_cvt_pk_bf16_f32 v63, v48, s0
	ds_write_b16 v118, v63 offset:4608
	v_add_f32_e32 v54, 1.0, v54
	v_rcp_f32_e32 v54, v54
	v_mov_b32_e32 v71, s7
	v_mul_f32_e32 v70, v28, v54
	v_mul_f32_e32 v28, v29, v29
	s_nop 1
	v_mov_b32_dpp v49, v28 quad_perm:[1,0,3,2] row_mask:0xf bank_mask:0xf
	v_fmac_f32_e32 v49, v29, v29
	s_nop 1
	v_add_f32_dpp v28, v49, v49 quad_perm:[2,3,0,1] row_mask:0xf bank_mask:0xf bound_ctrl:1
	v_mov_b32_e32 v49, 0
	s_nop 0
	v_add_f32_dpp v28, v28, v28 row_half_mirror row_mask:0xf bank_mask:0xf bound_ctrl:1
	s_nop 1
	v_add_f32_dpp v28, v28, v28 row_mirror row_mask:0xf bank_mask:0xf bound_ctrl:1
	s_nop 1
	v_mov_b32_dpp v49, v28 row_bcast:15 row_mask:0xa bank_mask:0xf
	v_add_f32_e32 v28, v28, v49
	v_mov_b32_e32 v49, 0
	s_nop 1
	v_mov_b32_dpp v49, v28 row_bcast:31 row_mask:0xc bank_mask:0xf
	v_add_f32_e32 v28, v28, v49
	v_mov_b32_e32 v49, 0
	v_readlane_b32 s2, v28, 63
	v_mul_f32_e32 v28, v70, v70
	s_nop 0
	v_add_f32_e32 v54, s2, v86
	v_mov_b32_dpp v49, v28 quad_perm:[1,0,3,2] row_mask:0xf bank_mask:0xf
	v_fmac_f32_e32 v49, v70, v70
	v_rsq_f32_e32 v54, v54
	s_nop 0
	v_add_f32_dpp v28, v49, v49 quad_perm:[2,3,0,1] row_mask:0xf bank_mask:0xf bound_ctrl:1
	v_mov_b32_e32 v49, 0
	s_nop 0
	v_add_f32_dpp v28, v28, v28 row_half_mirror row_mask:0xf bank_mask:0xf bound_ctrl:1
	s_nop 1
	v_add_f32_dpp v28, v28, v28 row_mirror row_mask:0xf bank_mask:0xf bound_ctrl:1
	s_nop 1
	v_mov_b32_dpp v49, v28 row_bcast:15 row_mask:0xa bank_mask:0xf
	v_add_f32_e32 v28, v28, v49
	v_mov_b32_e32 v49, 0
	s_nop 1
	v_mov_b32_dpp v49, v28 row_bcast:31 row_mask:0xc bank_mask:0xf
	v_add_f32_e32 v28, v28, v49
	v_mul_f32_e32 v49, v9, v68
	v_readlane_b32 s2, v28, 63
	v_mul_f32_e32 v28, v29, v54
	v_mul_f32_e32 v28, 0x3e000000, v28
	v_add_f32_e32 v29, s2, v86
	v_rsq_f32_e32 v72, v29
	v_xor_b32_e32 v29, 0x50, v65
	v_or_b32_e32 v29, v29, v64
	v_cvt_pk_bf16_f32 v28, v28, s0
	v_add_u32_e32 v119, s51, v29
	ds_write_b16 v119, v28 offset:640
	v_lshlrev_b32_e32 v54, 16, v160
	v_pk_mul_f32 v[28:29], v[4:5], v[34:35] op_sel_hi:[0,1]
	v_pk_fma_f32 v[28:29], v[2:3], v[50:51], v[28:29] op_sel_hi:[0,1,1]
	v_pk_mov_b32 v[58:59], v[34:35], v[54:55] op_sel:[1,0]
	v_fmac_f32_e32 v49, v5, v60
	v_pk_fma_f32 v[28:29], v[6:7], v[58:59], v[28:29] op_sel_hi:[0,1,1]
	v_pk_fma_f32 v[28:29], v[8:9], v[54:55], v[28:29] op_sel_hi:[0,1,1]
	v_mul_f32_e32 v34, 0xbfb8aa3b, v28
	v_mul_f32_e32 v35, 0xbfb8aa3b, v29
	v_exp_f32_e32 v34, v34
	v_exp_f32_e32 v35, v35
	v_fmac_f32_e32 v49, v7, v32
	v_fmac_f32_e32 v49, v105, v103
	v_add_f32_e32 v34, 1.0, v34
	v_add_f32_e32 v35, 1.0, v35
	v_mul_f32_e32 v50, 0xbfb8aa3b, v49
	v_rcp_f32_e32 v34, v34
	v_rcp_f32_e32 v35, v35
	v_exp_f32_e32 v50, v50
	v_mov_b32_e32 v60, 0
	v_readlane_b32 s2, v3, 5
	v_pk_mul_f32 v[28:29], v[28:29], v[34:35]
	v_add_f32_e32 v34, 1.0, v50
	v_rcp_f32_e32 v34, v34
	v_mov_b32_e32 v73, s2
	v_pk_mul_f32 v[50:51], v[70:71], v[72:73]
	v_pk_mul_f32 v[28:29], v[28:29], s[6:7]
	v_mul_f32_e32 v49, v49, v34
	v_mul_f32_e32 v34, v49, v49
	v_cvt_pk_bf16_f32 v35, v50, s0
	ds_write_b16 v119, v35 offset:4736
	v_mov_b32_dpp v60, v34 quad_perm:[1,0,3,2] row_mask:0xf bank_mask:0xf
	v_fmac_f32_e32 v60, v49, v49
	v_mul_f32_e32 v93, v50, v51
	v_xor_b32_e32 v51, 0x60, v65
	v_add_f32_dpp v34, v60, v60 quad_perm:[2,3,0,1] row_mask:0xf bank_mask:0xf bound_ctrl:1
	v_mov_b32_e32 v60, 0
	v_or_b32_e32 v51, v51, v64
	v_add_f32_dpp v34, v34, v34 row_half_mirror row_mask:0xf bank_mask:0xf bound_ctrl:1
	v_add_u32_e32 v124, s51, v51
	v_mov_b32_e32 v51, 0
	v_add_f32_dpp v34, v34, v34 row_mirror row_mask:0xf bank_mask:0xf bound_ctrl:1
	v_readlane_b32 s6, v102, 12
	v_readlane_b32 s7, v102, 13
	v_mov_b32_dpp v60, v34 row_bcast:15 row_mask:0xa bank_mask:0xf
	v_add_f32_e32 v34, v34, v60
	v_mov_b32_e32 v60, 0
	s_nop 1
	v_mov_b32_dpp v60, v34 row_bcast:31 row_mask:0xc bank_mask:0xf
	v_add_f32_e32 v34, v34, v60
	s_nop 0
	v_readlane_b32 s2, v34, 63
	s_nop 1
	v_add_f32_e32 v34, s2, v86
	v_rsq_f32_e32 v60, v34
	v_pk_mul_f32 v[34:35], v[14:15], v[52:53]
	v_readlane_b32 s2, v102, 6
	v_add_f32_e32 v34, v34, v35
	v_mul_f32_e32 v49, v49, v60
	v_lshlrev_b32_e32 v60, 16, v161
	v_pk_mov_b32 v[62:63], v[30:31], v[60:61] op_sel:[1,0]
	v_mul_f32_e32 v49, 0x3e000000, v49
	v_pk_mul_f32 v[52:53], v[10:11], v[62:63]
	v_cvt_pk_bf16_f32 v49, v49, s0
	v_add_f32_e32 v34, v34, v52
	v_add_f32_e32 v34, v34, v53
	v_mul_f32_e32 v35, 0xbfb8aa3b, v34
	v_exp_f32_e32 v35, v35
	ds_write_b16 v124, v49 offset:768
	v_mul_f32_e32 v49, v9, v32
	v_fmac_f32_e32 v49, v5, v68
	v_add_f32_e32 v35, 1.0, v35
	v_rcp_f32_e32 v35, v35
	v_pk_mul_f32 v[30:31], v[14:15], v[30:31]
	v_mov_b32_e32 v53, s3
	v_fmac_f32_e32 v49, v7, v103
	v_mul_f32_e32 v34, v34, v35
	v_mul_f32_e32 v35, v34, v34
	v_add_f32_e32 v30, v30, v31
	v_fmac_f32_e32 v49, v105, v98
	v_mov_b32_dpp v51, v35 quad_perm:[1,0,3,2] row_mask:0xf bank_mask:0xf
	v_fmac_f32_e32 v51, v34, v34
	v_mul_f32_e32 v31, 0xbfb8aa3b, v49
	v_exp_f32_e32 v31, v31
	v_add_f32_dpp v35, v51, v51 quad_perm:[2,3,0,1] row_mask:0xf bank_mask:0xf bound_ctrl:1
	v_mov_b32_e32 v51, 0
	v_pk_mul_f32 v[76:77], v[14:15], v[62:63]
	v_add_f32_dpp v35, v35, v35 row_half_mirror row_mask:0xf bank_mask:0xf bound_ctrl:1
	v_add_f32_e32 v31, 1.0, v31
	v_rcp_f32_e32 v31, v31
	v_add_f32_dpp v35, v35, v35 row_mirror row_mask:0xf bank_mask:0xf bound_ctrl:1
	v_mul_f32_e32 v31, v49, v31
	s_nop 0
	v_mov_b32_dpp v51, v35 row_bcast:15 row_mask:0xa bank_mask:0xf
	v_add_f32_e32 v35, v35, v51
	v_mov_b32_e32 v51, 0
	s_nop 1
	v_mov_b32_dpp v51, v35 row_bcast:31 row_mask:0xc bank_mask:0xf
	v_add_f32_e32 v35, v35, v51
	s_nop 0
	v_readlane_b32 s4, v35, 63
	s_nop 1
	v_add_f32_e32 v35, s4, v86
	v_rsq_f32_e32 v52, v35
	v_mov_b32_e32 v35, s2
	v_readlane_b32 s4, v3, 7
	v_pk_mul_f32 v[52:53], v[34:35], v[52:53]
	v_pk_mul_f32 v[34:35], v[10:11], v[60:61]
	v_mul_f32_e32 v94, v52, v53
	v_add_f32_e32 v30, v30, v34
	v_add_f32_e32 v30, v30, v35
	v_mul_f32_e32 v34, 0xbfb8aa3b, v30
	v_exp_f32_e32 v34, v34
	v_cvt_pk_bf16_f32 v35, v52, s0
	ds_write_b16 v124, v35 offset:4864
	v_mov_b32_e32 v71, s4
	v_add_f32_e32 v34, 1.0, v34
	v_rcp_f32_e32 v34, v34
	v_readlane_b32 s4, v3, 9
	v_mul_f32_e32 v68, v30, v34
	v_mul_f32_e32 v30, v31, v31
	v_mov_b32_e32 v34, 0
	s_nop 1
	v_mov_b32_dpp v34, v30 quad_perm:[1,0,3,2] row_mask:0xf bank_mask:0xf
	v_fmac_f32_e32 v34, v31, v31
	s_nop 1
	v_add_f32_dpp v30, v34, v34 quad_perm:[2,3,0,1] row_mask:0xf bank_mask:0xf bound_ctrl:1
	v_mov_b32_e32 v34, 0
	s_nop 0
	v_add_f32_dpp v30, v30, v30 row_half_mirror row_mask:0xf bank_mask:0xf bound_ctrl:1
	s_nop 1
	v_add_f32_dpp v30, v30, v30 row_mirror row_mask:0xf bank_mask:0xf bound_ctrl:1
	s_nop 1
	v_mov_b32_dpp v34, v30 row_bcast:15 row_mask:0xa bank_mask:0xf
	v_add_f32_e32 v30, v30, v34
	v_mov_b32_e32 v34, 0
	s_nop 1
	v_mov_b32_dpp v34, v30 row_bcast:31 row_mask:0xc bank_mask:0xf
	v_add_f32_e32 v30, v30, v34
	v_mov_b32_e32 v34, 0
	v_readlane_b32 s3, v30, 63
	v_mul_f32_e32 v30, v68, v68
	s_nop 0
	v_add_f32_e32 v35, s3, v86
	v_mov_b32_dpp v34, v30 quad_perm:[1,0,3,2] row_mask:0xf bank_mask:0xf
	v_fmac_f32_e32 v34, v68, v68
	v_rsq_f32_e32 v35, v35
	s_nop 0
	v_add_f32_dpp v30, v34, v34 quad_perm:[2,3,0,1] row_mask:0xf bank_mask:0xf bound_ctrl:1
	v_mov_b32_e32 v34, 0
	s_nop 0
	v_add_f32_dpp v30, v30, v30 row_half_mirror row_mask:0xf bank_mask:0xf bound_ctrl:1
	s_nop 1
	v_add_f32_dpp v30, v30, v30 row_mirror row_mask:0xf bank_mask:0xf bound_ctrl:1
	s_nop 1
	v_mov_b32_dpp v34, v30 row_bcast:15 row_mask:0xa bank_mask:0xf
	v_add_f32_e32 v30, v30, v34
	v_mov_b32_e32 v34, 0
	s_nop 1
	v_mov_b32_dpp v34, v30 row_bcast:31 row_mask:0xc bank_mask:0xf
	v_add_f32_e32 v30, v30, v34
	v_lshlrev_b32_e32 v34, 16, v162
	v_readlane_b32 s3, v30, 63
	v_mul_f32_e32 v30, v31, v35
	v_mul_f32_e32 v30, 0x3e000000, v30
	v_add_f32_e32 v31, s3, v86
	v_cvt_pk_bf16_f32 v49, v30, s0
	v_xor_b32_e32 v30, 0x70, v65
	v_rsq_f32_e32 v70, v31
	v_or_b32_e32 v51, v30, v64
	v_lshlrev_b32_e32 v35, 16, v163
	v_pk_mul_f32 v[30:31], v[4:5], v[54:55] op_sel_hi:[0,1]
	v_pk_fma_f32 v[30:31], v[2:3], v[58:59], v[30:31] op_sel_hi:[0,1,1]
	v_pk_mov_b32 v[58:59], v[54:55], v[34:35] op_sel:[1,0]
	v_add_u32_e32 v125, s51, v51
	v_pk_fma_f32 v[30:31], v[6:7], v[58:59], v[30:31] op_sel_hi:[0,1,1]
	v_pk_fma_f32 v[30:31], v[8:9], v[34:35], v[30:31] op_sel_hi:[0,1,1]
	v_mul_f32_e32 v53, 0xbfb8aa3b, v30
	v_exp_f32_e32 v53, v53
	v_mul_f32_e32 v54, 0xbfb8aa3b, v31
	v_exp_f32_e32 v55, v54
	v_readlane_b32 s3, v102, 7
	v_add_f32_e32 v51, 1.0, v53
	v_rcp_f32_e32 v54, v51
	v_add_f32_e32 v51, 1.0, v55
	v_rcp_f32_e32 v55, v51
	v_mov_b32_e32 v69, s3
	ds_write_b16 v125, v49 offset:896
	v_mov_b32_e32 v51, 0
	v_pk_mul_f32 v[30:31], v[30:31], v[54:55]
	v_pk_mul_f32 v[54:55], v[68:69], v[70:71]
	v_pk_mul_f32 v[30:31], v[30:31], s[2:3]
	v_cvt_pk_bf16_f32 v49, v54, s0
	ds_write_b16 v125, v49 offset:4992
	v_mul_f32_e32 v49, v9, v103
	v_fmac_f32_e32 v49, v5, v32
	v_fmac_f32_e32 v49, v7, v98
	v_fmac_f32_e32 v49, v105, v100
	v_mul_f32_e32 v32, 0xbfb8aa3b, v49
	v_exp_f32_e32 v32, v32
	s_mov_b64 s[2:3], 0xc000
	v_lshl_add_u64 v[64:65], v[44:45], 0, s[2:3]
	s_mov_b64 s[2:3], 0xd000
	v_add_f32_e32 v32, 1.0, v32
	v_rcp_f32_e32 v32, v32
	v_lshl_add_u64 v[68:69], v[44:45], 0, s[2:3]
	s_mov_b32 s2, 0xc000
	v_add_co_u32_e32 v70, vcc, s2, v44
	v_mul_f32_e32 v49, v49, v32
	v_mul_f32_e32 v32, v49, v49
	s_mov_b64 s[2:3], 0xe000
	v_addc_co_u32_e32 v71, vcc, 0, v45, vcc
	v_mov_b32_dpp v51, v32 quad_perm:[1,0,3,2] row_mask:0xf bank_mask:0xf
	v_fmac_f32_e32 v51, v49, v49
	v_lshl_add_u64 v[72:73], v[44:45], 0, s[2:3]
	s_mov_b32 s2, 0xd000
	v_add_f32_dpp v32, v51, v51 quad_perm:[2,3,0,1] row_mask:0xf bank_mask:0xf bound_ctrl:1
	v_mov_b32_e32 v51, 0
	v_add_co_u32_e32 v74, vcc, s2, v44
	v_add_f32_dpp v32, v32, v32 row_half_mirror row_mask:0xf bank_mask:0xf bound_ctrl:1
	s_mov_b64 s[2:3], 0xf000
	v_addc_co_u32_e32 v75, vcc, 0, v45, vcc
	v_add_f32_dpp v32, v32, v32 row_mirror row_mask:0xf bank_mask:0xf bound_ctrl:1
	v_lshl_add_u64 v[120:121], v[44:45], 0, s[2:3]
	s_mov_b32 s2, 0xe000
	v_mov_b32_dpp v51, v32 row_bcast:15 row_mask:0xa bank_mask:0xf
	v_add_f32_e32 v32, v32, v51
	v_mov_b32_e32 v51, 0
	v_add_co_u32_e32 v128, vcc, s2, v44
	s_nop 0
	v_mov_b32_dpp v51, v32 row_bcast:31 row_mask:0xc bank_mask:0xf
	v_add_f32_e32 v32, v32, v51
	v_addc_co_u32_e32 v129, vcc, 0, v45, vcc
	v_readlane_b32 s2, v32, 63
	v_mul_f32_e32 v95, v54, v55
	s_mov_b32 s3, 0x12000
	v_add_f32_e32 v32, s2, v86
	v_rsq_f32_e32 v51, v32
	s_mov_b32 s2, 0xf000
	v_add_co_u32_e32 v66, vcc, s2, v44
	v_mul_f32_e32 v49, v49, v51
	v_mul_f32_e32 v49, 0x3e000000, v49
	v_cvt_pk_bf16_f32 v113, v49, s0
	v_mul_f32_e32 v49, 0xbfb8aa3b, v123
	v_exp_f32_e32 v51, v49
	v_mov_b32_e32 v64, 0
	v_mov_b32_e32 v32, v61
	v_add_f32_e32 v51, 1.0, v51
	v_rcp_f32_e32 v56, v51
	v_pk_mul_f32 v[62:63], v[10:11], v[32:33]
	v_mul_f32_e32 v61, v12, v61
	v_mul_f32_e32 v69, v10, v33
	v_mul_f32_e32 v56, v123, v56
	v_mul_f32_e32 v57, v56, v56
	v_mov_b32_e32 v68, v62
	v_lshlrev_b32_e32 v62, 16, v173
	v_mov_b32_dpp v64, v57 quad_perm:[1,0,3,2] row_mask:0xf bank_mask:0xf
	v_fmac_f32_e32 v64, v56, v56
	v_mul_f32_e32 v70, v9, v100
	v_fmac_f32_e32 v70, v5, v98
	v_add_f32_dpp v57, v64, v64 quad_perm:[2,3,0,1] row_mask:0xf bank_mask:0xf bound_ctrl:1
	v_mov_b32_e32 v64, 0
	v_fmac_f32_e32 v70, v7, v41
	v_add_f32_dpp v57, v57, v57 row_half_mirror row_mask:0xf bank_mask:0xf bound_ctrl:1
	v_fmac_f32_e32 v70, v105, v39
	v_addc_co_u32_e32 v67, vcc, 0, v45, vcc
	v_add_f32_dpp v57, v57, v57 row_mirror row_mask:0xf bank_mask:0xf bound_ctrl:1
	v_mov_b32_dpp v64, v57 row_bcast:15 row_mask:0xa bank_mask:0xf
	v_add_f32_e32 v57, v57, v64
	v_mov_b32_e32 v64, 0
	ds_write_b16 v114, v113 offset:1024
	s_mov_b64 s[98:99], 0x10000
	v_lshl_add_u64 v[150:151], v[44:45], 0, s[98:99]
	global_load_ushort v192, v[150:151], off offset:-1024
	global_load_ushort v198, v[150:151], off
	global_load_ushort v199, v[150:151], off offset:1024
	s_mov_b64 s[98:99], 0x11000
	v_lshl_add_u64 v[150:151], v[44:45], 0, s[98:99]
	global_load_ushort v195, v[150:151], off offset:-1024
	global_load_ushort v197, v[150:151], off offset:1024
	global_load_ushort v200, v[150:151], off
	s_mov_b64 s[98:99], 0x12000
	v_lshl_add_u64 v[150:151], v[44:45], 0, s[98:99]
	global_load_ushort v193, v[150:151], off offset:-1024
	global_load_ushort v201, v[150:151], off
	s_mov_b64 s[98:99], 0x13000
	v_lshl_add_u64 v[150:151], v[44:45], 0, s[98:99]
	global_load_ushort v194, v[150:151], off offset:-1024
	s_waitcnt vmcnt(11) lgkmcnt(0)
	v_lshlrev_b32_e32 v107, 16, v177
	v_mov_b32_dpp v64, v57 row_bcast:31 row_mask:0xc bank_mask:0xf
	v_add_f32_e32 v57, v57, v64
	v_lshlrev_b32_e32 v121, 16, v178
	v_readlane_b32 s2, v57, 63
	s_nop 1
	v_add_f32_e32 v57, s2, v86
	v_rsq_f32_e32 v64, v57
	v_mul_f32_e32 v57, v13, v60
	v_mov_b32_e32 v60, v77
	v_mul_f32_e32 v56, v56, v64
	v_mul_f32_e32 v64, 0x3e000000, v56
	v_mov_b32_e32 v56, v76
	v_pk_add_f32 v[56:57], v[56:57], v[60:61]
	v_mul_f32_e32 v61, v11, v62
	v_pk_add_f32 v[56:57], v[56:57], v[68:69]
	v_mov_b32_e32 v60, v63
	v_pk_add_f32 v[56:57], v[56:57], v[60:61]
	v_mov_b32_e32 v63, 0
	v_mul_f32_e32 v60, 0xbfb8aa3b, v56
	v_mul_f32_e32 v61, 0xbfb8aa3b, v57
	v_exp_f32_e32 v60, v60
	v_exp_f32_e32 v61, v61
	v_pk_mul_f32 v[68:69], v[14:15], v[32:33]
	v_cvt_pk_bf16_f32 v64, v64, s0
	v_add_f32_e32 v60, 1.0, v60
	v_add_f32_e32 v61, 1.0, v61
	v_rcp_f32_e32 v60, v60
	v_rcp_f32_e32 v61, v61
	v_mul_f32_e32 v33, v13, v33
	v_mov_b32_e32 v76, 0
	v_pk_mul_f32 v[56:57], v[56:57], v[60:61]
	s_nop 0
	v_pk_mul_f32 v[60:61], v[56:57], v[56:57]
	s_nop 1
	v_add_f32_dpp v60, v60, v60 quad_perm:[1,0,3,2] row_mask:0xf bank_mask:0xf bound_ctrl:1
	v_add_f32_dpp v61, v61, v61 quad_perm:[1,0,3,2] row_mask:0xf bank_mask:0xf bound_ctrl:1
	s_nop 0
	v_add_f32_dpp v60, v60, v60 quad_perm:[2,3,0,1] row_mask:0xf bank_mask:0xf bound_ctrl:1
	v_add_f32_dpp v61, v61, v61 quad_perm:[2,3,0,1] row_mask:0xf bank_mask:0xf bound_ctrl:1
	s_nop 0
	v_add_f32_dpp v60, v60, v60 row_half_mirror row_mask:0xf bank_mask:0xf bound_ctrl:1
	v_add_f32_dpp v61, v61, v61 row_half_mirror row_mask:0xf bank_mask:0xf bound_ctrl:1
	s_nop 0
	v_add_f32_dpp v60, v60, v60 row_mirror row_mask:0xf bank_mask:0xf bound_ctrl:1
	v_add_f32_dpp v61, v61, v61 row_mirror row_mask:0xf bank_mask:0xf bound_ctrl:1
	s_nop 0
	v_mov_b32_dpp v63, v60 row_bcast:15 row_mask:0xa bank_mask:0xf
	v_add_f32_e32 v60, v60, v63
	v_mov_b32_e32 v63, 0
	s_nop 1
	v_mov_b32_dpp v63, v60 row_bcast:31 row_mask:0xc bank_mask:0xf
	v_add_f32_e32 v60, v60, v63
	v_mov_b32_e32 v63, 0
	v_readlane_b32 s2, v60, 63
	s_nop 0
	v_mov_b32_dpp v63, v61 row_bcast:15 row_mask:0xa bank_mask:0xf
	v_add_f32_e32 v61, v61, v63
	v_mov_b32_e32 v63, 0
	v_add_f32_e32 v60, s2, v86
	v_rsq_f32_e32 v60, v60
	v_mov_b32_dpp v63, v61 row_bcast:31 row_mask:0xc bank_mask:0xf
	v_add_f32_e32 v61, v61, v63
	v_mul_f32_e32 v63, 0xbfb8aa3b, v70
	v_exp_f32_e32 v71, v63
	v_readlane_b32 s2, v61, 63
	v_lshlrev_b32_e32 v63, 16, v174
	v_mul_f32_e32 v73, v10, v63
	v_add_f32_e32 v61, s2, v86
	v_rsq_f32_e32 v61, v61
	v_add_f32_e32 v32, 1.0, v71
	v_rcp_f32_e32 v32, v32
	v_mul_f32_e32 v71, v12, v62
	v_pk_mul_f32 v[56:57], v[56:57], v[60:61]
	v_mov_b32_e32 v61, 0
	v_cvt_pk_bf16_f32 v60, v56, s0
	v_mul_f32_e32 v32, v70, v32
	ds_write_b16 v114, v60 offset:5120
	ds_write_b16 v116, v64 offset:1152
	v_mul_f32_e32 v60, v32, v32
	v_lshlrev_b32_e32 v104, 16, v179
	v_lshlrev_b32_e32 v110, 16, v180
	v_mov_b32_dpp v61, v60 quad_perm:[1,0,3,2] row_mask:0xf bank_mask:0xf
	v_fmac_f32_e32 v61, v32, v32
	v_fmac_f32_e32 v132, v105, v104
	v_cvt_pk_bf16_f32 v38, v56, v57
	v_add_f32_dpp v60, v61, v61 quad_perm:[2,3,0,1] row_mask:0xf bank_mask:0xf bound_ctrl:1
	v_mov_b32_e32 v61, 0
	s_nop 0
	v_add_f32_dpp v60, v60, v60 row_half_mirror row_mask:0xf bank_mask:0xf bound_ctrl:1
	s_nop 1
	v_add_f32_dpp v60, v60, v60 row_mirror row_mask:0xf bank_mask:0xf bound_ctrl:1
	s_nop 1
	v_mov_b32_dpp v61, v60 row_bcast:15 row_mask:0xa bank_mask:0xf
	v_add_f32_e32 v60, v60, v61
	v_mov_b32_e32 v61, 0
	s_nop 1
	v_mov_b32_dpp v61, v60 row_bcast:31 row_mask:0xc bank_mask:0xf
	v_add_f32_e32 v60, v60, v61
	s_nop 0
	v_readlane_b32 s2, v60, 63
	s_nop 1
	v_add_f32_e32 v60, s2, v86
	v_rsq_f32_e32 v64, v60
	v_cvt_pk_bf16_f32 v60, v57, s0
	ds_write_b16 v116, v60 offset:5248
	v_pk_mul_f32 v[60:61], v[10:11], v[62:63]
	v_mul_f32_e32 v32, v32, v64
	v_mul_f32_e32 v64, v9, v41
	v_fmac_f32_e32 v64, v5, v100
	v_fmac_f32_e32 v64, v7, v39
	v_fmac_f32_e32 v64, v105, v37
	v_mul_f32_e32 v70, 0xbfb8aa3b, v64
	v_exp_f32_e32 v70, v70
	v_mul_f32_e32 v32, 0x3e000000, v32
	v_cvt_pk_bf16_f32 v32, v32, s0
	ds_write_b16 v115, v32 offset:1280
	v_add_f32_e32 v32, 1.0, v70
	v_rcp_f32_e32 v32, v32
	v_mov_b32_e32 v70, v69
	v_mov_b32_e32 v72, v60
	v_mul_f32_e32 v41, 0xbfb8aa3b, v132
	v_mul_f32_e32 v74, v64, v32
	v_mul_f32_e32 v32, v74, v74
	v_mov_b32_e32 v64, 0
	v_exp_f32_e32 v41, v41
	s_nop 0
	v_mov_b32_dpp v64, v32 quad_perm:[1,0,3,2] row_mask:0xf bank_mask:0xf
	v_fmac_f32_e32 v64, v74, v74
	v_add_f32_e32 v41, 1.0, v41
	v_rcp_f32_e32 v41, v41
	v_add_f32_dpp v32, v64, v64 quad_perm:[2,3,0,1] row_mask:0xf bank_mask:0xf bound_ctrl:1
	v_mov_b32_e32 v64, 0
	v_mul_f32_e32 v41, v132, v41
	v_add_f32_dpp v32, v32, v32 row_half_mirror row_mask:0xf bank_mask:0xf bound_ctrl:1
	s_nop 1
	v_add_f32_dpp v32, v32, v32 row_mirror row_mask:0xf bank_mask:0xf bound_ctrl:1
	s_nop 1
	v_mov_b32_dpp v64, v32 row_bcast:15 row_mask:0xa bank_mask:0xf
	v_add_f32_e32 v75, v32, v64
	v_mov_b32_e32 v32, v68
	v_pk_add_f32 v[32:33], v[32:33], v[70:71]
	v_lshlrev_b32_e32 v64, 16, v181
	v_pk_add_f32 v[32:33], v[32:33], v[72:73]
	v_mul_f32_e32 v69, v11, v64
	v_mov_b32_e32 v68, v61
	v_pk_add_f32 v[32:33], v[32:33], v[68:69]
	v_mov_b32_e32 v69, 0
	v_mul_f32_e32 v60, 0xbfb8aa3b, v32
	v_mul_f32_e32 v61, 0xbfb8aa3b, v33
	v_exp_f32_e32 v60, v60
	v_exp_f32_e32 v61, v61
	v_mov_b32_dpp v76, v75 row_bcast:31 row_mask:0xc bank_mask:0xf
	v_add_f32_e32 v68, v75, v76
	v_add_f32_e32 v60, 1.0, v60
	v_add_f32_e32 v61, 1.0, v61
	v_rcp_f32_e32 v60, v60
	v_rcp_f32_e32 v61, v61
	v_readlane_b32 s2, v68, 63
	v_pk_mul_f32 v[32:33], v[32:33], v[60:61]
	s_nop 0
	v_pk_mul_f32 v[60:61], v[32:33], v[32:33]
	v_add_f32_e32 v68, s2, v86
	v_rsq_f32_e32 v68, v68
	v_add_f32_dpp v60, v60, v60 quad_perm:[1,0,3,2] row_mask:0xf bank_mask:0xf bound_ctrl:1
	v_add_f32_dpp v61, v61, v61 quad_perm:[1,0,3,2] row_mask:0xf bank_mask:0xf bound_ctrl:1
	v_mul_f32_e32 v68, v74, v68
	v_add_f32_dpp v60, v60, v60 quad_perm:[2,3,0,1] row_mask:0xf bank_mask:0xf bound_ctrl:1
	v_add_f32_dpp v61, v61, v61 quad_perm:[2,3,0,1] row_mask:0xf bank_mask:0xf bound_ctrl:1
	v_mul_f32_e32 v68, 0x3e000000, v68
	v_add_f32_dpp v60, v60, v60 row_half_mirror row_mask:0xf bank_mask:0xf bound_ctrl:1
	v_add_f32_dpp v61, v61, v61 row_half_mirror row_mask:0xf bank_mask:0xf bound_ctrl:1
	v_cvt_pk_bf16_f32 v68, v68, s0
	v_add_f32_dpp v60, v60, v60 row_mirror row_mask:0xf bank_mask:0xf bound_ctrl:1
	v_add_f32_dpp v61, v61, v61 row_mirror row_mask:0xf bank_mask:0xf bound_ctrl:1
	s_nop 0
	v_mov_b32_dpp v69, v60 row_bcast:15 row_mask:0xa bank_mask:0xf
	v_add_f32_e32 v60, v60, v69
	v_mov_b32_e32 v69, 0
	s_nop 1
	v_mov_b32_dpp v69, v60 row_bcast:31 row_mask:0xc bank_mask:0xf
	v_add_f32_e32 v60, v60, v69
	v_mov_b32_e32 v69, 0
	v_readlane_b32 s2, v60, 63
	s_nop 0
	v_mov_b32_dpp v69, v61 row_bcast:15 row_mask:0xa bank_mask:0xf
	v_add_f32_e32 v61, v61, v69
	v_mov_b32_e32 v69, 0
	v_add_f32_e32 v60, s2, v86
	v_rsq_f32_e32 v60, v60
	v_mov_b32_dpp v69, v61 row_bcast:31 row_mask:0xc bank_mask:0xf
	v_add_f32_e32 v61, v61, v69
	s_nop 0
	v_readlane_b32 s2, v61, 63
	s_nop 1
	v_add_f32_e32 v61, s2, v86
	v_rsq_f32_e32 v61, v61
	s_mov_b32 s2, 0x10000
	v_add_co_u32_e32 v72, vcc, s2, v44
	v_pk_mul_f32 v[60:61], v[32:33], v[60:61]
	s_nop 0
	v_addc_co_u32_e32 v73, vcc, 0, v45, vcc
	v_cvt_pk_bf16_f32 v32, v60, s0
	ds_write_b16 v115, v32 offset:5376
	ds_write_b16 v117, v68 offset:1408
	v_cvt_pk_bf16_f32 v32, v61, s0
	ds_write_b16 v117, v32 offset:5504
	s_mov_b32 s2, 0x11000
	v_add_co_u32_e32 v76, vcc, s2, v44
	v_pk_mul_f32 v[32:33], v[4:5], v[34:35] op_sel_hi:[0,1]
	s_nop 0
	v_addc_co_u32_e32 v77, vcc, 0, v45, vcc
	v_add_co_u32_e32 v74, vcc, s3, v44
	v_lshlrev_b32_e32 v67, 16, v175
	s_nop 0
	v_addc_co_u32_e32 v75, vcc, 0, v45, vcc
	v_lshlrev_b32_e32 v66, 16, v176
	v_pk_fma_f32 v[32:33], v[2:3], v[58:59], v[32:33] op_sel_hi:[0,1,1]
	v_pk_mov_b32 v[34:35], v[34:35], v[66:67] op_sel:[1,0]
	v_readlane_b32 s3, v3, 8
	v_pk_fma_f32 v[32:33], v[6:7], v[34:35], v[32:33] op_sel_hi:[0,1,1]
	v_pk_fma_f32 v[32:33], v[8:9], v[66:67], v[32:33] op_sel_hi:[0,1,1]
	v_mul_f32_e32 v47, 0xbfb8aa3b, v32
	v_exp_f32_e32 v47, v47
	v_mul_f32_e32 v58, 0xbfb8aa3b, v33
	v_exp_f32_e32 v59, v58
	v_mov_b32_e32 v65, s3
	v_add_f32_e32 v47, 1.0, v47
	v_rcp_f32_e32 v58, v47
	v_add_f32_e32 v47, 1.0, v59
	v_rcp_f32_e32 v59, v47
	v_readlane_b32 s3, v102, 9
	v_pk_mul_f32 v[68:69], v[4:5], v[66:67] op_sel_hi:[0,1]
	v_pk_fma_f32 v[34:35], v[2:3], v[34:35], v[68:69] op_sel_hi:[0,1,1]
	v_pk_mul_f32 v[32:33], v[32:33], v[58:59]
	v_mov_b32_e32 v58, s4
	v_mul_f32_e32 v58, s3, v58
	v_mul_f32_e32 v97, v57, v58
	v_lshlrev_b32_e32 v59, 16, v182
	v_lshlrev_b32_e32 v58, 16, v183
	v_pk_mov_b32 v[70:71], v[66:67], v[58:59] op_sel:[1,0]
	v_readlane_b32 s2, v102, 8
	v_pk_fma_f32 v[34:35], v[6:7], v[70:71], v[34:35] op_sel_hi:[0,1,1]
	v_pk_fma_f32 v[34:35], v[8:9], v[58:59], v[34:35] op_sel_hi:[0,1,1]
	v_mul_f32_e32 v47, s2, v65
	v_mul_f32_e32 v98, v56, v47
	v_mul_f32_e32 v47, 0xbfb8aa3b, v34
	v_exp_f32_e32 v47, v47
	v_mul_f32_e32 v65, 0xbfb8aa3b, v35
	v_exp_f32_e32 v65, v65
	v_pk_mul_f32 v[32:33], v[32:33], s[2:3]
	v_readlane_b32 s3, v3, 10
	v_add_f32_e32 v47, 1.0, v47
	v_readlane_b32 s2, v102, 10
	v_mov_b32_e32 v68, s3
	v_rcp_f32_e32 v66, v47
	v_add_f32_e32 v47, 1.0, v65
	v_rcp_f32_e32 v67, v47
	v_mul_f32_e32 v47, s2, v68
	v_pk_mul_f32 v[68:69], v[14:15], v[62:63]
	v_mul_f32_e32 v100, v60, v47
	v_mul_f32_e32 v47, v41, v41
	v_mov_b32_e32 v62, 0
	v_readlane_b32 s4, v3, 11
	v_readlane_b32 s3, v102, 11
	v_mov_b32_dpp v62, v47 quad_perm:[1,0,3,2] row_mask:0xf bank_mask:0xf
	v_fmac_f32_e32 v62, v41, v41
	v_pk_mul_f32 v[34:35], v[34:35], v[66:67]
	v_mov_b32_e32 v65, s4
	v_add_f32_dpp v47, v62, v62 quad_perm:[2,3,0,1] row_mask:0xf bank_mask:0xf bound_ctrl:1
	v_mov_b32_e32 v62, 0
	v_pk_mul_f32 v[34:35], v[34:35], s[2:3]
	v_add_f32_dpp v47, v47, v47 row_half_mirror row_mask:0xf bank_mask:0xf bound_ctrl:1
	v_mul_f32_e32 v66, s3, v65
	s_mov_b32 s2, 0x13000
	v_add_f32_dpp v47, v47, v47 row_mirror row_mask:0xf bank_mask:0xf bound_ctrl:1
	v_mul_f32_e32 v99, v61, v66
	v_add_co_u32_e32 v66, vcc, s2, v44
	v_mov_b32_dpp v62, v47 row_bcast:15 row_mask:0xa bank_mask:0xf
	v_add_f32_e32 v47, v47, v62
	v_mov_b32_e32 v62, 0
	v_addc_co_u32_e32 v67, vcc, 0, v45, vcc
	s_nop 0
	v_mov_b32_dpp v62, v47 row_bcast:31 row_mask:0xc bank_mask:0xf
	v_add_f32_e32 v47, v47, v62
	v_mul_f32_e32 v62, v9, v37
	v_fmac_f32_e32 v62, v5, v39
	v_fmac_f32_e32 v62, v7, v104
	v_fmac_f32_e32 v62, v105, v107
	v_mul_f32_e32 v39, 0xbfb8aa3b, v62
	v_exp_f32_e32 v39, v39
	v_readlane_b32 s2, v47, 63
	v_lshlrev_b32_e32 v65, 16, v184
	v_add_f32_e32 v47, s2, v86
	v_rsq_f32_e32 v47, v47
	v_add_f32_e32 v39, 1.0, v39
	v_rcp_f32_e32 v39, v39
	s_mov_b64 s[98:99], 0x12000
	v_lshl_add_u64 v[150:151], v[44:45], 0, s[98:99]
	global_load_ushort v206, v[150:151], off offset:1024
	s_mov_b64 s[98:99], 0x13000
	v_lshl_add_u64 v[150:151], v[44:45], 0, s[98:99]
	global_load_ushort v205, v[150:151], off offset:1024
	global_load_ushort v204, v[150:151], off
	s_mov_b64 s[98:99], 0x14000
	v_lshl_add_u64 v[150:151], v[44:45], 0, s[98:99]
	global_load_ushort v202, v[150:151], off offset:-1024
	global_load_ushort v207, v[150:151], off
	global_load_ushort v209, v[150:151], off offset:1024
	s_mov_b64 s[98:99], 0x15000
	v_lshl_add_u64 v[150:151], v[44:45], 0, s[98:99]
	global_load_ushort v203, v[150:151], off offset:-1024
	global_load_ushort v210, v[150:151], off
	global_load_ushort v208, v[150:151], off offset:1024
	s_mov_b64 s[98:99], 0x16000
	v_lshl_add_u64 v[150:151], v[44:45], 0, s[98:99]
	global_load_ushort v212, v[150:151], off offset:1024
	s_mov_b64 s[98:99], 0x17000
	v_lshl_add_u64 v[150:151], v[44:45], 0, s[98:99]
	global_load_ushort v211, v[150:151], off offset:1024
	s_waitcnt vmcnt(11) lgkmcnt(0)
	v_lshlrev_b32_e32 v120, 16, v192
	v_mul_f32_e32 v41, v41, v47
	v_mul_f32_e32 v41, 0x3e000000, v41
	v_cvt_pk_bf16_f32 v41, v41, s0
	v_mul_f32_e32 v39, v62, v39
	ds_write_b16 v118, v41 offset:1536
	v_mul_f32_e32 v41, v39, v39
	v_mov_b32_e32 v47, 0
	v_mul_f32_e32 v63, v13, v63
	v_mul_f32_e32 v73, v12, v64
	v_mov_b32_dpp v47, v41 quad_perm:[1,0,3,2] row_mask:0xf bank_mask:0xf
	v_fmac_f32_e32 v47, v39, v39
	v_mov_b32_e32 v62, v68
	v_mov_b32_e32 v72, v69
	v_add_f32_dpp v41, v47, v47 quad_perm:[2,3,0,1] row_mask:0xf bank_mask:0xf bound_ctrl:1
	v_mov_b32_e32 v47, 0
	v_pk_add_f32 v[62:63], v[62:63], v[72:73]
	v_add_f32_dpp v41, v41, v41 row_half_mirror row_mask:0xf bank_mask:0xf bound_ctrl:1
	v_lshlrev_b32_e32 v69, 16, v185
	v_lshlrev_b32_e32 v68, 16, v186
	v_add_f32_dpp v41, v41, v41 row_mirror row_mask:0xf bank_mask:0xf bound_ctrl:1
	v_pk_mul_f32 v[72:73], v[4:5], v[58:59] op_sel_hi:[0,1]
	v_pk_fma_f32 v[72:73], v[2:3], v[70:71], v[72:73] op_sel_hi:[0,1,1]
	v_mov_b32_dpp v47, v41 row_bcast:15 row_mask:0xa bank_mask:0xf
	v_add_f32_e32 v41, v41, v47
	v_mov_b32_e32 v47, 0
	v_pk_mov_b32 v[70:71], v[58:59], v[68:69] op_sel:[1,0]
	v_pk_mul_f32 v[74:75], v[10:11], v[64:65]
	v_mov_b32_dpp v47, v41 row_bcast:31 row_mask:0xc bank_mask:0xf
	v_pk_fma_f32 v[58:59], v[6:7], v[70:71], v[72:73] op_sel_hi:[0,1,1]
	v_lshlrev_b32_e32 v77, 16, v193
	v_lshlrev_b32_e32 v76, 16, v194
	v_add_f32_e32 v41, v41, v47
	v_mul_f32_e32 v131, v10, v65
	v_mov_b32_e32 v130, v74
	v_pk_fma_f32 v[72:73], v[8:9], v[68:69], v[58:59] op_sel_hi:[0,1,1]
	v_lshlrev_b32_e32 v58, 16, v187
	v_readlane_b32 s3, v41, 63
	v_pk_add_f32 v[62:63], v[62:63], v[130:131]
	v_mul_f32_e32 v131, v11, v58
	v_mov_b32_e32 v130, v75
	v_add_f32_e32 v41, s3, v86
	v_pk_add_f32 v[62:63], v[62:63], v[130:131]
	v_rsq_f32_e32 v41, v41
	v_mul_f32_e32 v47, 0xbfb8aa3b, v62
	v_exp_f32_e32 v47, v47
	v_mul_f32_e32 v59, 0xbfb8aa3b, v63
	v_exp_f32_e32 v59, v59
	v_mul_f32_e32 v39, v39, v41
	v_mul_f32_e32 v41, v9, v104
	v_fmac_f32_e32 v41, v5, v37
	v_add_f32_e32 v37, 1.0, v47
	v_rcp_f32_e32 v74, v37
	v_add_f32_e32 v37, 1.0, v59
	v_rcp_f32_e32 v75, v37
	v_mov_b32_e32 v47, 0
	v_fmac_f32_e32 v41, v7, v107
	v_fmac_f32_e32 v41, v105, v121
	v_pk_mul_f32 v[62:63], v[62:63], v[74:75]
	v_mul_f32_e32 v39, 0x3e000000, v39
	v_pk_mul_f32 v[74:75], v[62:63], v[62:63]
	v_cvt_pk_bf16_f32 v39, v39, s0
	v_pk_mul_f32 v[130:131], v[14:15], v[64:65]
	v_add_f32_dpp v37, v74, v74 quad_perm:[1,0,3,2] row_mask:0xf bank_mask:0xf bound_ctrl:1
	v_lshlrev_b32_e32 v59, 16, v188
	v_mul_f32_e32 v65, v13, v65
	v_add_f32_dpp v37, v37, v37 quad_perm:[2,3,0,1] row_mask:0xf bank_mask:0xf bound_ctrl:1
	v_mul_f32_e32 v133, v12, v58
	v_mov_b32_e32 v132, v131
	v_add_f32_dpp v37, v37, v37 row_half_mirror row_mask:0xf bank_mask:0xf bound_ctrl:1
	v_mul_f32_e32 v135, v10, v59
	v_readlane_b32 s2, v3, 12
	v_add_f32_dpp v37, v37, v37 row_mirror row_mask:0xf bank_mask:0xf bound_ctrl:1
	v_readlane_b32 s4, v3, 15
	v_lshlrev_b32_e32 v78, 16, v195
	v_mov_b32_dpp v47, v37 row_bcast:15 row_mask:0xa bank_mask:0xf
	v_add_f32_e32 v37, v37, v47
	v_mov_b32_e32 v47, 0
	v_lshlrev_b32_e32 v53, 16, v197
	v_mul_f32_e32 v126, v9, v77
	v_mov_b32_dpp v47, v37 row_bcast:31 row_mask:0xc bank_mask:0xf
	v_add_f32_e32 v37, v37, v47
	v_mov_b32_e32 v47, 0
	v_readlane_b32 s3, v37, 63
	v_fmac_f32_e32 v126, v5, v78
	v_fmac_f32_e32 v126, v7, v76
	v_add_f32_e32 v37, s3, v86
	v_rsq_f32_e32 v74, v37
	s_nop 0
	v_add_f32_dpp v37, v75, v75 quad_perm:[1,0,3,2] row_mask:0xf bank_mask:0xf bound_ctrl:1
	s_nop 1
	v_add_f32_dpp v37, v37, v37 quad_perm:[2,3,0,1] row_mask:0xf bank_mask:0xf bound_ctrl:1
	s_nop 1
	v_add_f32_dpp v37, v37, v37 row_half_mirror row_mask:0xf bank_mask:0xf bound_ctrl:1
	s_nop 1
	v_add_f32_dpp v37, v37, v37 row_mirror row_mask:0xf bank_mask:0xf bound_ctrl:1
	s_nop 1
	v_mov_b32_dpp v47, v37 row_bcast:15 row_mask:0xa bank_mask:0xf
	v_add_f32_e32 v37, v37, v47
	v_mov_b32_e32 v47, 0
	s_nop 1
	v_mov_b32_dpp v47, v37 row_bcast:31 row_mask:0xc bank_mask:0xf
	v_add_f32_e32 v37, v37, v47
	s_nop 0
	v_readlane_b32 s3, v37, 63
	s_nop 1
	v_add_f32_e32 v37, s3, v86
	v_rsq_f32_e32 v75, v37
	v_mul_f32_e32 v37, 0xbfb8aa3b, v41
	v_exp_f32_e32 v37, v37
	v_pk_mul_f32 v[74:75], v[62:63], v[74:75]
	s_nop 0
	v_cvt_pk_bf16_f32 v47, v74, s0
	v_add_f32_e32 v37, 1.0, v37
	v_rcp_f32_e32 v37, v37
	ds_write_b16 v118, v47 offset:5632
	ds_write_b16 v119, v39 offset:1664
	v_mov_b32_e32 v47, 0
	v_cvt_pk_bf16_f32 v39, v75, s0
	v_mul_f32_e32 v37, v41, v37
	v_mul_f32_e32 v41, v37, v37
	ds_write_b16 v119, v39 offset:5760
	s_nop 0
	v_mov_b32_dpp v47, v41 quad_perm:[1,0,3,2] row_mask:0xf bank_mask:0xf
	v_fmac_f32_e32 v47, v37, v37
	s_nop 1
	v_add_f32_dpp v41, v47, v47 quad_perm:[2,3,0,1] row_mask:0xf bank_mask:0xf bound_ctrl:1
	v_mov_b32_e32 v47, 0
	s_nop 0
	v_add_f32_dpp v41, v41, v41 row_half_mirror row_mask:0xf bank_mask:0xf bound_ctrl:1
	s_nop 1
	v_add_f32_dpp v41, v41, v41 row_mirror row_mask:0xf bank_mask:0xf bound_ctrl:1
	s_nop 1
	v_mov_b32_dpp v47, v41 row_bcast:15 row_mask:0xa bank_mask:0xf
	v_add_f32_e32 v41, v41, v47
	v_mov_b32_e32 v47, 0
	s_nop 1
	v_mov_b32_dpp v47, v41 row_bcast:31 row_mask:0xc bank_mask:0xf
	v_add_f32_e32 v41, v41, v47
	v_mul_f32_e32 v47, v9, v107
	v_fmac_f32_e32 v47, v5, v104
	v_fmac_f32_e32 v47, v7, v121
	v_fmac_f32_e32 v47, v105, v110
	v_mul_f32_e32 v62, 0xbfb8aa3b, v47
	v_readlane_b32 s3, v41, 63
	v_exp_f32_e32 v64, v62
	v_pk_mul_f32 v[62:63], v[10:11], v[58:59]
	v_add_f32_e32 v41, s3, v86
	v_rsq_f32_e32 v41, v41
	v_add_f32_e32 v39, 1.0, v64
	v_rcp_f32_e32 v39, v39
	v_mov_b32_e32 v64, v130
	v_mul_f32_e32 v37, v37, v41
	v_mul_f32_e32 v37, 0x3e000000, v37
	v_cvt_pk_bf16_f32 v37, v37, s0
	ds_write_b16 v124, v37 offset:1792
	v_mul_f32_e32 v37, v47, v39
	v_mul_f32_e32 v39, v37, v37
	v_mov_b32_e32 v41, 0
	v_pk_add_f32 v[64:65], v[64:65], v[132:133]
	v_mov_b32_e32 v134, v62
	v_mov_b32_dpp v41, v39 quad_perm:[1,0,3,2] row_mask:0xf bank_mask:0xf
	v_fmac_f32_e32 v41, v37, v37
	v_lshlrev_b32_e32 v62, 16, v189
	v_pk_add_f32 v[64:65], v[64:65], v[134:135]
	v_add_f32_dpp v39, v41, v41 quad_perm:[2,3,0,1] row_mask:0xf bank_mask:0xf bound_ctrl:1
	v_mov_b32_e32 v41, 0
	v_mul_f32_e32 v131, v11, v62
	v_add_f32_dpp v39, v39, v39 row_half_mirror row_mask:0xf bank_mask:0xf bound_ctrl:1
	v_mov_b32_e32 v130, v63
	v_pk_add_f32 v[64:65], v[64:65], v[130:131]
	v_add_f32_dpp v39, v39, v39 row_mirror row_mask:0xf bank_mask:0xf bound_ctrl:1
	v_mov_b32_e32 v55, 0
	v_cvt_pk_bf16_f32 v132, v74, v75
	v_mov_b32_dpp v41, v39 row_bcast:15 row_mask:0xa bank_mask:0xf
	v_add_f32_e32 v39, v39, v41
	v_mov_b32_e32 v41, 0
	v_lshlrev_b32_e32 v63, 16, v198
	s_nop 0
	v_mov_b32_dpp v41, v39 row_bcast:31 row_mask:0xc bank_mask:0xf
	v_add_f32_e32 v39, v39, v41
	s_nop 0
	v_readlane_b32 s3, v39, 63
	s_nop 1
	v_add_f32_e32 v39, s3, v86
	v_rsq_f32_e32 v39, v39
	s_nop 0
	v_mul_f32_e32 v37, v37, v39
	v_mul_f32_e32 v37, 0x3e000000, v37
	v_cvt_pk_bf16_f32 v103, v37, s0
	v_mul_f32_e32 v37, 0xbfb8aa3b, v64
	v_exp_f32_e32 v37, v37
	v_mul_f32_e32 v39, 0xbfb8aa3b, v65
	v_exp_f32_e32 v39, v39
	v_add_f32_e32 v37, 1.0, v37
	v_rcp_f32_e32 v130, v37
	v_add_f32_e32 v37, 1.0, v39
	v_rcp_f32_e32 v131, v37
	v_cvt_pk_bf16_f32 v37, v40, v46
	v_cvt_pk_bf16_f32 v39, v60, v61
	v_pk_mul_f32 v[40:41], v[64:65], v[130:131]
	s_nop 0
	v_pk_mul_f32 v[46:47], v[40:41], v[40:41]
	v_cvt_pk_bf16_f32 v131, v52, v54
	v_cvt_pk_bf16_f32 v130, v48, v50
	v_add_f32_dpp v46, v46, v46 quad_perm:[1,0,3,2] row_mask:0xf bank_mask:0xf bound_ctrl:1
	v_add_f32_dpp v47, v47, v47 quad_perm:[1,0,3,2] row_mask:0xf bank_mask:0xf bound_ctrl:1
	s_nop 0
	v_add_f32_dpp v46, v46, v46 quad_perm:[2,3,0,1] row_mask:0xf bank_mask:0xf bound_ctrl:1
	v_add_f32_dpp v47, v47, v47 quad_perm:[2,3,0,1] row_mask:0xf bank_mask:0xf bound_ctrl:1
	s_nop 0
	v_add_f32_dpp v46, v46, v46 row_half_mirror row_mask:0xf bank_mask:0xf bound_ctrl:1
	v_add_f32_dpp v47, v47, v47 row_half_mirror row_mask:0xf bank_mask:0xf bound_ctrl:1
	s_nop 0
	v_add_f32_dpp v46, v46, v46 row_mirror row_mask:0xf bank_mask:0xf bound_ctrl:1
	v_add_f32_dpp v47, v47, v47 row_mirror row_mask:0xf bank_mask:0xf bound_ctrl:1
	s_nop 0
	v_mov_b32_dpp v55, v46 row_bcast:15 row_mask:0xa bank_mask:0xf
	v_add_f32_e32 v46, v46, v55
	v_mov_b32_e32 v55, 0
	s_nop 1
	v_mov_b32_dpp v55, v46 row_bcast:31 row_mask:0xc bank_mask:0xf
	v_add_f32_e32 v46, v46, v55
	v_mov_b32_e32 v55, 0
	v_readlane_b32 s3, v46, 63
	s_nop 0
	v_mov_b32_dpp v55, v47 row_bcast:15 row_mask:0xa bank_mask:0xf
	v_add_f32_e32 v47, v47, v55
	v_mov_b32_e32 v55, 0
	v_add_f32_e32 v46, s3, v86
	v_rsq_f32_e32 v46, v46
	v_mov_b32_dpp v55, v47 row_bcast:31 row_mask:0xc bank_mask:0xf
	v_add_f32_e32 v47, v47, v55
	s_nop 0
	v_readlane_b32 s3, v47, 63
	s_nop 1
	v_add_f32_e32 v47, s3, v86
	v_rsq_f32_e32 v47, v47
	s_mov_b32 s3, 0x14000
	v_pk_mul_f32 v[54:55], v[40:41], v[46:47]
	s_nop 0
	v_cvt_pk_bf16_f32 v40, v54, s0
	ds_write_b16 v124, v40 offset:5888
	ds_write_b16 v125, v103 offset:1920
	v_cvt_pk_bf16_f32 v40, v55, s0
	ds_write_b16 v125, v40 offset:6016
	v_add_co_u32_e32 v40, vcc, s14, v42
	v_cvt_pk_bf16_f32 v133, v54, v55
	s_nop 0
	v_addc_co_u32_e32 v41, vcc, 0, v43, vcc
	global_store_dwordx4 v[40:41], v[36:39], off offset:2048
	global_store_dwordx4 v[16:17], v[130:133], off offset:512
	v_add_co_u32_e32 v56, vcc, s3, v44
	v_mov_b32_e32 v38, s2
	s_nop 0
	v_addc_co_u32_e32 v57, vcc, 0, v45, vcc
	v_readlane_b32 s2, v3, 13
	v_mul_f32_e32 v38, s6, v38
	v_mul_f32_e32 v104, v74, v38
	v_mov_b32_e32 v39, s2
	v_mul_f32_e32 v39, s7, v39
	v_mul_f32_e32 v103, v75, v39
	v_lshlrev_b32_e32 v41, 16, v190
	v_lshlrev_b32_e32 v40, 16, v191
	v_pk_mul_f32 v[38:39], v[4:5], v[68:69] op_sel_hi:[0,1]
	v_pk_fma_f32 v[38:39], v[2:3], v[70:71], v[38:39] op_sel_hi:[0,1,1]
	v_pk_mov_b32 v[42:43], v[68:69], v[40:41] op_sel:[1,0]
	v_mul_f32_e32 v69, v9, v121
	v_pk_fma_f32 v[38:39], v[6:7], v[42:43], v[38:39] op_sel_hi:[0,1,1]
	v_pk_fma_f32 v[38:39], v[8:9], v[40:41], v[38:39] op_sel_hi:[0,1,1]
	v_mul_f32_e32 v46, 0xbfb8aa3b, v38
	v_mul_f32_e32 v47, 0xbfb8aa3b, v39
	v_exp_f32_e32 v46, v46
	v_exp_f32_e32 v47, v47
	v_readlane_b32 s3, v3, 14
	v_fmac_f32_e32 v69, v5, v107
	v_add_f32_e32 v46, 1.0, v46
	v_add_f32_e32 v47, 1.0, v47
	v_rcp_f32_e32 v46, v46
	v_rcp_f32_e32 v47, v47
	v_readlane_b32 s2, v102, 14
	v_mov_b32_e32 v48, s3
	v_fmac_f32_e32 v69, v7, v110
	v_mul_f32_e32 v66, s2, v48
	v_fmac_f32_e32 v69, v105, v120
	v_mul_f32_e32 v36, 0xbfb8aa3b, v72
	v_mul_f32_e32 v37, 0xbfb8aa3b, v73
	v_readlane_b32 s3, v102, 15
	v_pk_mul_f32 v[38:39], v[38:39], v[46:47]
	v_mov_b32_e32 v46, s4
	v_mul_f32_e32 v107, v54, v66
	v_mul_f32_e32 v54, 0xbfb8aa3b, v69
	v_exp_f32_e32 v36, v36
	v_exp_f32_e32 v37, v37
	v_mul_f32_e32 v67, s3, v46
	v_pk_mul_f32 v[46:47], v[14:15], v[58:59]
	v_exp_f32_e32 v58, v54
	v_pk_mul_f32 v[38:39], v[38:39], s[2:3]
	s_mov_b64 s[2:3], 0x14000
	v_lshl_add_u64 v[48:49], v[44:45], 0, s[2:3]
	s_mov_b64 s[2:3], 0x15000
	v_add_f32_e32 v36, 1.0, v36
	v_add_f32_e32 v37, 1.0, v37
	v_lshl_add_u64 v[50:51], v[44:45], 0, s[2:3]
	s_mov_b64 s[2:3], 0x16000
	v_add_f32_e32 v58, 1.0, v58
	v_rcp_f32_e32 v36, v36
	v_rcp_f32_e32 v37, v37
	v_lshl_add_u64 v[60:61], v[44:45], 0, s[2:3]
	s_mov_b64 s[2:3], 0x17000
	v_rcp_f32_e32 v58, v58
	v_lshl_add_u64 v[64:65], v[44:45], 0, s[2:3]
	s_mov_b32 s2, 0x15000
	v_add_co_u32_e32 v54, vcc, s2, v44
	v_mul_f32_e32 v106, v55, v67
	s_nop 0
	v_addc_co_u32_e32 v55, vcc, 0, v45, vcc
	v_pk_mul_f32 v[36:37], v[72:73], v[36:37]
	v_mul_f32_e32 v50, v69, v58
	v_mul_f32_e32 v48, v50, v50
	v_mov_b32_e32 v49, 0
	v_mul_f32_e32 v61, v9, v110
	v_fmac_f32_e32 v61, v5, v121
	v_mov_b32_dpp v49, v48 quad_perm:[1,0,3,2] row_mask:0xf bank_mask:0xf
	v_fmac_f32_e32 v49, v50, v50
	v_fmac_f32_e32 v61, v7, v120
	v_fmac_f32_e32 v61, v105, v78
	v_add_f32_dpp v48, v49, v49 quad_perm:[2,3,0,1] row_mask:0xf bank_mask:0xf bound_ctrl:1
	v_mov_b32_e32 v49, 0
	s_mov_b32 s2, 0x16000
	v_add_f32_dpp v48, v48, v48 row_half_mirror row_mask:0xf bank_mask:0xf bound_ctrl:1
	v_add_co_u32_e32 v56, vcc, s2, v44
	s_nop 0
	v_add_f32_dpp v48, v48, v48 row_mirror row_mask:0xf bank_mask:0xf bound_ctrl:1
	s_mov_b64 s[98:99], 0x16000
	v_lshl_add_u64 v[150:151], v[44:45], 0, s[98:99]
	global_load_ushort v213, v[150:151], off offset:-1024
	global_load_ushort v215, v[150:151], off
	s_mov_b64 s[98:99], 0x17000
	v_lshl_add_u64 v[150:151], v[44:45], 0, s[98:99]
	global_load_ushort v214, v[150:151], off offset:-1024
	global_load_ushort v216, v[150:151], off
	s_waitcnt vmcnt(10) lgkmcnt(0)
	v_lshlrev_b32_e32 v71, 16, v202
	v_addc_co_u32_e32 v57, vcc, 0, v45, vcc
	v_mov_b32_dpp v49, v48 row_bcast:15 row_mask:0xa bank_mask:0xf
	v_add_f32_e32 v48, v48, v49
	v_mov_b32_e32 v49, 0
	s_mov_b32 s2, 0x17000
	v_readlane_b32 s4, v3, 17
	v_mov_b32_dpp v49, v48 row_bcast:31 row_mask:0xc bank_mask:0xf
	v_add_f32_e32 v48, v48, v49
	v_fmac_f32_e32 v126, v105, v71
	v_readlane_b32 s3, v48, 63
	v_lshlrev_b32_e32 v122, 16, v203
	v_pk_mul_f32 v[36:37], v[36:37], s[6:7]
	v_add_f32_e32 v48, s3, v86
	v_rsq_f32_e32 v51, v48
	v_pk_mul_f32 v[48:49], v[10:11], v[62:63]
	v_readlane_b32 s3, v3, 16
	v_readlane_b32 s7, v102, 21
	v_mul_f32_e32 v50, v50, v51
	v_mul_f32_e32 v50, 0x3e000000, v50
	v_cvt_pk_bf16_f32 v58, v50, s0
	v_mul_f32_e32 v50, 0xbfb8aa3b, v61
	v_exp_f32_e32 v52, v50
	v_add_co_u32_e32 v50, vcc, s2, v44
	v_readlane_b32 s6, v102, 20
	v_add_f32_e32 v52, 1.0, v52
	v_rcp_f32_e32 v64, v52
	v_addc_co_u32_e32 v51, vcc, 0, v45, vcc
	v_mul_f32_e32 v54, v61, v64
	v_mul_f32_e32 v55, v54, v54
	v_mov_b32_e32 v56, 0
	v_mul_f32_e32 v57, v12, v62
	ds_write_b16 v114, v58 offset:2048
	v_mov_b32_dpp v56, v55 quad_perm:[1,0,3,2] row_mask:0xf bank_mask:0xf
	v_fmac_f32_e32 v56, v54, v54
	v_mov_b32_e32 v58, v48
	v_mul_f32_e32 v64, v9, v120
	v_add_f32_dpp v55, v56, v56 quad_perm:[2,3,0,1] row_mask:0xf bank_mask:0xf bound_ctrl:1
	v_mov_b32_e32 v56, 0
	v_fmac_f32_e32 v64, v5, v110
	v_add_f32_dpp v55, v55, v55 row_half_mirror row_mask:0xf bank_mask:0xf bound_ctrl:1
	v_fmac_f32_e32 v64, v7, v78
	v_fmac_f32_e32 v64, v105, v77
	v_add_f32_dpp v55, v55, v55 row_mirror row_mask:0xf bank_mask:0xf bound_ctrl:1
	v_mov_b32_e32 v110, 0
	s_mov_b64 s[98:99], 0x18000
	v_lshl_add_u64 v[150:151], v[44:45], 0, s[98:99]
	global_load_ushort v217, v[150:151], off offset:-1024
	global_load_ushort v221, v[150:151], off
	global_load_ushort v223, v[150:151], off offset:1024
	s_mov_b64 s[98:99], 0x19000
	v_lshl_add_u64 v[150:151], v[44:45], 0, s[98:99]
	global_load_ushort v218, v[150:151], off offset:-1024
	global_load_ushort v222, v[150:151], off offset:1024
	global_load_ushort v224, v[150:151], off
	s_mov_b64 s[98:99], 0x1a000
	v_lshl_add_u64 v[150:151], v[44:45], 0, s[98:99]
	global_load_ushort v219, v[150:151], off offset:-1024
	global_load_ushort v225, v[150:151], off
	s_mov_b64 s[98:99], 0x1b000
	v_lshl_add_u64 v[150:151], v[44:45], 0, s[98:99]
	global_load_ushort v220, v[150:151], off offset:-1024
	s_waitcnt vmcnt(10) lgkmcnt(0)
	v_lshlrev_b32_e32 v134, 16, v213
	v_mov_b32_dpp v56, v55 row_bcast:15 row_mask:0xa bank_mask:0xf
	v_add_f32_e32 v55, v55, v56
	v_mov_b32_e32 v56, 0
	v_lshlrev_b32_e32 v52, 16, v199
	v_lshlrev_b32_e32 v129, 16, v214
	v_mov_b32_dpp v56, v55 row_bcast:31 row_mask:0xc bank_mask:0xf
	v_add_f32_e32 v55, v55, v56
	v_mul_f32_e32 v149, v9, v134
	v_readlane_b32 s2, v55, 63
	v_fmac_f32_e32 v149, v5, v122
	v_fmac_f32_e32 v149, v7, v129
	v_add_f32_e32 v55, s2, v86
	v_rsq_f32_e32 v56, v55
	v_mul_f32_e32 v55, v13, v59
	v_mul_f32_e32 v59, v10, v63
	v_mul_f32_e32 v54, v54, v56
	v_mul_f32_e32 v61, 0x3e000000, v54
	v_mov_b32_e32 v54, v46
	v_mov_b32_e32 v56, v47
	v_pk_add_f32 v[46:47], v[54:55], v[56:57]
	v_mov_b32_e32 v56, v49
	v_pk_add_f32 v[54:55], v[46:47], v[58:59]
	v_lshlrev_b32_e32 v46, 16, v200
	v_mul_f32_e32 v57, v11, v46
	v_pk_add_f32 v[48:49], v[54:55], v[56:57]
	v_cvt_pk_bf16_f32 v61, v61, s0
	v_mul_f32_e32 v47, 0xbfb8aa3b, v48
	v_exp_f32_e32 v47, v47
	v_mul_f32_e32 v54, 0xbfb8aa3b, v49
	v_exp_f32_e32 v55, v54
	v_pk_mul_f32 v[58:59], v[14:15], v[62:63]
	v_add_f32_e32 v47, 1.0, v47
	v_rcp_f32_e32 v54, v47
	v_add_f32_e32 v47, 1.0, v55
	v_rcp_f32_e32 v55, v47
	v_mov_b32_e32 v62, 0
	v_pk_mul_f32 v[48:49], v[48:49], v[54:55]
	s_nop 0
	v_pk_mul_f32 v[54:55], v[48:49], v[48:49]
	s_nop 1
	v_add_f32_dpp v47, v54, v54 quad_perm:[1,0,3,2] row_mask:0xf bank_mask:0xf bound_ctrl:1
	v_mov_b32_e32 v54, 0
	s_nop 0
	v_add_f32_dpp v47, v47, v47 quad_perm:[2,3,0,1] row_mask:0xf bank_mask:0xf bound_ctrl:1
	s_nop 1
	v_add_f32_dpp v47, v47, v47 row_half_mirror row_mask:0xf bank_mask:0xf bound_ctrl:1
	s_nop 1
	v_add_f32_dpp v47, v47, v47 row_mirror row_mask:0xf bank_mask:0xf bound_ctrl:1
	s_nop 1
	v_mov_b32_dpp v54, v47 row_bcast:15 row_mask:0xa bank_mask:0xf
	v_add_f32_e32 v47, v47, v54
	v_mov_b32_e32 v54, 0
	s_nop 1
	v_mov_b32_dpp v54, v47 row_bcast:31 row_mask:0xc bank_mask:0xf
	v_add_f32_e32 v47, v47, v54
	s_nop 0
	v_readlane_b32 s2, v47, 63
	s_nop 1
	v_add_f32_e32 v47, s2, v86
	v_rsq_f32_e32 v54, v47
	s_nop 0
	v_add_f32_dpp v47, v55, v55 quad_perm:[1,0,3,2] row_mask:0xf bank_mask:0xf bound_ctrl:1
	v_mov_b32_e32 v55, 0
	s_nop 0
	v_add_f32_dpp v47, v47, v47 quad_perm:[2,3,0,1] row_mask:0xf bank_mask:0xf bound_ctrl:1
	s_nop 1
	v_add_f32_dpp v47, v47, v47 row_half_mirror row_mask:0xf bank_mask:0xf bound_ctrl:1
	s_nop 1
	v_add_f32_dpp v47, v47, v47 row_mirror row_mask:0xf bank_mask:0xf bound_ctrl:1
	s_nop 1
	v_mov_b32_dpp v55, v47 row_bcast:15 row_mask:0xa bank_mask:0xf
	v_add_f32_e32 v47, v47, v55
	v_mov_b32_e32 v55, 0
	s_nop 1
	v_mov_b32_dpp v55, v47 row_bcast:31 row_mask:0xc bank_mask:0xf
	v_add_f32_e32 v47, v47, v55
	s_nop 0
	v_readlane_b32 s2, v47, 63
	s_nop 1
	v_add_f32_e32 v47, s2, v86
	v_rsq_f32_e32 v55, v47
	v_mul_f32_e32 v47, 0xbfb8aa3b, v64
	v_exp_f32_e32 v65, v47
	v_lshlrev_b32_e32 v47, 16, v201
	v_pk_mul_f32 v[56:57], v[48:49], v[54:55]
	v_add_f32_e32 v48, 1.0, v65
	v_rcp_f32_e32 v48, v48
	v_cvt_pk_bf16_f32 v49, v56, s0
	ds_write_b16 v114, v49 offset:6144
	ds_write_b16 v116, v61 offset:2176
	v_mov_b32_e32 v49, 0
	v_mul_f32_e32 v54, v64, v48
	v_mul_f32_e32 v48, v54, v54
	v_mul_f32_e32 v61, v9, v78
	v_fmac_f32_e32 v61, v5, v120
	v_mov_b32_dpp v49, v48 quad_perm:[1,0,3,2] row_mask:0xf bank_mask:0xf
	v_fmac_f32_e32 v49, v54, v54
	v_fmac_f32_e32 v61, v7, v77
	v_fmac_f32_e32 v61, v105, v76
	v_add_f32_dpp v48, v49, v49 quad_perm:[2,3,0,1] row_mask:0xf bank_mask:0xf bound_ctrl:1
	v_mov_b32_e32 v49, 0
	v_mul_f32_e32 v65, v10, v47
	v_add_f32_dpp v48, v48, v48 row_half_mirror row_mask:0xf bank_mask:0xf bound_ctrl:1
	s_nop 1
	v_add_f32_dpp v48, v48, v48 row_mirror row_mask:0xf bank_mask:0xf bound_ctrl:1
	s_nop 1
	v_mov_b32_dpp v49, v48 row_bcast:15 row_mask:0xa bank_mask:0xf
	v_add_f32_e32 v48, v48, v49
	v_mov_b32_e32 v49, 0
	s_nop 1
	v_mov_b32_dpp v49, v48 row_bcast:31 row_mask:0xc bank_mask:0xf
	v_add_f32_e32 v48, v48, v49
	s_nop 0
	v_readlane_b32 s2, v48, 63
	s_nop 1
	v_add_f32_e32 v48, s2, v86
	v_rsq_f32_e32 v55, v48
	v_cvt_pk_bf16_f32 v48, v57, s0
	ds_write_b16 v116, v48 offset:6272
	v_pk_mul_f32 v[48:49], v[10:11], v[46:47]
	v_mul_f32_e32 v54, v54, v55
	v_mul_f32_e32 v55, 0xbfb8aa3b, v61
	v_exp_f32_e32 v55, v55
	v_mul_f32_e32 v54, 0x3e000000, v54
	v_cvt_pk_bf16_f32 v54, v54, s0
	ds_write_b16 v115, v54 offset:2304
	v_add_f32_e32 v54, 1.0, v55
	v_rcp_f32_e32 v54, v54
	v_mul_f32_e32 v55, v13, v63
	v_mul_f32_e32 v63, v12, v46
	v_mov_b32_e32 v64, v48
	v_mul_f32_e32 v61, v61, v54
	v_mul_f32_e32 v54, v61, v61
	v_lshlrev_b32_e32 v48, 16, v204
	s_nop 0
	v_mov_b32_dpp v62, v54 quad_perm:[1,0,3,2] row_mask:0xf bank_mask:0xf
	v_fmac_f32_e32 v62, v61, v61
	s_nop 1
	v_add_f32_dpp v54, v62, v62 quad_perm:[2,3,0,1] row_mask:0xf bank_mask:0xf bound_ctrl:1
	v_mov_b32_e32 v62, 0
	s_nop 0
	v_add_f32_dpp v54, v54, v54 row_half_mirror row_mask:0xf bank_mask:0xf bound_ctrl:1
	s_nop 1
	v_add_f32_dpp v54, v54, v54 row_mirror row_mask:0xf bank_mask:0xf bound_ctrl:1
	s_nop 1
	v_mov_b32_dpp v62, v54 row_bcast:15 row_mask:0xa bank_mask:0xf
	v_add_f32_e32 v69, v54, v62
	v_mov_b32_e32 v54, v58
	v_mov_b32_e32 v62, v59
	v_pk_add_f32 v[54:55], v[54:55], v[62:63]
	v_mul_f32_e32 v59, v11, v48
	v_pk_add_f32 v[54:55], v[54:55], v[64:65]
	v_mov_b32_e32 v58, v49
	v_pk_add_f32 v[54:55], v[54:55], v[58:59]
	v_mov_b32_dpp v110, v69 row_bcast:31 row_mask:0xc bank_mask:0xf
	v_mul_f32_e32 v49, 0xbfb8aa3b, v54
	v_exp_f32_e32 v49, v49
	v_mul_f32_e32 v58, 0xbfb8aa3b, v55
	v_exp_f32_e32 v59, v58
	v_add_f32_e32 v62, v69, v110
	v_add_f32_e32 v49, 1.0, v49
	v_rcp_f32_e32 v58, v49
	v_add_f32_e32 v49, 1.0, v59
	v_rcp_f32_e32 v59, v49
	v_readlane_b32 s2, v62, 63
	v_mov_b32_e32 v62, 0
	v_pk_mul_f32 v[54:55], v[54:55], v[58:59]
	s_nop 0
	v_pk_mul_f32 v[58:59], v[54:55], v[54:55]
	v_add_f32_e32 v49, s2, v86
	v_rsq_f32_e32 v49, v49
	v_add_f32_dpp v58, v58, v58 quad_perm:[1,0,3,2] row_mask:0xf bank_mask:0xf bound_ctrl:1
	v_add_f32_dpp v59, v59, v59 quad_perm:[1,0,3,2] row_mask:0xf bank_mask:0xf bound_ctrl:1
	v_mul_f32_e32 v49, v61, v49
	v_add_f32_dpp v58, v58, v58 quad_perm:[2,3,0,1] row_mask:0xf bank_mask:0xf bound_ctrl:1
	v_add_f32_dpp v59, v59, v59 quad_perm:[2,3,0,1] row_mask:0xf bank_mask:0xf bound_ctrl:1
	v_mul_f32_e32 v49, 0x3e000000, v49
	v_add_f32_dpp v58, v58, v58 row_half_mirror row_mask:0xf bank_mask:0xf bound_ctrl:1
	v_add_f32_dpp v59, v59, v59 row_half_mirror row_mask:0xf bank_mask:0xf bound_ctrl:1
	v_cvt_pk_bf16_f32 v49, v49, s0
	v_add_f32_dpp v58, v58, v58 row_mirror row_mask:0xf bank_mask:0xf bound_ctrl:1
	v_add_f32_dpp v59, v59, v59 row_mirror row_mask:0xf bank_mask:0xf bound_ctrl:1
	v_pk_mov_b32 v[60:61], v[40:41], v[52:53] op_sel:[1,0]
	v_mov_b32_dpp v62, v58 row_bcast:15 row_mask:0xa bank_mask:0xf
	v_add_f32_e32 v58, v58, v62
	v_mov_b32_e32 v62, 0
	s_nop 1
	v_mov_b32_dpp v62, v58 row_bcast:31 row_mask:0xc bank_mask:0xf
	v_add_f32_e32 v58, v58, v62
	v_mov_b32_e32 v62, 0
	v_readlane_b32 s2, v58, 63
	s_nop 0
	v_mov_b32_dpp v62, v59 row_bcast:15 row_mask:0xa bank_mask:0xf
	v_add_f32_e32 v59, v59, v62
	v_mov_b32_e32 v62, 0
	v_add_f32_e32 v58, s2, v86
	v_rsq_f32_e32 v58, v58
	v_mov_b32_dpp v62, v59 row_bcast:31 row_mask:0xc bank_mask:0xf
	v_add_f32_e32 v59, v59, v62
	s_nop 0
	v_readlane_b32 s2, v59, 63
	s_nop 1
	v_add_f32_e32 v59, s2, v86
	v_rsq_f32_e32 v59, v59
	s_mov_b32 s2, 0x18000
	v_pk_mul_f32 v[58:59], v[54:55], v[58:59]
	s_nop 0
	v_cvt_pk_bf16_f32 v54, v58, s0
	ds_write_b16 v115, v54 offset:6400
	ds_write_b16 v117, v49 offset:2432
	v_cvt_pk_bf16_f32 v49, v59, s0
	v_add_co_u32_e32 v54, vcc, s2, v44
	ds_write_b16 v117, v49 offset:6528
	s_nop 0
	v_addc_co_u32_e32 v55, vcc, 0, v45, vcc
	s_mov_b32 s2, 0x19000
	v_add_co_u32_e32 v62, vcc, s2, v44
	v_mov_b32_e32 v49, s3
	s_nop 0
	v_addc_co_u32_e32 v63, vcc, 0, v45, vcc
	v_pk_mul_f32 v[50:51], v[4:5], v[40:41] op_sel_hi:[0,1]
	v_pk_fma_f32 v[42:43], v[2:3], v[42:43], v[50:51] op_sel_hi:[0,1,1]
	v_pk_fma_f32 v[40:41], v[6:7], v[60:61], v[42:43] op_sel_hi:[0,1,1]
	v_pk_fma_f32 v[40:41], v[8:9], v[52:53], v[40:41] op_sel_hi:[0,1,1]
	v_mul_f32_e32 v42, 0xbfb8aa3b, v40
	v_mul_f32_e32 v43, 0xbfb8aa3b, v41
	v_exp_f32_e32 v42, v42
	v_exp_f32_e32 v43, v43
	s_mov_b32 s3, 0x1a000
	v_add_co_u32_e32 v64, vcc, s3, v44
	v_add_f32_e32 v42, 1.0, v42
	v_add_f32_e32 v43, 1.0, v43
	v_rcp_f32_e32 v42, v42
	v_rcp_f32_e32 v43, v43
	v_readlane_b32 s3, v102, 17
	v_lshlrev_b32_e32 v51, 16, v205
	v_lshlrev_b32_e32 v50, 16, v206
	v_pk_mul_f32 v[40:41], v[40:41], v[42:43]
	v_mov_b32_e32 v42, s4
	v_mul_f32_e32 v42, s3, v42
	v_mul_f32_e32 v110, v57, v42
	v_pk_mul_f32 v[42:43], v[4:5], v[52:53] op_sel_hi:[0,1]
	v_pk_fma_f32 v[42:43], v[2:3], v[60:61], v[42:43] op_sel_hi:[0,1,1]
	v_pk_mov_b32 v[52:53], v[52:53], v[50:51] op_sel:[1,0]
	v_readlane_b32 s2, v102, 16
	v_pk_fma_f32 v[42:43], v[6:7], v[52:53], v[42:43] op_sel_hi:[0,1,1]
	v_pk_fma_f32 v[42:43], v[8:9], v[50:51], v[42:43] op_sel_hi:[0,1,1]
	v_mul_f32_e32 v49, s2, v49
	v_mul_f32_e32 v111, v56, v49
	v_mul_f32_e32 v49, 0xbfb8aa3b, v42
	v_exp_f32_e32 v49, v49
	v_mul_f32_e32 v60, 0xbfb8aa3b, v43
	v_exp_f32_e32 v61, v60
	v_pk_mul_f32 v[40:41], v[40:41], s[2:3]
	v_add_f32_e32 v49, 1.0, v49
	v_rcp_f32_e32 v60, v49
	v_add_f32_e32 v49, 1.0, v61
	v_rcp_f32_e32 v61, v49
	v_readlane_b32 s3, v3, 18
	v_readlane_b32 s4, v3, 19
	v_readlane_b32 s2, v102, 18
	v_pk_mul_f32 v[42:43], v[42:43], v[60:61]
	v_pk_mul_f32 v[60:61], v[14:15], v[46:47]
	v_mul_f32_e32 v46, 0xbfb8aa3b, v126
	v_exp_f32_e32 v46, v46
	v_mov_b32_e32 v112, s3
	v_readlane_b32 s3, v102, 19
	v_mov_b32_e32 v49, s4
	v_add_f32_e32 v46, 1.0, v46
	v_rcp_f32_e32 v46, v46
	v_addc_co_u32_e32 v65, vcc, 0, v45, vcc
	v_mul_f32_e32 v112, s2, v112
	v_mul_f32_e32 v123, s3, v49
	v_mul_f32_e32 v46, v126, v46
	v_mul_f32_e32 v113, v58, v112
	v_mul_f32_e32 v112, v59, v123
	v_mul_f32_e32 v54, v46, v46
	v_mov_b32_e32 v55, 0
	v_pk_mul_f32 v[42:43], v[42:43], s[2:3]
	v_lshlrev_b32_e32 v49, 16, v207
	v_mov_b32_dpp v55, v54 quad_perm:[1,0,3,2] row_mask:0xf bank_mask:0xf
	v_fmac_f32_e32 v55, v46, v46
	v_pk_mul_f32 v[62:63], v[10:11], v[48:49]
	v_mul_f32_e32 v47, v13, v47
	v_add_f32_dpp v54, v55, v55 quad_perm:[2,3,0,1] row_mask:0xf bank_mask:0xf bound_ctrl:1
	v_mov_b32_e32 v55, 0
	v_readlane_b32 s3, v3, 22
	v_add_f32_dpp v54, v54, v54 row_half_mirror row_mask:0xf bank_mask:0xf bound_ctrl:1
	v_readlane_b32 s4, v3, 23
	s_mov_b64 s[98:99], 0x1a000
	v_lshl_add_u64 v[150:151], v[44:45], 0, s[98:99]
	global_load_ushort v232, v[150:151], off offset:1024
	s_mov_b64 s[98:99], 0x1b000
	v_lshl_add_u64 v[150:151], v[44:45], 0, s[98:99]
	global_load_ushort v231, v[150:151], off offset:1024
	global_load_ushort v233, v[150:151], off
	s_mov_b64 s[98:99], 0x1c000
	v_lshl_add_u64 v[150:151], v[44:45], 0, s[98:99]
	global_load_ushort v226, v[150:151], off offset:-1024
	global_load_ushort v234, v[150:151], off
	global_load_ushort v152, v[150:151], off offset:1024
	s_mov_b64 s[98:99], 0x1d000
	v_lshl_add_u64 v[150:151], v[44:45], 0, s[98:99]
	global_load_ushort v227, v[150:151], off offset:-1024
	global_load_ushort v153, v[150:151], off
	global_load_ushort v242, v[150:151], off offset:1024
	s_mov_b64 s[98:99], 0x1e000
	v_lshl_add_u64 v[150:151], v[44:45], 0, s[98:99]
	global_load_ushort v228, v[150:151], off offset:-1024
	global_load_ushort v155, v[150:151], off offset:1024
	global_load_ushort v154, v[150:151], off
	s_mov_b64 s[98:99], 0x1f000
	v_lshl_add_u64 v[150:151], v[44:45], 0, s[98:99]
	global_load_ushort v230, v[150:151], off offset:-1024
	global_load_ushort v229, v[150:151], off
	global_load_ushort v156, v[150:151], off offset:1024
	s_waitcnt vmcnt(15) lgkmcnt(0)
	v_lshlrev_b32_e32 v133, 16, v217
	v_add_f32_dpp v54, v54, v54 row_mirror row_mask:0xf bank_mask:0xf bound_ctrl:1
	v_mul_f32_e32 v69, v10, v49
	v_lshlrev_b32_e32 v128, 16, v218
	v_mov_b32_dpp v55, v54 row_bcast:15 row_mask:0xa bank_mask:0xf
	v_add_f32_e32 v54, v54, v55
	v_mov_b32_e32 v55, 0
	v_mov_b32_e32 v120, 0
	v_lshlrev_b32_e32 v127, 16, v219
	v_mov_b32_dpp v55, v54 row_bcast:31 row_mask:0xc bank_mask:0xf
	v_add_f32_e32 v54, v54, v55
	v_fmac_f32_e32 v149, v105, v133
	v_readlane_b32 s2, v54, 63
	v_lshlrev_b32_e32 v126, 16, v220
	s_nop 0
	v_add_f32_e32 v54, s2, v86
	s_mov_b32 s2, 0x1b000
	v_rsq_f32_e32 v68, v54
	v_add_co_u32_e32 v54, vcc, s2, v44
	v_readlane_b32 s2, v3, 20
	s_nop 0
	v_addc_co_u32_e32 v55, vcc, 0, v45, vcc
	v_mul_f32_e32 v64, v9, v76
	v_fmac_f32_e32 v64, v5, v77
	v_fmac_f32_e32 v64, v7, v71
	v_fmac_f32_e32 v64, v105, v122
	v_mul_f32_e32 v65, 0xbfb8aa3b, v64
	v_exp_f32_e32 v65, v65
	v_mul_f32_e32 v46, v46, v68
	v_mul_f32_e32 v46, 0x3e000000, v46
	v_cvt_pk_bf16_f32 v46, v46, s0
	ds_write_b16 v118, v46 offset:2560
	v_add_f32_e32 v46, 1.0, v65
	v_rcp_f32_e32 v46, v46
	v_mov_b32_e32 v65, 0
	v_mov_b32_e32 v77, s2
	v_mov_b32_e32 v68, v62
	v_mul_f32_e32 v46, v64, v46
	v_mul_f32_e32 v64, v46, v46
	s_nop 1
	v_mov_b32_dpp v65, v64 quad_perm:[1,0,3,2] row_mask:0xf bank_mask:0xf
	v_fmac_f32_e32 v65, v46, v46
	s_nop 1
	v_add_f32_dpp v64, v65, v65 quad_perm:[2,3,0,1] row_mask:0xf bank_mask:0xf bound_ctrl:1
	v_mov_b32_e32 v65, 0
	s_nop 0
	v_add_f32_dpp v64, v64, v64 row_half_mirror row_mask:0xf bank_mask:0xf bound_ctrl:1
	s_nop 1
	v_add_f32_dpp v64, v64, v64 row_mirror row_mask:0xf bank_mask:0xf bound_ctrl:1
	s_nop 1
	v_mov_b32_dpp v65, v64 row_bcast:15 row_mask:0xa bank_mask:0xf
	v_add_f32_e32 v64, v64, v65
	v_mov_b32_e32 v65, 0
	s_nop 1
	v_mov_b32_dpp v65, v64 row_bcast:31 row_mask:0xc bank_mask:0xf
	v_add_f32_e32 v64, v64, v65
	v_mul_f32_e32 v65, v12, v48
	v_readlane_b32 s2, v64, 63
	s_nop 1
	v_add_f32_e32 v64, s2, v86
	v_rsq_f32_e32 v64, v64
	s_nop 0
	v_mul_f32_e32 v46, v46, v64
	v_mul_f32_e32 v78, 0x3e000000, v46
	v_mov_b32_e32 v46, v60
	v_mov_b32_e32 v64, v61
	v_pk_add_f32 v[46:47], v[46:47], v[64:65]
	v_lshlrev_b32_e32 v65, 16, v208
	v_pk_add_f32 v[60:61], v[46:47], v[68:69]
	v_lshlrev_b32_e32 v64, 16, v209
	v_pk_mul_f32 v[46:47], v[4:5], v[50:51] op_sel_hi:[0,1]
	v_pk_fma_f32 v[46:47], v[2:3], v[52:53], v[46:47] op_sel_hi:[0,1,1]
	v_pk_mov_b32 v[66:67], v[50:51], v[64:65] op_sel:[1,0]
	v_mov_b32_e32 v52, v63
	v_pk_fma_f32 v[46:47], v[6:7], v[66:67], v[46:47] op_sel_hi:[0,1,1]
	v_pk_fma_f32 v[46:47], v[8:9], v[64:65], v[46:47] op_sel_hi:[0,1,1]
	v_mul_f32_e32 v50, 0xbfb8aa3b, v46
	v_exp_f32_e32 v50, v50
	v_mul_f32_e32 v51, 0xbfb8aa3b, v47
	v_exp_f32_e32 v51, v51
	v_pk_mul_f32 v[62:63], v[14:15], v[48:49]
	v_add_f32_e32 v50, 1.0, v50
	v_rcp_f32_e32 v68, v50
	v_add_f32_e32 v50, 1.0, v51
	v_rcp_f32_e32 v69, v50
	v_lshlrev_b32_e32 v50, 16, v210
	v_mul_f32_e32 v53, v11, v50
	v_pk_add_f32 v[52:53], v[60:61], v[52:53]
	v_mul_f32_e32 v73, v9, v71
	v_mul_f32_e32 v51, 0xbfb8aa3b, v52
	v_exp_f32_e32 v51, v51
	v_mul_f32_e32 v60, 0xbfb8aa3b, v53
	v_exp_f32_e32 v61, v60
	v_fmac_f32_e32 v73, v5, v76
	v_add_f32_e32 v51, 1.0, v51
	v_rcp_f32_e32 v60, v51
	v_add_f32_e32 v51, 1.0, v61
	v_rcp_f32_e32 v61, v51
	v_fmac_f32_e32 v73, v7, v122
	v_fmac_f32_e32 v73, v105, v134
	v_cvt_pk_bf16_f32 v78, v78, s0
	v_pk_mul_f32 v[52:53], v[52:53], v[60:61]
	v_mul_f32_e32 v49, v13, v49
	v_pk_mul_f32 v[60:61], v[52:53], v[52:53]
	v_pk_mul_f32 v[46:47], v[46:47], v[68:69]
	v_lshlrev_b32_e32 v69, 16, v211
	v_add_f32_dpp v51, v60, v60 quad_perm:[1,0,3,2] row_mask:0xf bank_mask:0xf bound_ctrl:1
	v_mov_b32_e32 v60, 0
	v_pk_mul_f32 v[46:47], v[46:47], s[6:7]
	v_add_f32_dpp v51, v51, v51 quad_perm:[2,3,0,1] row_mask:0xf bank_mask:0xf bound_ctrl:1
	s_nop 1
	v_add_f32_dpp v51, v51, v51 row_half_mirror row_mask:0xf bank_mask:0xf bound_ctrl:1
	s_nop 1
	v_add_f32_dpp v51, v51, v51 row_mirror row_mask:0xf bank_mask:0xf bound_ctrl:1
	s_nop 1
	v_mov_b32_dpp v60, v51 row_bcast:15 row_mask:0xa bank_mask:0xf
	v_add_f32_e32 v51, v51, v60
	v_mov_b32_e32 v60, 0
	s_nop 1
	v_mov_b32_dpp v60, v51 row_bcast:31 row_mask:0xc bank_mask:0xf
	v_add_f32_e32 v51, v51, v60
	s_nop 0
	v_readlane_b32 s2, v51, 63
	s_nop 1
	v_add_f32_e32 v51, s2, v86
	v_rsq_f32_e32 v60, v51
	s_nop 0
	v_add_f32_dpp v51, v61, v61 quad_perm:[1,0,3,2] row_mask:0xf bank_mask:0xf bound_ctrl:1
	v_mov_b32_e32 v61, 0
	s_nop 0
	v_add_f32_dpp v51, v51, v51 quad_perm:[2,3,0,1] row_mask:0xf bank_mask:0xf bound_ctrl:1
	s_nop 1
	v_add_f32_dpp v51, v51, v51 row_half_mirror row_mask:0xf bank_mask:0xf bound_ctrl:1
	s_nop 1
	v_add_f32_dpp v51, v51, v51 row_mirror row_mask:0xf bank_mask:0xf bound_ctrl:1
	s_nop 1
	v_mov_b32_dpp v61, v51 row_bcast:15 row_mask:0xa bank_mask:0xf
	v_add_f32_e32 v51, v51, v61
	v_mov_b32_e32 v61, 0
	s_nop 1
	v_mov_b32_dpp v61, v51 row_bcast:31 row_mask:0xc bank_mask:0xf
	v_add_f32_e32 v51, v51, v61
	s_nop 0
	v_readlane_b32 s2, v51, 63
	s_nop 1
	v_add_f32_e32 v51, s2, v86
	v_rsq_f32_e32 v61, v51
	v_mul_f32_e32 v51, 0xbfb8aa3b, v73
	v_exp_f32_e32 v76, v51
	v_lshlrev_b32_e32 v51, 16, v215
	v_pk_mul_f32 v[60:61], v[52:53], v[60:61]
	v_mov_b32_e32 v53, 0
	v_add_f32_e32 v48, 1.0, v76
	v_rcp_f32_e32 v48, v48
	v_cvt_pk_bf16_f32 v52, v60, s0
	ds_write_b16 v118, v52 offset:6656
	ds_write_b16 v119, v78 offset:2688
	v_mul_f32_e32 v79, v10, v51
	v_mul_f32_e32 v48, v73, v48
	v_mul_f32_e32 v52, v48, v48
	v_mul_f32_e32 v73, v12, v50
	s_nop 0
	v_mov_b32_dpp v53, v52 quad_perm:[1,0,3,2] row_mask:0xf bank_mask:0xf
	v_fmac_f32_e32 v53, v48, v48
	s_nop 1
	v_add_f32_dpp v52, v53, v53 quad_perm:[2,3,0,1] row_mask:0xf bank_mask:0xf bound_ctrl:1
	v_mov_b32_e32 v53, 0
	s_nop 0
	v_add_f32_dpp v52, v52, v52 row_half_mirror row_mask:0xf bank_mask:0xf bound_ctrl:1
	s_nop 1
	v_add_f32_dpp v52, v52, v52 row_mirror row_mask:0xf bank_mask:0xf bound_ctrl:1
	s_nop 1
	v_mov_b32_dpp v53, v52 row_bcast:15 row_mask:0xa bank_mask:0xf
	v_add_f32_e32 v52, v52, v53
	v_mov_b32_e32 v53, 0
	s_nop 1
	v_mov_b32_dpp v53, v52 row_bcast:31 row_mask:0xc bank_mask:0xf
	v_add_f32_e32 v52, v52, v53
	s_nop 0
	v_readlane_b32 s2, v52, 63
	s_nop 1
	v_add_f32_e32 v52, s2, v86
	v_rsq_f32_e32 v72, v52
	v_cvt_pk_bf16_f32 v52, v61, s0
	ds_write_b16 v119, v52 offset:6784
	v_pk_mul_f32 v[52:53], v[10:11], v[50:51]
	v_mul_f32_e32 v48, v48, v72
	v_mul_f32_e32 v72, v9, v122
	v_fmac_f32_e32 v72, v5, v71
	v_fmac_f32_e32 v72, v7, v134
	v_fmac_f32_e32 v72, v105, v129
	v_mul_f32_e32 v71, 0xbfb8aa3b, v72
	v_exp_f32_e32 v71, v71
	v_mul_f32_e32 v48, 0x3e000000, v48
	v_cvt_pk_bf16_f32 v48, v48, s0
	ds_write_b16 v124, v48 offset:2816
	v_add_f32_e32 v48, 1.0, v71
	v_rcp_f32_e32 v48, v48
	v_mov_b32_e32 v78, v52
	v_lshlrev_b32_e32 v52, 16, v216
	v_mul_f32_e32 v71, v72, v48
	v_mul_f32_e32 v48, v71, v71
	v_mov_b32_e32 v72, 0
	s_nop 1
	v_mov_b32_dpp v72, v48 quad_perm:[1,0,3,2] row_mask:0xf bank_mask:0xf
	v_fmac_f32_e32 v72, v71, v71
	s_nop 1
	v_add_f32_dpp v48, v72, v72 quad_perm:[2,3,0,1] row_mask:0xf bank_mask:0xf bound_ctrl:1
	v_mov_b32_e32 v72, 0
	s_nop 0
	v_add_f32_dpp v48, v48, v48 row_half_mirror row_mask:0xf bank_mask:0xf bound_ctrl:1
	s_nop 1
	v_add_f32_dpp v48, v48, v48 row_mirror row_mask:0xf bank_mask:0xf bound_ctrl:1
	s_nop 1
	v_mov_b32_dpp v72, v48 row_bcast:15 row_mask:0xa bank_mask:0xf
	v_add_f32_e32 v76, v48, v72
	v_mov_b32_e32 v48, v62
	v_mov_b32_e32 v72, v63
	v_pk_add_f32 v[48:49], v[48:49], v[72:73]
	v_mul_f32_e32 v63, v11, v52
	v_pk_add_f32 v[48:49], v[48:49], v[78:79]
	v_mov_b32_e32 v62, v53
	v_pk_add_f32 v[48:49], v[48:49], v[62:63]
	v_mov_b32_dpp v120, v76 row_bcast:31 row_mask:0xc bank_mask:0xf
	v_mul_f32_e32 v53, 0xbfb8aa3b, v48
	v_exp_f32_e32 v53, v53
	v_mul_f32_e32 v62, 0xbfb8aa3b, v49
	v_exp_f32_e32 v63, v62
	v_add_f32_e32 v70, v76, v120
	v_add_f32_e32 v53, 1.0, v53
	v_rcp_f32_e32 v62, v53
	v_add_f32_e32 v53, 1.0, v63
	v_rcp_f32_e32 v63, v53
	v_readlane_b32 s2, v70, 63
	v_mov_b32_e32 v70, 0
	v_pk_mul_f32 v[48:49], v[48:49], v[62:63]
	s_nop 0
	v_pk_mul_f32 v[62:63], v[48:49], v[48:49]
	v_add_f32_e32 v53, s2, v86
	v_rsq_f32_e32 v53, v53
	v_add_f32_dpp v62, v62, v62 quad_perm:[1,0,3,2] row_mask:0xf bank_mask:0xf bound_ctrl:1
	v_add_f32_dpp v63, v63, v63 quad_perm:[1,0,3,2] row_mask:0xf bank_mask:0xf bound_ctrl:1
	v_mul_f32_e32 v53, v71, v53
	v_add_f32_dpp v62, v62, v62 quad_perm:[2,3,0,1] row_mask:0xf bank_mask:0xf bound_ctrl:1
	v_add_f32_dpp v63, v63, v63 quad_perm:[2,3,0,1] row_mask:0xf bank_mask:0xf bound_ctrl:1
	v_mul_f32_e32 v53, 0x3e000000, v53
	v_add_f32_dpp v62, v62, v62 row_half_mirror row_mask:0xf bank_mask:0xf bound_ctrl:1
	v_add_f32_dpp v63, v63, v63 row_half_mirror row_mask:0xf bank_mask:0xf bound_ctrl:1
	v_cvt_pk_bf16_f32 v53, v53, s0
	v_add_f32_dpp v62, v62, v62 row_mirror row_mask:0xf bank_mask:0xf bound_ctrl:1
	v_add_f32_dpp v63, v63, v63 row_mirror row_mask:0xf bank_mask:0xf bound_ctrl:1
	s_nop 0
	v_mov_b32_dpp v70, v62 row_bcast:15 row_mask:0xa bank_mask:0xf
	v_add_f32_e32 v62, v62, v70
	v_mov_b32_e32 v70, 0
	s_nop 1
	v_mov_b32_dpp v70, v62 row_bcast:31 row_mask:0xc bank_mask:0xf
	v_add_f32_e32 v62, v62, v70
	v_mov_b32_e32 v70, 0
	v_readlane_b32 s2, v62, 63
	s_nop 0
	v_mov_b32_dpp v70, v63 row_bcast:15 row_mask:0xa bank_mask:0xf
	v_add_f32_e32 v63, v63, v70
	v_mov_b32_e32 v70, 0
	v_add_f32_e32 v62, s2, v86
	v_rsq_f32_e32 v62, v62
	v_mov_b32_dpp v70, v63 row_bcast:31 row_mask:0xc bank_mask:0xf
	v_add_f32_e32 v63, v63, v70
	s_nop 0
	v_readlane_b32 s2, v63, 63
	s_nop 1
	v_add_f32_e32 v63, s2, v86
	v_rsq_f32_e32 v63, v63
	s_mov_b32 s2, 0x1c000
	v_add_co_u32_e32 v70, vcc, s2, v44
	v_pk_mul_f32 v[62:63], v[48:49], v[62:63]
	s_nop 0
	v_addc_co_u32_e32 v71, vcc, 0, v45, vcc
	v_cvt_pk_bf16_f32 v48, v62, s0
	ds_write_b16 v124, v48 offset:6912
	ds_write_b16 v125, v53 offset:2944
	v_cvt_pk_bf16_f32 v48, v63, s0
	ds_write_b16 v125, v48 offset:7040
	s_mov_b32 s2, 0x1d000
	v_add_co_u32_e32 v54, vcc, s2, v44
	v_readlane_b32 s2, v3, 21
	s_nop 0
	v_addc_co_u32_e32 v55, vcc, 0, v45, vcc
	v_mov_b32_e32 v48, s2
	s_mov_b32 s2, 0x1e000
	v_add_co_u32_e32 v72, vcc, s2, v44
	s_mov_b32 s2, 0x1f000
	s_nop 0
	v_addc_co_u32_e32 v73, vcc, 0, v45, vcc
	v_mul_f32_e32 v68, s7, v48
	v_add_co_u32_e32 v48, vcc, s2, v44
	s_nop 0
	v_addc_co_u32_e32 v49, vcc, 0, v45, vcc
	v_mul_f32_e32 v120, v61, v68
	v_lshlrev_b32_e32 v68, 16, v212
	v_pk_mul_f32 v[48:49], v[4:5], v[64:65] op_sel_hi:[0,1]
	v_pk_fma_f32 v[48:49], v[2:3], v[66:67], v[48:49] op_sel_hi:[0,1,1]
	v_pk_mov_b32 v[64:65], v[64:65], v[68:69] op_sel:[1,0]
	v_mul_f32_e32 v53, s6, v77
	v_pk_fma_f32 v[48:49], v[6:7], v[64:65], v[48:49] op_sel_hi:[0,1,1]
	v_pk_fma_f32 v[48:49], v[8:9], v[68:69], v[48:49] op_sel_hi:[0,1,1]
	v_mul_f32_e32 v121, v60, v53
	v_mul_f32_e32 v53, 0xbfb8aa3b, v48
	v_exp_f32_e32 v53, v53
	v_mul_f32_e32 v66, 0xbfb8aa3b, v49
	v_exp_f32_e32 v67, v66
	v_readlane_b32 s2, v102, 22
	v_add_f32_e32 v53, 1.0, v53
	v_rcp_f32_e32 v66, v53
	v_add_f32_e32 v53, 1.0, v67
	v_rcp_f32_e32 v67, v53
	v_mov_b32_e32 v74, s3
	v_readlane_b32 s3, v102, 23
	v_mov_b32_e32 v53, s4
	v_pk_mul_f32 v[48:49], v[48:49], v[66:67]
	v_mul_f32_e32 v139, s2, v74
	v_pk_mul_f32 v[48:49], v[48:49], s[2:3]
	v_mul_f32_e32 v140, s3, v53
	s_mov_b64 s[2:3], 0x1c000
	v_lshl_add_u64 v[76:77], v[44:45], 0, s[2:3]
	s_mov_b64 s[2:3], 0x1d000
	v_lshl_add_u64 v[78:79], v[44:45], 0, s[2:3]
	s_mov_b64 s[2:3], 0x1e000
	v_lshl_add_u64 v[66:67], v[44:45], 0, s[2:3]
	s_mov_b64 s[2:3], 0x1f000
	v_lshl_add_u64 v[74:75], v[44:45], 0, s[2:3]
	v_pk_mul_f32 v[44:45], v[14:15], v[50:51]
	v_mul_f32_e32 v50, 0xbfb8aa3b, v149
	v_exp_f32_e32 v50, v50
	v_lshlrev_b32_e32 v53, 16, v221
	v_mul_f32_e32 v123, v62, v139
	v_mul_f32_e32 v122, v63, v140
	v_add_f32_e32 v50, 1.0, v50
	v_rcp_f32_e32 v50, v50
	s_nop 0
	s_nop 0
	v_mov_b32_e32 v66, 0
	v_mul_f32_e32 v50, v149, v50
	v_mul_f32_e32 v55, v50, v50
	v_readlane_b32 s3, v3, 24
	v_mul_f32_e32 v51, v13, v51
	v_mov_b32_dpp v66, v55 quad_perm:[1,0,3,2] row_mask:0xf bank_mask:0xf
	v_fmac_f32_e32 v66, v50, v50
	v_pk_mul_f32 v[70:71], v[10:11], v[52:53]
	v_mul_f32_e32 v73, v10, v53
	v_add_f32_dpp v55, v66, v66 quad_perm:[2,3,0,1] row_mask:0xf bank_mask:0xf bound_ctrl:1
	v_mov_b32_e32 v66, 0
	v_mov_b32_e32 v72, v70
	v_add_f32_dpp v55, v55, v55 row_half_mirror row_mask:0xf bank_mask:0xf bound_ctrl:1
	v_readlane_b32 s4, v3, 25
	v_mul_f32_e32 v77, v9, v133
	v_add_f32_dpp v55, v55, v55 row_mirror row_mask:0xf bank_mask:0xf bound_ctrl:1
	v_fmac_f32_e32 v77, v5, v129
	v_fmac_f32_e32 v77, v7, v128
	v_mov_b32_dpp v66, v55 row_bcast:15 row_mask:0xa bank_mask:0xf
	v_add_f32_e32 v55, v55, v66
	v_mov_b32_e32 v66, 0
	v_fmac_f32_e32 v77, v105, v127
	s_waitcnt vmcnt(0) lgkmcnt(0)
	v_lshlrev_b32_e32 v54, 16, v226
	v_mov_b32_dpp v66, v55 row_bcast:31 row_mask:0xc bank_mask:0xf
	v_add_f32_e32 v55, v55, v66
	v_lshlrev_b32_e32 v142, 16, v227
	v_readlane_b32 s2, v55, 63
	v_cmp_gt_u32_e32 vcc, 32, v22
	v_lshlrev_b32_e32 v141, 16, v228
	v_add_f32_e32 v55, s2, v86
	v_rsq_f32_e32 v66, v55
	v_readlane_b32 s2, v102, 24
	v_lshlrev_b32_e32 v55, 16, v229
	v_lshlrev_b32_e32 v143, 16, v230
	v_mul_f32_e32 v50, v50, v66
	v_mul_f32_e32 v66, v9, v129
	v_fmac_f32_e32 v66, v5, v134
	v_fmac_f32_e32 v66, v7, v133
	v_fmac_f32_e32 v66, v105, v128
	v_mul_f32_e32 v67, 0xbfb8aa3b, v66
	v_exp_f32_e32 v67, v67
	v_mul_f32_e32 v50, 0x3e000000, v50
	v_cvt_pk_bf16_f32 v50, v50, s0
	ds_write_b16 v114, v50 offset:3072
	v_add_f32_e32 v50, 1.0, v67
	v_rcp_f32_e32 v50, v50
	v_mov_b32_e32 v67, s3
	v_mul_f32_e32 v74, s2, v67
	v_mov_b32_e32 v67, 0
	v_mul_f32_e32 v50, v66, v50
	v_mul_f32_e32 v66, v50, v50
	s_nop 1
	v_mov_b32_dpp v67, v66 quad_perm:[1,0,3,2] row_mask:0xf bank_mask:0xf
	v_fmac_f32_e32 v67, v50, v50
	s_nop 1
	v_add_f32_dpp v66, v67, v67 quad_perm:[2,3,0,1] row_mask:0xf bank_mask:0xf bound_ctrl:1
	v_mov_b32_e32 v67, 0
	s_nop 0
	v_add_f32_dpp v66, v66, v66 row_half_mirror row_mask:0xf bank_mask:0xf bound_ctrl:1
	s_nop 1
	v_add_f32_dpp v66, v66, v66 row_mirror row_mask:0xf bank_mask:0xf bound_ctrl:1
	s_nop 1
	v_mov_b32_dpp v67, v66 row_bcast:15 row_mask:0xa bank_mask:0xf
	v_add_f32_e32 v66, v66, v67
	v_mov_b32_e32 v67, 0
	s_nop 1
	v_mov_b32_dpp v67, v66 row_bcast:31 row_mask:0xc bank_mask:0xf
	v_add_f32_e32 v66, v66, v67
	v_mul_f32_e32 v67, v12, v52
	v_readlane_b32 s3, v66, 63
	s_nop 1
	v_add_f32_e32 v66, s3, v86
	v_rsq_f32_e32 v66, v66
	v_readlane_b32 s3, v102, 25
	v_mul_f32_e32 v50, v50, v66
	v_mul_f32_e32 v75, 0x3e000000, v50
	v_mov_b32_e32 v50, v44
	v_mov_b32_e32 v66, v45
	v_pk_add_f32 v[44:45], v[50:51], v[66:67]
	v_lshlrev_b32_e32 v51, 16, v222
	v_lshlrev_b32_e32 v50, 16, v223
	v_pk_mul_f32 v[66:67], v[4:5], v[68:69] op_sel_hi:[0,1]
	v_pk_fma_f32 v[64:65], v[2:3], v[64:65], v[66:67] op_sel_hi:[0,1,1]
	v_pk_mov_b32 v[66:67], v[68:69], v[50:51] op_sel:[1,0]
	v_pk_add_f32 v[72:73], v[44:45], v[72:73]
	v_pk_fma_f32 v[64:65], v[6:7], v[66:67], v[64:65] op_sel_hi:[0,1,1]
	v_pk_fma_f32 v[64:65], v[8:9], v[50:51], v[64:65] op_sel_hi:[0,1,1]
	v_mul_f32_e32 v68, 0xbfb8aa3b, v64
	v_mul_f32_e32 v69, 0xbfb8aa3b, v65
	v_exp_f32_e32 v68, v68
	v_exp_f32_e32 v69, v69
	v_cvt_pk_bf16_f32 v75, v75, s0
	v_add_f32_e32 v44, 1.0, v68
	v_add_f32_e32 v45, 1.0, v69
	v_rcp_f32_e32 v44, v44
	v_rcp_f32_e32 v45, v45
	v_lshlrev_b32_e32 v68, 16, v224
	v_pk_mul_f32 v[44:45], v[64:65], v[44:45]
	v_mov_b32_e32 v64, s4
	v_mul_f32_e32 v76, s3, v64
	v_mul_f32_e32 v65, v11, v68
	v_mov_b32_e32 v64, v71
	v_pk_add_f32 v[64:65], v[72:73], v[64:65]
	v_pk_mul_f32 v[72:73], v[14:15], v[52:53]
	v_mul_f32_e32 v69, 0xbfb8aa3b, v64
	v_exp_f32_e32 v69, v69
	v_mul_f32_e32 v70, 0xbfb8aa3b, v65
	v_exp_f32_e32 v71, v70
	v_pk_mul_f32 v[44:45], v[44:45], s[2:3]
	v_add_f32_e32 v69, 1.0, v69
	v_rcp_f32_e32 v70, v69
	v_add_f32_e32 v69, 1.0, v71
	v_rcp_f32_e32 v71, v69
	v_mov_b32_e32 v69, 0
	v_readlane_b32 s3, v3, 26
	v_mul_f32_e32 v53, v13, v53
	v_pk_mul_f32 v[64:65], v[64:65], v[70:71]
	v_readlane_b32 s4, v3, 27
	v_pk_mul_f32 v[70:71], v[64:65], v[64:65]
	s_nop 1
	v_add_f32_dpp v52, v70, v70 quad_perm:[1,0,3,2] row_mask:0xf bank_mask:0xf bound_ctrl:1
	s_nop 1
	v_add_f32_dpp v52, v52, v52 quad_perm:[2,3,0,1] row_mask:0xf bank_mask:0xf bound_ctrl:1
	s_nop 1
	v_add_f32_dpp v52, v52, v52 row_half_mirror row_mask:0xf bank_mask:0xf bound_ctrl:1
	s_nop 1
	v_add_f32_dpp v52, v52, v52 row_mirror row_mask:0xf bank_mask:0xf bound_ctrl:1
	s_nop 1
	v_mov_b32_dpp v69, v52 row_bcast:15 row_mask:0xa bank_mask:0xf
	v_add_f32_e32 v52, v52, v69
	v_mov_b32_e32 v69, 0
	s_nop 1
	v_mov_b32_dpp v69, v52 row_bcast:31 row_mask:0xc bank_mask:0xf
	v_add_f32_e32 v52, v52, v69
	v_mov_b32_e32 v69, 0
	v_readlane_b32 s2, v52, 63
	s_nop 1
	v_add_f32_e32 v52, s2, v86
	v_rsq_f32_e32 v70, v52
	s_nop 0
	v_add_f32_dpp v52, v71, v71 quad_perm:[1,0,3,2] row_mask:0xf bank_mask:0xf bound_ctrl:1
	s_nop 1
	v_add_f32_dpp v52, v52, v52 quad_perm:[2,3,0,1] row_mask:0xf bank_mask:0xf bound_ctrl:1
	s_nop 1
	v_add_f32_dpp v52, v52, v52 row_half_mirror row_mask:0xf bank_mask:0xf bound_ctrl:1
	s_nop 1
	v_add_f32_dpp v52, v52, v52 row_mirror row_mask:0xf bank_mask:0xf bound_ctrl:1
	s_nop 1
	v_mov_b32_dpp v69, v52 row_bcast:15 row_mask:0xa bank_mask:0xf
	v_add_f32_e32 v52, v52, v69
	v_mov_b32_e32 v69, 0
	s_nop 1
	v_mov_b32_dpp v69, v52 row_bcast:31 row_mask:0xc bank_mask:0xf
	v_add_f32_e32 v52, v52, v69
	v_lshlrev_b32_e32 v69, 16, v225
	v_readlane_b32 s2, v52, 63
	v_mul_f32_e32 v135, v10, v69
	v_mul_f32_e32 v13, v13, v69
	v_add_f32_e32 v52, s2, v86
	v_rsq_f32_e32 v71, v52
	v_mul_f32_e32 v52, 0xbfb8aa3b, v77
	v_exp_f32_e32 v52, v52
	v_pk_mul_f32 v[64:65], v[64:65], v[70:71]
	s_nop 0
	v_cvt_pk_bf16_f32 v70, v64, s0
	v_add_f32_e32 v52, 1.0, v52
	v_rcp_f32_e32 v52, v52
	ds_write_b16 v114, v70 offset:7168
	ds_write_b16 v116, v75 offset:3200
	v_mov_b32_e32 v75, 0
	v_mul_f32_e32 v52, v77, v52
	v_mul_f32_e32 v71, v52, v52
	v_cvt_pk_bf16_f32 v70, v65, s0
	ds_write_b16 v116, v70 offset:7296
	v_mov_b32_dpp v75, v71 quad_perm:[1,0,3,2] row_mask:0xf bank_mask:0xf
	v_fmac_f32_e32 v75, v52, v52
	v_mul_f32_e32 v74, v64, v74
	s_nop 0
	v_add_f32_dpp v71, v75, v75 quad_perm:[2,3,0,1] row_mask:0xf bank_mask:0xf bound_ctrl:1
	v_mov_b32_e32 v75, 0
	s_nop 0
	v_add_f32_dpp v71, v71, v71 row_half_mirror row_mask:0xf bank_mask:0xf bound_ctrl:1
	s_nop 1
	v_add_f32_dpp v71, v71, v71 row_mirror row_mask:0xf bank_mask:0xf bound_ctrl:1
	s_nop 1
	v_mov_b32_dpp v75, v71 row_bcast:15 row_mask:0xa bank_mask:0xf
	v_add_f32_e32 v71, v71, v75
	v_mov_b32_e32 v75, 0
	s_nop 1
	v_mov_b32_dpp v75, v71 row_bcast:31 row_mask:0xc bank_mask:0xf
	v_add_f32_e32 v71, v71, v75
	v_mul_f32_e32 v75, v65, v76
	v_readlane_b32 s2, v71, 63
	v_mul_f32_e32 v76, v9, v128
	v_fmac_f32_e32 v76, v5, v133
	v_add_f32_e32 v71, s2, v86
	v_rsq_f32_e32 v77, v71
	v_fmac_f32_e32 v76, v7, v127
	v_fmac_f32_e32 v76, v105, v126
	v_readlane_b32 s2, v102, 26
	v_mul_f32_e32 v52, v52, v77
	v_mul_f32_e32 v77, 0xbfb8aa3b, v76
	v_exp_f32_e32 v77, v77
	v_mul_f32_e32 v52, 0x3e000000, v52
	v_cvt_pk_bf16_f32 v52, v52, s0
	ds_write_b16 v115, v52 offset:3328
	v_add_f32_e32 v52, 1.0, v77
	v_rcp_f32_e32 v52, v52
	v_mov_b32_e32 v77, s3
	v_mul_f32_e32 v114, s2, v77
	v_mov_b32_e32 v77, 0
	v_mul_f32_e32 v52, v76, v52
	v_mul_f32_e32 v76, v52, v52
	v_pk_mul_f32 v[70:71], v[10:11], v[68:69]
	s_nop 0
	v_mov_b32_dpp v77, v76 quad_perm:[1,0,3,2] row_mask:0xf bank_mask:0xf
	v_fmac_f32_e32 v77, v52, v52
	v_mov_b32_e32 v134, v70
	s_nop 0
	v_add_f32_dpp v76, v77, v77 quad_perm:[2,3,0,1] row_mask:0xf bank_mask:0xf bound_ctrl:1
	v_mov_b32_e32 v77, 0
	s_nop 0
	v_add_f32_dpp v76, v76, v76 row_half_mirror row_mask:0xf bank_mask:0xf bound_ctrl:1
	s_nop 1
	v_add_f32_dpp v76, v76, v76 row_mirror row_mask:0xf bank_mask:0xf bound_ctrl:1
	s_nop 1
	v_mov_b32_dpp v77, v76 row_bcast:15 row_mask:0xa bank_mask:0xf
	v_add_f32_e32 v76, v76, v77
	v_mov_b32_e32 v77, 0
	s_nop 1
	v_mov_b32_dpp v77, v76 row_bcast:31 row_mask:0xc bank_mask:0xf
	v_add_f32_e32 v76, v76, v77
	v_mul_f32_e32 v77, v12, v68
	v_readlane_b32 s3, v76, 63
	s_nop 1
	v_add_f32_e32 v76, s3, v86
	v_rsq_f32_e32 v76, v76
	v_readlane_b32 s3, v102, 27
	v_mul_f32_e32 v52, v52, v76
	v_mul_f32_e32 v116, 0x3e000000, v52
	v_mov_b32_e32 v52, v72
	v_mov_b32_e32 v76, v73
	v_pk_add_f32 v[76:77], v[52:53], v[76:77]
	v_lshlrev_b32_e32 v53, 16, v231
	v_lshlrev_b32_e32 v52, 16, v232
	v_pk_mul_f32 v[72:73], v[4:5], v[50:51] op_sel_hi:[0,1]
	v_pk_fma_f32 v[66:67], v[2:3], v[66:67], v[72:73] op_sel_hi:[0,1,1]
	v_pk_mov_b32 v[72:73], v[50:51], v[52:53] op_sel:[1,0]
	v_mul_f32_e32 v131, v9, v127
	v_pk_fma_f32 v[50:51], v[6:7], v[72:73], v[66:67] op_sel_hi:[0,1,1]
	v_pk_fma_f32 v[50:51], v[8:9], v[52:53], v[50:51] op_sel_hi:[0,1,1]
	v_mul_f32_e32 v66, 0xbfb8aa3b, v50
	v_exp_f32_e32 v70, v66
	v_mul_f32_e32 v66, 0xbfb8aa3b, v51
	v_exp_f32_e32 v129, v66
	v_pk_add_f32 v[66:67], v[76:77], v[134:135]
	v_add_f32_e32 v70, 1.0, v70
	v_rcp_f32_e32 v76, v70
	v_add_f32_e32 v70, 1.0, v129
	v_rcp_f32_e32 v77, v70
	v_lshlrev_b32_e32 v70, 16, v233
	v_fmac_f32_e32 v131, v5, v128
	v_fmac_f32_e32 v131, v7, v126
	v_pk_mul_f32 v[50:51], v[50:51], v[76:77]
	v_mul_f32_e32 v77, v11, v70
	v_mov_b32_e32 v76, v71
	v_pk_add_f32 v[66:67], v[66:67], v[76:77]
	v_pk_mul_f32 v[50:51], v[50:51], s[2:3]
	v_mul_f32_e32 v71, 0xbfb8aa3b, v66
	v_exp_f32_e32 v71, v71
	v_mul_f32_e32 v76, 0xbfb8aa3b, v67
	v_exp_f32_e32 v77, v76
	v_mov_b32_e32 v129, s4
	v_add_f32_e32 v71, 1.0, v71
	v_rcp_f32_e32 v76, v71
	v_add_f32_e32 v71, 1.0, v77
	v_rcp_f32_e32 v77, v71
	v_fmac_f32_e32 v131, v105, v54
	v_mul_f32_e32 v130, s3, v129
	v_pk_mul_f32 v[128:129], v[14:15], v[68:69]
	v_pk_mul_f32 v[66:67], v[66:67], v[76:77]
	v_mul_f32_e32 v68, 0xbfb8aa3b, v131
	v_pk_mul_f32 v[76:77], v[66:67], v[66:67]
	v_exp_f32_e32 v68, v68
	v_cvt_pk_bf16_f32 v116, v116, s0
	v_add_f32_dpp v71, v76, v76 quad_perm:[1,0,3,2] row_mask:0xf bank_mask:0xf bound_ctrl:1
	v_mov_b32_e32 v76, 0
	v_add_f32_e32 v68, 1.0, v68
	v_add_f32_dpp v71, v71, v71 quad_perm:[2,3,0,1] row_mask:0xf bank_mask:0xf bound_ctrl:1
	v_rcp_f32_e32 v68, v68
	v_readlane_b32 s3, v3, 28
	v_add_f32_dpp v71, v71, v71 row_half_mirror row_mask:0xf bank_mask:0xf bound_ctrl:1
	v_mul_f32_e32 v69, v12, v70
	v_mul_f32_e32 v68, v131, v68
	v_add_f32_dpp v71, v71, v71 row_mirror row_mask:0xf bank_mask:0xf bound_ctrl:1
	v_readlane_b32 s4, v3, 29
	s_nop 0
	v_mov_b32_dpp v76, v71 row_bcast:15 row_mask:0xa bank_mask:0xf
	v_add_f32_e32 v71, v71, v76
	v_mov_b32_e32 v76, 0
	s_nop 1
	v_mov_b32_dpp v76, v71 row_bcast:31 row_mask:0xc bank_mask:0xf
	v_add_f32_e32 v71, v71, v76
	s_nop 0
	v_readlane_b32 s2, v71, 63
	s_nop 1
	v_add_f32_e32 v71, s2, v86
	v_rsq_f32_e32 v76, v71
	s_nop 0
	v_add_f32_dpp v71, v77, v77 quad_perm:[1,0,3,2] row_mask:0xf bank_mask:0xf bound_ctrl:1
	v_mov_b32_e32 v77, 0
	s_nop 0
	v_add_f32_dpp v71, v71, v71 quad_perm:[2,3,0,1] row_mask:0xf bank_mask:0xf bound_ctrl:1
	s_nop 1
	v_add_f32_dpp v71, v71, v71 row_half_mirror row_mask:0xf bank_mask:0xf bound_ctrl:1
	s_nop 1
	v_add_f32_dpp v71, v71, v71 row_mirror row_mask:0xf bank_mask:0xf bound_ctrl:1
	s_nop 1
	v_mov_b32_dpp v77, v71 row_bcast:15 row_mask:0xa bank_mask:0xf
	v_add_f32_e32 v71, v71, v77
	v_mov_b32_e32 v77, 0
	s_nop 1
	v_mov_b32_dpp v77, v71 row_bcast:31 row_mask:0xc bank_mask:0xf
	v_add_f32_e32 v71, v71, v77
	s_nop 0
	v_readlane_b32 s2, v71, 63
	s_nop 1
	v_add_f32_e32 v71, s2, v86
	v_rsq_f32_e32 v77, v71
	v_lshlrev_b32_e32 v71, 16, v234
	v_pk_mul_f32 v[66:67], v[66:67], v[76:77]
	s_nop 0
	v_cvt_pk_bf16_f32 v76, v66, s0
	v_cvt_pk_bf16_f32 v77, v67, s0
	ds_write_b16 v115, v76 offset:7424
	v_mul_f32_e32 v76, v66, v114
	ds_write_b16 v117, v77 offset:7552
	v_mul_f32_e32 v77, v68, v68
	v_mov_b32_e32 v114, 0
	ds_write_b16 v117, v116 offset:3456
	s_nop 0
	v_mov_b32_dpp v114, v77 quad_perm:[1,0,3,2] row_mask:0xf bank_mask:0xf
	v_fmac_f32_e32 v114, v68, v68
	s_nop 1
	v_add_f32_dpp v77, v114, v114 quad_perm:[2,3,0,1] row_mask:0xf bank_mask:0xf bound_ctrl:1
	v_mov_b32_e32 v114, 0
	s_nop 0
	v_add_f32_dpp v77, v77, v77 row_half_mirror row_mask:0xf bank_mask:0xf bound_ctrl:1
	s_nop 1
	v_add_f32_dpp v77, v77, v77 row_mirror row_mask:0xf bank_mask:0xf bound_ctrl:1
	s_nop 1
	v_mov_b32_dpp v114, v77 row_bcast:15 row_mask:0xa bank_mask:0xf
	v_add_f32_e32 v77, v77, v114
	v_mov_b32_e32 v114, 0
	s_nop 1
	v_mov_b32_dpp v114, v77 row_bcast:31 row_mask:0xc bank_mask:0xf
	v_add_f32_e32 v77, v77, v114
	v_pk_mul_f32 v[114:115], v[10:11], v[70:71]
	v_readlane_b32 s2, v77, 63
	s_nop 1
	v_add_f32_e32 v77, s2, v86
	v_rsq_f32_e32 v116, v77
	v_readlane_b32 s2, v102, 28
	v_mul_f32_e32 v77, v67, v130
	v_mul_f32_e32 v68, v68, v116
	v_mul_f32_e32 v116, v9, v126
	v_fmac_f32_e32 v116, v5, v127
	v_fmac_f32_e32 v116, v7, v54
	v_fmac_f32_e32 v116, v105, v142
	v_mul_f32_e32 v117, 0xbfb8aa3b, v116
	v_exp_f32_e32 v117, v117
	v_mul_f32_e32 v68, 0x3e000000, v68
	v_cvt_pk_bf16_f32 v68, v68, s0
	ds_write_b16 v118, v68 offset:3584
	v_add_f32_e32 v68, 1.0, v117
	v_rcp_f32_e32 v68, v68
	v_mov_b32_e32 v117, s3
	v_mul_f32_e32 v130, s2, v117
	v_mov_b32_e32 v117, 0
	v_mul_f32_e32 v68, v116, v68
	v_mul_f32_e32 v116, v68, v68
	s_nop 1
	v_mov_b32_dpp v117, v116 quad_perm:[1,0,3,2] row_mask:0xf bank_mask:0xf
	v_fmac_f32_e32 v117, v68, v68
	s_nop 1
	v_add_f32_dpp v116, v117, v117 quad_perm:[2,3,0,1] row_mask:0xf bank_mask:0xf bound_ctrl:1
	v_mov_b32_e32 v117, 0
	s_nop 0
	v_add_f32_dpp v116, v116, v116 row_half_mirror row_mask:0xf bank_mask:0xf bound_ctrl:1
	s_nop 1
	v_add_f32_dpp v116, v116, v116 row_mirror row_mask:0xf bank_mask:0xf bound_ctrl:1
	s_nop 1
	v_mov_b32_dpp v117, v116 row_bcast:15 row_mask:0xa bank_mask:0xf
	v_add_f32_e32 v116, v116, v117
	v_mov_b32_e32 v117, 0
	s_nop 1
	v_mov_b32_dpp v117, v116 row_bcast:31 row_mask:0xc bank_mask:0xf
	v_add_f32_e32 v116, v116, v117
	v_mul_f32_e32 v117, v10, v71
	v_readlane_b32 s3, v116, 63
	s_nop 1
	v_add_f32_e32 v116, s3, v86
	v_rsq_f32_e32 v116, v116
	v_readlane_b32 s3, v102, 29
	v_mul_f32_e32 v12, v68, v116
	v_mul_f32_e32 v127, 0x3e000000, v12
	v_mov_b32_e32 v12, v128
	v_mov_b32_e32 v68, v129
	v_pk_add_f32 v[128:129], v[12:13], v[68:69]
	v_lshlrev_b32_e32 v13, 16, v242
	v_lshlrev_b32_e32 v12, 16, v152
	v_pk_mul_f32 v[68:69], v[4:5], v[52:53] op_sel_hi:[0,1]
	v_pk_fma_f32 v[72:73], v[2:3], v[72:73], v[68:69] op_sel_hi:[0,1,1]
	v_pk_mov_b32 v[68:69], v[52:53], v[12:13] op_sel:[1,0]
	v_mov_b32_e32 v116, v114
	v_pk_fma_f32 v[52:53], v[6:7], v[68:69], v[72:73] op_sel_hi:[0,1,1]
	v_pk_fma_f32 v[52:53], v[8:9], v[12:13], v[52:53] op_sel_hi:[0,1,1]
	v_mul_f32_e32 v72, 0xbfb8aa3b, v52
	v_exp_f32_e32 v79, v72
	v_mul_f32_e32 v72, 0xbfb8aa3b, v53
	v_exp_f32_e32 v114, v72
	v_pk_add_f32 v[72:73], v[128:129], v[116:117]
	v_add_f32_e32 v79, 1.0, v79
	v_rcp_f32_e32 v116, v79
	v_add_f32_e32 v79, 1.0, v114
	v_rcp_f32_e32 v117, v79
	v_lshlrev_b32_e32 v114, 16, v153
	v_cvt_pk_bf16_f32 v79, v127, s0
	v_mov_b32_e32 v127, s4
	v_pk_mul_f32 v[52:53], v[52:53], v[116:117]
	v_mul_f32_e32 v117, v11, v114
	v_mov_b32_e32 v116, v115
	v_pk_add_f32 v[72:73], v[72:73], v[116:117]
	v_pk_mul_f32 v[52:53], v[52:53], s[2:3]
	v_mul_f32_e32 v115, 0xbfb8aa3b, v72
	v_exp_f32_e32 v115, v115
	v_mul_f32_e32 v116, 0xbfb8aa3b, v73
	v_exp_f32_e32 v117, v116
	v_mul_f32_e32 v129, v9, v54
	v_add_f32_e32 v115, 1.0, v115
	v_rcp_f32_e32 v116, v115
	v_add_f32_e32 v115, 1.0, v117
	v_rcp_f32_e32 v117, v115
	v_mul_f32_e32 v128, s3, v127
	v_fmac_f32_e32 v129, v5, v126
	v_pk_mul_f32 v[126:127], v[14:15], v[70:71]
	v_pk_mul_f32 v[72:73], v[72:73], v[116:117]
	v_fmac_f32_e32 v129, v7, v142
	v_pk_mul_f32 v[116:117], v[72:73], v[72:73]
	v_fmac_f32_e32 v129, v105, v141
	v_mul_f32_e32 v9, v9, v142
	v_add_f32_dpp v115, v116, v116 quad_perm:[1,0,3,2] row_mask:0xf bank_mask:0xf bound_ctrl:1
	v_mov_b32_e32 v116, 0
	v_fmac_f32_e32 v9, v5, v54
	v_add_f32_dpp v115, v115, v115 quad_perm:[2,3,0,1] row_mask:0xf bank_mask:0xf bound_ctrl:1
	v_fmac_f32_e32 v9, v7, v141
	v_fmac_f32_e32 v9, v105, v143
	v_add_f32_dpp v115, v115, v115 row_half_mirror row_mask:0xf bank_mask:0xf bound_ctrl:1
	v_mul_f32_e32 v7, 0xbfb8aa3b, v9
	v_exp_f32_e32 v7, v7
	v_add_f32_dpp v115, v115, v115 row_mirror row_mask:0xf bank_mask:0xf bound_ctrl:1
	v_readlane_b32 s3, v3, 30
	v_readlane_b32 s4, v3, 31
	v_mov_b32_dpp v116, v115 row_bcast:15 row_mask:0xa bank_mask:0xf
	v_add_f32_e32 v115, v115, v116
	v_mov_b32_e32 v116, 0
	v_add_f32_e32 v7, 1.0, v7
	v_rcp_f32_e32 v7, v7
	v_mov_b32_dpp v116, v115 row_bcast:31 row_mask:0xc bank_mask:0xf
	v_add_f32_e32 v115, v115, v116
	v_mul_f32_e32 v7, v9, v7
	v_readlane_b32 s2, v115, 63
	v_mov_b32_e32 v9, 0
	s_nop 0
	v_add_f32_e32 v115, s2, v86
	v_rsq_f32_e32 v116, v115
	s_nop 0
	v_add_f32_dpp v115, v117, v117 quad_perm:[1,0,3,2] row_mask:0xf bank_mask:0xf bound_ctrl:1
	v_mov_b32_e32 v117, 0
	s_nop 0
	v_add_f32_dpp v115, v115, v115 quad_perm:[2,3,0,1] row_mask:0xf bank_mask:0xf bound_ctrl:1
	s_nop 1
	v_add_f32_dpp v115, v115, v115 row_half_mirror row_mask:0xf bank_mask:0xf bound_ctrl:1
	s_nop 1
	v_add_f32_dpp v115, v115, v115 row_mirror row_mask:0xf bank_mask:0xf bound_ctrl:1
	s_nop 1
	v_mov_b32_dpp v117, v115 row_bcast:15 row_mask:0xa bank_mask:0xf
	v_add_f32_e32 v115, v115, v117
	v_mov_b32_e32 v117, 0
	s_nop 1
	v_mov_b32_dpp v117, v115 row_bcast:31 row_mask:0xc bank_mask:0xf
	v_add_f32_e32 v115, v115, v117
	s_nop 0
	v_readlane_b32 s2, v115, 63
	s_nop 1
	v_add_f32_e32 v115, s2, v86
	v_rsq_f32_e32 v117, v115
	v_lshlrev_b32_e32 v115, 16, v154
	v_mov_b32_e32 v54, v115
	v_pk_mul_f32 v[72:73], v[72:73], v[116:117]
	s_nop 0
	v_cvt_pk_bf16_f32 v70, v72, s0
	ds_write_b16 v118, v70 offset:7680
	v_pk_mul_f32 v[116:117], v[10:11], v[114:115]
	v_add_f32_e32 v70, v126, v127
	v_add_f32_e32 v70, v70, v116
	ds_write_b16 v119, v79 offset:3712
	v_add_f32_e32 v70, v70, v117
	v_mul_f32_e32 v79, 0xbfb8aa3b, v129
	v_exp_f32_e32 v79, v79
	v_mul_f32_e32 v116, 0xbfb8aa3b, v70
	v_exp_f32_e32 v116, v116
	v_cvt_pk_bf16_f32 v117, v73, s0
	v_add_f32_e32 v79, 1.0, v79
	v_rcp_f32_e32 v118, v79
	v_add_f32_e32 v79, 1.0, v116
	v_rcp_f32_e32 v116, v79
	ds_write_b16 v119, v117 offset:7808
	v_mul_f32_e32 v117, v129, v118
	v_mov_b32_e32 v118, 0
	v_mul_f32_e32 v116, v70, v116
	v_mul_f32_e32 v70, v117, v117
	v_pk_mul_f32 v[10:11], v[10:11], v[54:55]
	v_lshlrev_b32_e32 v54, 16, v155
	v_mov_b32_dpp v118, v70 quad_perm:[1,0,3,2] row_mask:0xf bank_mask:0xf
	v_fmac_f32_e32 v118, v117, v117
	v_lshlrev_b32_e32 v55, 16, v156
	v_mul_f32_e32 v78, v72, v130
	v_add_f32_dpp v70, v118, v118 quad_perm:[2,3,0,1] row_mask:0xf bank_mask:0xf bound_ctrl:1
	v_mov_b32_e32 v118, 0
	v_mul_f32_e32 v79, v73, v128
	v_add_f32_dpp v70, v70, v70 row_half_mirror row_mask:0xf bank_mask:0xf bound_ctrl:1
	v_and_b32_e32 v127, 7, v22
	s_nop 0
	v_add_f32_dpp v70, v70, v70 row_mirror row_mask:0xf bank_mask:0xf bound_ctrl:1
	s_nop 1
	v_mov_b32_dpp v118, v70 row_bcast:15 row_mask:0xa bank_mask:0xf
	v_add_f32_e32 v70, v70, v118
	v_mov_b32_e32 v118, 0
	s_nop 1
	v_mov_b32_dpp v118, v70 row_bcast:31 row_mask:0xc bank_mask:0xf
	v_add_f32_e32 v70, v70, v118
	v_mov_b32_e32 v118, 0
	v_readlane_b32 s2, v70, 63
	v_mul_f32_e32 v70, v116, v116
	s_nop 0
	v_add_f32_e32 v119, s2, v86
	v_mov_b32_dpp v118, v70 quad_perm:[1,0,3,2] row_mask:0xf bank_mask:0xf
	v_fmac_f32_e32 v118, v116, v116
	v_rsq_f32_e32 v119, v119
	s_nop 0
	v_add_f32_dpp v70, v118, v118 quad_perm:[2,3,0,1] row_mask:0xf bank_mask:0xf bound_ctrl:1
	v_mov_b32_e32 v118, 0
	s_nop 0
	v_add_f32_dpp v70, v70, v70 row_half_mirror row_mask:0xf bank_mask:0xf bound_ctrl:1
	s_nop 1
	v_add_f32_dpp v70, v70, v70 row_mirror row_mask:0xf bank_mask:0xf bound_ctrl:1
	s_nop 1
	v_mov_b32_dpp v118, v70 row_bcast:15 row_mask:0xa bank_mask:0xf
	v_add_f32_e32 v70, v70, v118
	v_mov_b32_e32 v118, 0
	s_nop 1
	v_mov_b32_dpp v118, v70 row_bcast:31 row_mask:0xc bank_mask:0xf
	v_add_f32_e32 v70, v70, v118
	s_nop 0
	v_readlane_b32 s2, v70, 63
	v_mul_f32_e32 v70, v117, v119
	v_mul_f32_e32 v70, 0x3e000000, v70
	v_cvt_pk_bf16_f32 v70, v70, s0
	ds_write_b16 v124, v70 offset:3840
	v_pk_mov_b32 v[70:71], v[70:71], v[114:115] op_sel:[1,0]
	v_add_f32_e32 v117, s2, v86
	v_pk_mul_f32 v[14:15], v[14:15], v[70:71]
	v_rsq_f32_e32 v118, v117
	v_add_f32_e32 v5, v14, v15
	v_add_f32_e32 v5, v5, v10
	v_add_f32_e32 v5, v5, v11
	v_mul_f32_e32 v10, 0xbfb8aa3b, v5
	v_exp_f32_e32 v10, v10
	v_mov_b32_e32 v119, s3
	v_readlane_b32 s2, v102, 30
	v_mov_b32_e32 v15, s4
	v_add_f32_e32 v10, 1.0, v10
	v_rcp_f32_e32 v10, v10
	v_mov_b32_e32 v117, s2
	v_pk_mul_f32 v[116:117], v[116:117], v[118:119]
	v_add_u32_e32 v119, 4, v109
	v_mul_f32_e32 v10, v5, v10
	v_mul_f32_e32 v5, v7, v7
	v_cvt_pk_bf16_f32 v11, v116, s0
	ds_write_b16 v124, v11 offset:7936
	v_mov_b32_dpp v9, v5 quad_perm:[1,0,3,2] row_mask:0xf bank_mask:0xf
	v_fmac_f32_e32 v9, v7, v7
	v_mul_f32_e32 v105, v116, v117
	v_add_u32_e32 v117, 2, v109
	v_add_f32_dpp v5, v9, v9 quad_perm:[2,3,0,1] row_mask:0xf bank_mask:0xf bound_ctrl:1
	v_mov_b32_e32 v9, 0
	v_lshlrev_b32_e32 v115, 2, v109
	v_add_f32_dpp v5, v5, v5 row_half_mirror row_mask:0xf bank_mask:0xf bound_ctrl:1
	v_sub_u32_e32 v128, v96, v115
	s_movk_i32 s4, 0x50
	v_add_f32_dpp v5, v5, v5 row_mirror row_mask:0xf bank_mask:0xf bound_ctrl:1
	s_nop 1
	v_mov_b32_dpp v9, v5 row_bcast:15 row_mask:0xa bank_mask:0xf
	v_add_f32_e32 v5, v5, v9
	v_mov_b32_e32 v9, 0
	s_nop 1
	v_mov_b32_dpp v9, v5 row_bcast:31 row_mask:0xc bank_mask:0xf
	v_add_f32_e32 v5, v5, v9
	v_mov_b32_e32 v9, 0
	v_readlane_b32 s3, v5, 63
	v_mul_f32_e32 v5, v10, v10
	s_nop 0
	v_add_f32_e32 v11, s3, v86
	v_mov_b32_dpp v9, v5 quad_perm:[1,0,3,2] row_mask:0xf bank_mask:0xf
	v_fmac_f32_e32 v9, v10, v10
	v_rsq_f32_e32 v11, v11
	s_nop 0
	v_add_f32_dpp v5, v9, v9 quad_perm:[2,3,0,1] row_mask:0xf bank_mask:0xf bound_ctrl:1
	v_mov_b32_e32 v9, 0
	s_nop 0
	v_add_f32_dpp v5, v5, v5 row_half_mirror row_mask:0xf bank_mask:0xf bound_ctrl:1
	s_nop 1
	v_add_f32_dpp v5, v5, v5 row_mirror row_mask:0xf bank_mask:0xf bound_ctrl:1
	s_nop 1
	v_mov_b32_dpp v9, v5 row_bcast:15 row_mask:0xa bank_mask:0xf
	v_add_f32_e32 v5, v5, v9
	v_mov_b32_e32 v9, 0
	s_nop 1
	v_mov_b32_dpp v9, v5 row_bcast:31 row_mask:0xc bank_mask:0xf
	v_add_f32_e32 v5, v5, v9
	s_nop 0
	v_readlane_b32 s3, v5, 63
	v_mul_f32_e32 v5, v7, v11
	v_mul_f32_e32 v7, 0x3e000000, v5
	v_add_f32_e32 v5, s3, v86
	v_rsq_f32_e32 v14, v5
	v_pk_mul_f32 v[4:5], v[4:5], v[12:13] op_sel_hi:[0,1]
	v_pk_fma_f32 v[4:5], v[2:3], v[68:69], v[4:5] op_sel_hi:[0,1,1]
	v_pk_mov_b32 v[12:13], v[12:13], v[54:55] op_sel:[1,0]
	v_readlane_b32 s3, v102, 31
	v_pk_fma_f32 v[4:5], v[6:7], v[12:13], v[4:5] op_sel_hi:[0,1,1]
	v_pk_fma_f32 v[4:5], v[8:9], v[54:55], v[4:5] op_sel_hi:[0,1,1]
	v_mul_f32_e32 v2, 0xbfb8aa3b, v4
	v_exp_f32_e32 v2, v2
	v_mul_f32_e32 v6, 0xbfb8aa3b, v5
	v_exp_f32_e32 v8, v6
	v_cvt_pk_bf16_f32 v9, v7, s0
	v_add_f32_e32 v2, 1.0, v2
	v_rcp_f32_e32 v6, v2
	v_add_f32_e32 v2, 1.0, v8
	v_rcp_f32_e32 v7, v2
	v_mov_b32_e32 v11, s3
	v_pk_mul_f32 v[10:11], v[10:11], v[14:15]
	ds_write_b16 v125, v9 offset:3968
	v_pk_mul_f32 v[2:3], v[4:5], v[6:7]
	v_cvt_pk_bf16_f32 v4, v64, v65
	v_pk_mul_f32 v[54:55], v[2:3], s[2:3]
	v_cvt_pk_bf16_f32 v2, v10, s0
	ds_write_b16 v125, v2 offset:8064
	v_cvt_pk_bf16_f32 v2, v56, v57
	v_cvt_pk_bf16_f32 v3, v58, v59
	v_cvt_pk_bf16_f32 v5, v66, v67
	v_cvt_pk_bf16_f32 v6, v60, v61
	v_cvt_pk_bf16_f32 v7, v62, v63
	v_cvt_pk_bf16_f32 v8, v72, v73
	v_cvt_pk_bf16_f32 v9, v116, v10
	global_store_dwordx4 v[16:17], v[2:5], off offset:1024
	global_store_dwordx4 v[16:17], v[6:9], off offset:1536
	v_mul_f32_e32 v114, v10, v11
	v_lshlrev_b32_e32 v2, 7, v22
	v_and_b32_e32 v2, 0xf80, v2
	v_add_u32_e32 v64, s51, v2
	v_bitop3_b32 v2, v109, v22, 7 bitop3:0x78
	s_waitcnt lgkmcnt(0)
	v_lshl_add_u32 v116, v2, 4, v64
	ds_read_b128 v[2:5], v116 offset:4096
	ds_read_b128 v[6:9], v116
	s_waitcnt lgkmcnt(0)
	v_mfma_f32_32x32x16_bf16 v[2:17], v[2:5], v[6:9], 0
	v_bitop3_b32 v56, v117, v22, 7 bitop3:0x78
	v_lshl_add_u32 v118, v56, 4, v64
	ds_read_b128 v[56:59], v118 offset:4096
	ds_read_b128 v[60:63], v118
	v_add_u32_e32 v125, 6, v109
	v_readlane_b32 s2, v101, 0
	v_readlane_b32 s3, v101, 4
	s_waitcnt lgkmcnt(0)
	v_mfma_f32_32x32x16_bf16 v[2:17], v[56:59], v[60:63], v[2:17]
	v_bitop3_b32 v56, v119, v22, 7 bitop3:0x78
	v_lshl_add_u32 v124, v56, 4, v64
	ds_read_b128 v[56:59], v124 offset:4096
	ds_read_b128 v[60:63], v124
	s_waitcnt lgkmcnt(0)
	v_mfma_f32_32x32x16_bf16 v[2:17], v[56:59], v[60:63], v[2:17]
	v_bitop3_b32 v56, v125, v22, 7 bitop3:0x78
	v_lshl_add_u32 v126, v56, 4, v64
	ds_read_b128 v[56:59], v126 offset:4096
	ds_read_b128 v[60:63], v126
	s_waitcnt lgkmcnt(0)
	v_mfma_f32_32x32x16_bf16 v[2:17], v[56:59], v[60:63], v[2:17]
	v_mov_b32_e32 v56, s3
	v_mov_b32_e32 v57, s2
	v_cndmask_b32_e32 v56, v56, v57, vcc
	v_sub_f32_e32 v56, v101, v56
	v_mul_f32_e32 v56, 0x3fb8aa3b, v56
	v_readlane_b32 s2, v101, 1
	v_readlane_b32 s3, v101, 5
	v_exp_f32_e32 v64, v56
	v_mov_b32_e32 v57, s2
	v_mov_b32_e32 v56, s3
	v_cndmask_b32_e32 v56, v56, v57, vcc
	v_sub_f32_e32 v56, v101, v56
	v_mul_f32_e32 v56, 0x3fb8aa3b, v56
	v_readlane_b32 s2, v101, 2
	v_readlane_b32 s3, v101, 6
	v_exp_f32_e32 v65, v56
	v_mov_b32_e32 v57, s2
	v_mov_b32_e32 v56, s3
	v_cndmask_b32_e32 v56, v56, v57, vcc
	v_sub_f32_e32 v56, v101, v56
	v_mul_f32_e32 v56, 0x3fb8aa3b, v56
	v_readlane_b32 s2, v101, 3
	v_readlane_b32 s3, v101, 7
	v_exp_f32_e32 v62, v56
	v_mov_b32_e32 v57, s2
	v_mov_b32_e32 v56, s3
	v_cndmask_b32_e32 v56, v56, v57, vcc
	v_sub_f32_e32 v56, v101, v56
	v_mul_f32_e32 v56, 0x3fb8aa3b, v56
	v_readlane_b32 s2, v101, 8
	v_readlane_b32 s3, v101, 12
	v_exp_f32_e32 v63, v56
	v_mov_b32_e32 v57, s2
	v_mov_b32_e32 v56, s3
	v_cndmask_b32_e32 v56, v56, v57, vcc
	v_sub_f32_e32 v56, v101, v56
	v_mul_f32_e32 v56, 0x3fb8aa3b, v56
	v_readlane_b32 s2, v101, 9
	v_readlane_b32 s3, v101, 13
	v_exp_f32_e32 v60, v56
	v_mov_b32_e32 v57, s2
	v_mov_b32_e32 v56, s3
	v_cndmask_b32_e32 v56, v56, v57, vcc
	v_sub_f32_e32 v56, v101, v56
	v_mul_f32_e32 v56, 0x3fb8aa3b, v56
	v_readlane_b32 s2, v101, 10
	v_readlane_b32 s3, v101, 14
	v_exp_f32_e32 v61, v56
	v_mov_b32_e32 v57, s2
	v_mov_b32_e32 v56, s3
	v_cndmask_b32_e32 v56, v56, v57, vcc
	v_sub_f32_e32 v56, v101, v56
	v_mul_f32_e32 v56, 0x3fb8aa3b, v56
	v_readlane_b32 s2, v101, 11
	v_readlane_b32 s3, v101, 15
	v_exp_f32_e32 v58, v56
	v_mov_b32_e32 v57, s2
	v_mov_b32_e32 v56, s3
	v_cndmask_b32_e32 v56, v56, v57, vcc
	v_sub_f32_e32 v56, v101, v56
	v_mul_f32_e32 v56, 0x3fb8aa3b, v56
	v_readlane_b32 s2, v101, 16
	v_readlane_b32 s3, v101, 20
	v_exp_f32_e32 v59, v56
	v_mov_b32_e32 v57, s2
	v_mov_b32_e32 v56, s3
	v_cndmask_b32_e32 v56, v56, v57, vcc
	v_sub_f32_e32 v56, v101, v56
	v_mul_f32_e32 v56, 0x3fb8aa3b, v56
	v_readlane_b32 s2, v101, 17
	v_readlane_b32 s3, v101, 21
	v_exp_f32_e32 v72, v56
	v_mov_b32_e32 v57, s2
	v_mov_b32_e32 v56, s3
	v_cndmask_b32_e32 v56, v56, v57, vcc
	v_sub_f32_e32 v56, v101, v56
	v_mul_f32_e32 v56, 0x3fb8aa3b, v56
	v_readlane_b32 s2, v101, 18
	v_readlane_b32 s3, v101, 22
	v_exp_f32_e32 v73, v56
	v_mov_b32_e32 v57, s2
	v_mov_b32_e32 v56, s3
	v_cndmask_b32_e32 v56, v56, v57, vcc
	v_sub_f32_e32 v56, v101, v56
	v_mul_f32_e32 v56, 0x3fb8aa3b, v56
	v_readlane_b32 s2, v101, 19
	v_readlane_b32 s3, v101, 23
	v_exp_f32_e32 v70, v56
	v_mov_b32_e32 v57, s2
	v_mov_b32_e32 v56, s3
	v_cndmask_b32_e32 v56, v56, v57, vcc
	v_sub_f32_e32 v56, v101, v56
	v_mul_f32_e32 v56, 0x3fb8aa3b, v56
	v_readlane_b32 s2, v101, 24
	v_readlane_b32 s3, v101, 28
	v_exp_f32_e32 v71, v56
	v_mov_b32_e32 v57, s2
	v_mov_b32_e32 v56, s3
	v_cndmask_b32_e32 v56, v56, v57, vcc
	v_sub_f32_e32 v56, v101, v56
	v_mul_f32_e32 v56, 0x3fb8aa3b, v56
	v_readlane_b32 s2, v101, 25
	v_readlane_b32 s3, v101, 29
	v_exp_f32_e32 v68, v56
	v_mov_b32_e32 v57, s2
	v_mov_b32_e32 v56, s3
	v_cndmask_b32_e32 v56, v56, v57, vcc
	v_sub_f32_e32 v56, v101, v56
	v_mul_f32_e32 v56, 0x3fb8aa3b, v56
	v_readlane_b32 s2, v101, 26
	v_readlane_b32 s3, v101, 30
	v_exp_f32_e32 v69, v56
	v_mov_b32_e32 v57, s2
	v_mov_b32_e32 v56, s3
	v_cndmask_b32_e32 v56, v56, v57, vcc
	v_sub_f32_e32 v56, v101, v56
	v_mul_f32_e32 v56, 0x3fb8aa3b, v56
	v_readlane_b32 s2, v101, 27
	v_readlane_b32 s3, v101, 31
	v_pk_mul_f32 v[2:3], v[2:3], v[64:65]
	v_exp_f32_e32 v66, v56
	v_mov_b32_e32 v56, s3
	v_mov_b32_e32 v57, s2
	v_cndmask_b32_e32 v56, v56, v57, vcc
	v_cvt_pk_bf16_f32 v2, v2, v3
	v_cmp_lt_i32_e32 vcc, -1, v128
	v_pk_mul_f32 v[4:5], v[4:5], v[62:63]
	v_pk_mul_f32 v[6:7], v[6:7], v[60:61]
	v_cndmask_b32_e32 v3, 0, v2, vcc
	v_lshrrev_b32_e32 v2, 16, v2
	v_cmp_lt_i32_e32 vcc, 0, v128
	v_pk_mul_f32 v[8:9], v[8:9], v[58:59]
	v_sub_f32_e32 v56, v101, v56
	v_cndmask_b32_e32 v2, 0, v2, vcc
	v_perm_b32 v2, v2, v3, s15
	v_cvt_pk_bf16_f32 v3, v4, v5
	v_cmp_lt_i32_e32 vcc, 1, v128
	v_mul_f32_e32 v56, 0x3fb8aa3b, v56
	v_exp_f32_e32 v67, v56
	v_cndmask_b32_e32 v4, 0, v3, vcc
	v_lshrrev_b32_e32 v3, 16, v3
	v_cmp_lt_i32_e32 vcc, 2, v128
	s_add_u32 s2, s0, 0x2000
	v_lshlrev_b32_e32 v56, 4, v22
	v_cndmask_b32_e32 v3, 0, v3, vcc
	v_perm_b32 v3, v3, v4, s15
	v_cvt_pk_bf16_f32 v4, v6, v7
	v_cmp_lt_i32_e32 vcc, 7, v128
	s_addc_u32 s3, s1, 0
	v_ashrrev_i32_e32 v57, 31, v56
	v_cndmask_b32_e32 v5, 0, v4, vcc
	v_lshrrev_b32_e32 v4, 16, v4
	v_cmp_lt_i32_e32 vcc, 8, v128
	v_pk_mul_f32 v[10:11], v[10:11], v[72:73]
	v_pk_mul_f32 v[12:13], v[12:13], v[70:71]
	v_cndmask_b32_e32 v4, 0, v4, vcc
	v_perm_b32 v4, v4, v5, s15
	v_cvt_pk_bf16_f32 v5, v8, v9
	v_cmp_lt_i32_e32 vcc, 9, v128
	v_pk_mul_f32 v[14:15], v[14:15], v[68:69]
	v_pk_mul_f32 v[16:17], v[16:17], v[66:67]
	v_cndmask_b32_e32 v6, 0, v5, vcc
	v_lshrrev_b32_e32 v5, 16, v5
	v_cmp_lt_i32_e32 vcc, 10, v128
	v_lshl_add_u32 v101, v96, 7, s51
	v_lshl_add_u32 v8, v109, 3, v101
	v_cndmask_b32_e32 v5, 0, v5, vcc
	v_perm_b32 v5, v5, v6, s15
	v_lshl_add_u64 v[6:7], s[2:3], 0, v[56:57]
	flat_store_dwordx4 v[6:7], v[2:5]
	v_cmp_lt_i32_e32 vcc, 15, v128
	v_lshlrev_b32_e32 v9, 4, v127
	v_cvt_pk_bf16_f32 v2, v10, v11
	v_cndmask_b32_e32 v3, 0, v2, vcc
	v_lshrrev_b32_e32 v2, 16, v2
	v_cmp_lt_i32_e32 vcc, 16, v128
	v_lshlrev_b32_e32 v109, 9, v109
	s_nop 0
	v_cndmask_b32_e32 v2, 0, v2, vcc
	v_perm_b32 v2, v2, v3, s15
	v_cvt_pk_bf16_f32 v3, v12, v13
	v_cmp_lt_i32_e32 vcc, 17, v128
	s_nop 1
	v_cndmask_b32_e32 v4, 0, v3, vcc
	v_lshrrev_b32_e32 v3, 16, v3
	v_cmp_lt_i32_e32 vcc, 18, v128
	s_nop 1
	v_cndmask_b32_e32 v3, 0, v3, vcc
	v_perm_b32 v3, v3, v4, s15
	v_cvt_pk_bf16_f32 v4, v14, v15
	v_cmp_lt_i32_e32 vcc, 23, v128
	s_nop 1
	v_cndmask_b32_e32 v5, 0, v4, vcc
	v_lshrrev_b32_e32 v4, 16, v4
	v_cmp_lt_i32_e32 vcc, 24, v128
	s_nop 1
	v_cndmask_b32_e32 v4, 0, v4, vcc
	v_perm_b32 v4, v4, v5, s15
	v_cvt_pk_bf16_f32 v5, v16, v17
	v_cmp_lt_i32_e32 vcc, 25, v128
	s_nop 1
	v_cndmask_b32_e32 v6, 0, v5, vcc
	v_lshrrev_b32_e32 v5, 16, v5
	v_cmp_lt_i32_e32 vcc, 26, v128
	s_nop 1
	v_cndmask_b32_e32 v5, 0, v5, vcc
	v_perm_b32 v5, v5, v6, s15
	v_add_u32_e32 v6, 0x400, v56
	v_ashrrev_i32_e32 v7, 31, v6
	v_lshl_add_u64 v[6:7], s[2:3], 0, v[6:7]
	flat_store_dwordx4 v[6:7], v[2:5]
	s_add_u32 s2, s0, 0x1000
	v_or_b32_e32 v6, v109, v108
	v_add_u32_e32 v2, v8, v9
	v_xad_u32 v4, v9, 16, v8
	ds_read_b64 v[2:3], v2
	ds_read_b64 v[4:5], v4
	s_addc_u32 s3, s1, 0
	v_ashrrev_i32_e32 v7, 31, v6
	v_lshl_add_u64 v[6:7], s[2:3], 0, v[6:7]
	v_cmp_gt_i32_e32 vcc, v96, v115
	s_waitcnt lgkmcnt(0)
	flat_store_dwordx4 v[6:7], v[2:5]
	v_lshl_or_b32 v6, v117, 9, v108
	v_ashrrev_i32_e32 v7, 31, v6
	v_xad_u32 v2, v9, 32, v8
	v_xad_u32 v4, v9, 48, v8
	ds_read_b64 v[2:3], v2
	ds_read_b64 v[4:5], v4
	v_lshl_add_u64 v[6:7], s[2:3], 0, v[6:7]
	s_waitcnt lgkmcnt(0)
	flat_store_dwordx4 v[6:7], v[2:5]
	s_nop 1
	v_xad_u32 v2, v9, 64, v8
	v_xad_u32 v4, v9, s4, v8
	ds_read_b64 v[2:3], v2
	ds_read_b64 v[4:5], v4
	v_lshl_or_b32 v6, v119, 9, v108
	v_ashrrev_i32_e32 v7, 31, v6
	v_lshl_add_u64 v[6:7], s[2:3], 0, v[6:7]
	s_movk_i32 s4, 0x60
	s_waitcnt lgkmcnt(0)
	flat_store_dwordx4 v[6:7], v[2:5]
	v_lshl_or_b32 v6, v125, 9, v108
	v_ashrrev_i32_e32 v7, 31, v6
	v_xad_u32 v2, v9, s4, v8
	s_movk_i32 s4, 0x70
	v_xad_u32 v4, v9, s4, v8
	ds_read_b64 v[2:3], v2
	ds_read_b64 v[4:5], v4
	v_lshl_add_u64 v[6:7], s[2:3], 0, v[6:7]
	s_movk_i32 s2, 0xff84
	v_mad_i32_i24 v101, v96, s2, v101
	s_add_u32 s2, s0, 0x3800
	s_waitcnt lgkmcnt(0)
	flat_store_dwordx4 v[6:7], v[2:5]
	ds_read_b128 v[2:5], v116 offset:4096
	ds_read_b128 v[116:119], v118 offset:4096
	s_waitcnt lgkmcnt(0)
	v_mfma_f32_32x32x16_bf16 v[2:17], v[2:5], v[2:5], 0
	s_addc_u32 s3, s1, 0
	v_mfma_f32_32x32x16_bf16 v[2:17], v[116:119], v[116:119], v[2:17]
	ds_read_b128 v[116:119], v124 offset:4096
	ds_read_b128 v[124:127], v126 offset:4096
	s_waitcnt lgkmcnt(0)
	v_mfma_f32_32x32x16_bf16 v[2:17], v[116:119], v[116:119], v[2:17]
	v_mfma_f32_32x32x16_bf16 v[2:17], v[124:127], v[124:127], v[2:17]
	s_nop 11
	v_mul_f32_e32 v2, v102, v2
	v_mul_f32_e32 v2, v2, v64
	v_cndmask_b32_e32 v2, 0, v2, vcc
	v_add_u32_e32 v64, v101, v109
	ds_write_b32 v64, v2 offset:8192
	v_or_b32_e32 v2, 1, v115
	v_mul_f32_e32 v3, v102, v3
	v_mul_f32_e32 v3, v3, v65
	v_cmp_gt_i32_e32 vcc, v96, v2
	v_lshl_add_u32 v2, v2, 7, v101
	s_nop 0
	v_cndmask_b32_e32 v3, 0, v3, vcc
	ds_write_b32 v2, v3 offset:8192
	v_or_b32_e32 v2, 2, v115
	v_mul_f32_e32 v3, v102, v4
	v_mul_f32_e32 v3, v3, v62
	v_cmp_gt_i32_e32 vcc, v96, v2
	v_lshl_add_u32 v2, v2, 7, v101
	s_nop 0
	v_cndmask_b32_e32 v3, 0, v3, vcc
	ds_write_b32 v2, v3 offset:8192
	v_or_b32_e32 v2, 3, v115
	v_mul_f32_e32 v3, v102, v5
	v_mul_f32_e32 v3, v3, v63
	v_cmp_gt_i32_e32 vcc, v96, v2
	v_lshl_add_u32 v2, v2, 7, v101
	s_nop 0
	v_cndmask_b32_e32 v3, 0, v3, vcc
	ds_write_b32 v2, v3 offset:8192
	v_add_u32_e32 v2, 8, v115
	v_mul_f32_e32 v3, v102, v6
	v_mul_f32_e32 v3, v3, v60
	v_cmp_gt_i32_e32 vcc, v96, v2
	v_lshl_add_u32 v2, v2, 7, v101
	s_nop 0
	v_cndmask_b32_e32 v3, 0, v3, vcc
	ds_write_b32 v2, v3 offset:8192
	v_add_u32_e32 v2, 9, v115
	v_mul_f32_e32 v3, v102, v7
	v_mul_f32_e32 v3, v3, v61
	v_cmp_gt_i32_e32 vcc, v96, v2
	v_lshl_add_u32 v2, v2, 7, v101
	s_nop 0
	v_cndmask_b32_e32 v3, 0, v3, vcc
	ds_write_b32 v2, v3 offset:8192
	v_add_u32_e32 v2, 10, v115
	v_mul_f32_e32 v3, v102, v8
	v_mul_f32_e32 v3, v3, v58
	v_cmp_gt_i32_e32 vcc, v96, v2
	v_lshl_add_u32 v2, v2, 7, v101
	v_mov_b32_e32 v58, 0
	v_cndmask_b32_e32 v3, 0, v3, vcc
	ds_write_b32 v2, v3 offset:8192
	v_add_u32_e32 v2, 11, v115
	v_mul_f32_e32 v3, v102, v9
	v_mul_f32_e32 v3, v3, v59
	v_cmp_gt_i32_e32 vcc, v96, v2
	v_lshl_add_u32 v2, v2, 7, v101
	s_nop 0
	v_cndmask_b32_e32 v3, 0, v3, vcc
	ds_write_b32 v2, v3 offset:8192
	v_add_u32_e32 v2, 16, v115
	v_mul_f32_e32 v3, v102, v10
	v_mul_f32_e32 v3, v3, v72
	v_cmp_gt_i32_e32 vcc, v96, v2
	v_lshl_add_u32 v2, v2, 7, v101
	s_nop 0
	v_cndmask_b32_e32 v3, 0, v3, vcc
	ds_write_b32 v2, v3 offset:8192
	v_add_u32_e32 v2, 17, v115
	v_mul_f32_e32 v3, v102, v11
	v_mul_f32_e32 v3, v3, v73
	v_cmp_gt_i32_e32 vcc, v96, v2
	v_lshl_add_u32 v2, v2, 7, v101
	s_nop 0
	v_cndmask_b32_e32 v3, 0, v3, vcc
	ds_write_b32 v2, v3 offset:8192
	v_add_u32_e32 v2, 18, v115
	v_mul_f32_e32 v3, v102, v12
	v_mul_f32_e32 v3, v3, v70
	v_cmp_gt_i32_e32 vcc, v96, v2
	v_lshl_add_u32 v2, v2, 7, v101
	s_nop 0
	v_cndmask_b32_e32 v3, 0, v3, vcc
	ds_write_b32 v2, v3 offset:8192
	v_add_u32_e32 v2, 19, v115
	v_mul_f32_e32 v3, v102, v13
	v_mul_f32_e32 v3, v3, v71
	v_cmp_gt_i32_e32 vcc, v96, v2
	v_lshl_add_u32 v2, v2, 7, v101
	s_nop 0
	v_cndmask_b32_e32 v3, 0, v3, vcc
	ds_write_b32 v2, v3 offset:8192
	v_add_u32_e32 v2, 24, v115
	v_mul_f32_e32 v3, v102, v14
	v_mul_f32_e32 v3, v3, v68
	v_cmp_gt_i32_e32 vcc, v96, v2
	v_lshl_add_u32 v2, v2, 7, v101
	s_nop 0
	v_cndmask_b32_e32 v3, 0, v3, vcc
	ds_write_b32 v2, v3 offset:8192
	v_add_u32_e32 v2, 25, v115
	v_mul_f32_e32 v3, v102, v15
	v_mul_f32_e32 v3, v3, v69
	v_cmp_gt_i32_e32 vcc, v96, v2
	v_lshl_add_u32 v2, v2, 7, v101
	s_nop 0
	v_cndmask_b32_e32 v3, 0, v3, vcc
	ds_write_b32 v2, v3 offset:8192
	v_add_u32_e32 v2, 26, v115
	v_mul_f32_e32 v3, v102, v16
	v_mul_f32_e32 v3, v3, v66
	v_cmp_gt_i32_e32 vcc, v96, v2
	v_lshl_add_u32 v2, v2, 7, v101
	s_nop 0
	v_cndmask_b32_e32 v3, 0, v3, vcc
	ds_write_b32 v2, v3 offset:8192
	v_add_u32_e32 v2, 27, v115
	v_mul_f32_e32 v3, v102, v17
	v_mul_f32_e32 v3, v3, v67
	v_cmp_gt_i32_e32 vcc, v96, v2
	v_lshl_add_u32 v2, v2, 7, v101
	s_nop 0
	v_cndmask_b32_e32 v3, 0, v3, vcc
	ds_write_b32 v2, v3 offset:8192
	s_waitcnt lgkmcnt(0)
	s_nop 0
	v_add_u32_e32 v14, s51, v58
	ds_read_b128 v[2:5], v14 offset:8192
	ds_read_b128 v[6:9], v14 offset:8208
	ds_read_b128 v[10:13], v14 offset:8224
	ds_read_b128 v[14:17], v14 offset:8240
	s_waitcnt lgkmcnt(0)
	v_fma_f32 v36, -v14, v24, v36
	v_fma_f32 v104, -v14, v88, v104
	v_fma_f32 v39, -v17, v24, v39
	v_fma_f32 v25, -v3, v24, v25
	v_fma_f32 v90, -v3, v88, v90
	v_fma_f32 v26, -v4, v24, v26
	v_fma_f32 v89, -v4, v88, v89
	v_fma_f32 v27, -v5, v24, v27
	s_nop 0
	v_fma_f32 v91, -v5, v88, v91
	v_fma_f32 v28, -v6, v24, v28
	v_fma_f32 v92, -v6, v88, v92
	v_fma_f32 v29, -v7, v24, v29
	v_fma_f32 v93, -v7, v88, v93
	s_nop 0
	v_add_u32_e32 v14, s51, v58
	v_fma_f32 v30, -v8, v24, v30
	v_fma_f32 v94, -v8, v88, v94
	v_fma_f32 v31, -v9, v24, v31
	v_fma_f32 v95, -v9, v88, v95
	v_fma_f32 v32, -v10, v24, v32
	v_fma_f32 v98, -v10, v88, v98
	v_fma_f32 v33, -v11, v24, v33
	v_fma_f32 v97, -v11, v88, v97
	v_fma_f32 v34, -v12, v24, v34
	v_fma_f32 v100, -v12, v88, v100
	v_fma_f32 v35, -v13, v24, v35
	v_fma_f32 v99, -v13, v88, v99
	v_fma_f32 v37, -v15, v24, v37
	v_fma_f32 v103, -v15, v88, v103
	v_fma_f32 v38, -v16, v24, v38
	v_fma_f32 v107, -v16, v88, v107
	ds_read_b128 v[2:5], v14 offset:8256
	v_fma_f32 v106, -v17, v88, v106
	ds_read_b128 v[6:9], v14 offset:8272
	ds_read_b128 v[10:13], v14 offset:8288
	ds_read_b128 v[14:17], v14 offset:8304
	v_mov_b32_e32 v58, 0x80
	s_waitcnt lgkmcnt(0)
	v_fma_f32 v52, -v14, v24, v52
	v_fma_f32 v78, -v14, v88, v78
	v_fma_f32 v40, -v2, v24, v40
	v_fma_f32 v111, -v2, v88, v111
	v_fma_f32 v41, -v3, v24, v41
	v_fma_f32 v110, -v3, v88, v110
	v_fma_f32 v42, -v4, v24, v42
	s_nop 0
	v_add_u32_e32 v14, s51, v58
	v_fma_f32 v113, -v4, v88, v113
	v_fma_f32 v43, -v5, v24, v43
	v_fma_f32 v112, -v5, v88, v112
	v_fma_f32 v46, -v6, v24, v46
	v_fma_f32 v121, -v6, v88, v121
	v_fma_f32 v47, -v7, v24, v47
	v_fma_f32 v120, -v7, v88, v120
	v_fma_f32 v48, -v8, v24, v48
	v_fma_f32 v123, -v8, v88, v123
	v_fma_f32 v49, -v9, v24, v49
	v_fma_f32 v122, -v9, v88, v122
	v_fma_f32 v44, -v10, v24, v44
	v_fma_f32 v74, -v10, v88, v74
	v_fma_f32 v45, -v11, v24, v45
	v_fma_f32 v75, -v11, v88, v75
	v_fma_f32 v50, -v12, v24, v50
	v_fma_f32 v76, -v12, v88, v76
	v_fma_f32 v51, -v13, v24, v51
	v_fma_f32 v77, -v13, v88, v77
	v_fma_f32 v53, -v15, v24, v53
	v_fma_f32 v79, -v15, v88, v79
	v_fma_f32 v54, -v16, v24, v54
	v_fma_f32 v105, -v16, v88, v105
	v_fma_f32 v55, -v17, v24, v55
	ds_read_b128 v[2:5], v14 offset:8192
	v_fma_f32 v114, -v17, v88, v114
	ds_read_b128 v[6:9], v14 offset:8208
	ds_read_b128 v[10:13], v14 offset:8224
	ds_read_b128 v[14:17], v14 offset:8240
	s_waitcnt lgkmcnt(0)
	v_fma_f32 v36, -v14, v25, v36
	v_fma_f32 v104, -v14, v90, v104
	v_fma_f32 v39, -v17, v25, v39
	v_fma_f32 v26, -v4, v25, v26
	v_fma_f32 v89, -v4, v90, v89
	v_fma_f32 v27, -v5, v25, v27
	v_fma_f32 v91, -v5, v90, v91
	v_fma_f32 v28, -v6, v25, v28
	s_nop 0
	v_fma_f32 v92, -v6, v90, v92
	v_fma_f32 v29, -v7, v25, v29
	v_fma_f32 v93, -v7, v90, v93
	v_fma_f32 v30, -v8, v25, v30
	v_fma_f32 v94, -v8, v90, v94
	s_nop 0
	v_add_u32_e32 v14, s51, v58
	v_fma_f32 v31, -v9, v25, v31
	v_fma_f32 v95, -v9, v90, v95
	v_fma_f32 v32, -v10, v25, v32
	v_fma_f32 v98, -v10, v90, v98
	v_fma_f32 v33, -v11, v25, v33
	v_fma_f32 v97, -v11, v90, v97
	v_fma_f32 v34, -v12, v25, v34
	v_fma_f32 v100, -v12, v90, v100
	v_fma_f32 v35, -v13, v25, v35
	v_fma_f32 v99, -v13, v90, v99
	v_fma_f32 v37, -v15, v25, v37
	v_fma_f32 v103, -v15, v90, v103
	v_fma_f32 v38, -v16, v25, v38
	v_fma_f32 v107, -v16, v90, v107
	ds_read_b128 v[2:5], v14 offset:8256
	v_fma_f32 v106, -v17, v90, v106
	ds_read_b128 v[6:9], v14 offset:8272
	ds_read_b128 v[10:13], v14 offset:8288
	ds_read_b128 v[14:17], v14 offset:8304
	v_mov_b32_e32 v58, 0x100
	s_waitcnt lgkmcnt(0)
	v_fma_f32 v52, -v14, v25, v52
	v_fma_f32 v78, -v14, v90, v78
	v_fma_f32 v40, -v2, v25, v40
	v_fma_f32 v111, -v2, v90, v111
	v_fma_f32 v41, -v3, v25, v41
	v_fma_f32 v110, -v3, v90, v110
	v_fma_f32 v42, -v4, v25, v42
	s_nop 0
	v_add_u32_e32 v14, s51, v58
	v_fma_f32 v113, -v4, v90, v113
	v_fma_f32 v43, -v5, v25, v43
	v_fma_f32 v112, -v5, v90, v112
	v_fma_f32 v46, -v6, v25, v46
	v_fma_f32 v121, -v6, v90, v121
	v_fma_f32 v47, -v7, v25, v47
	v_fma_f32 v120, -v7, v90, v120
	v_fma_f32 v48, -v8, v25, v48
	v_fma_f32 v123, -v8, v90, v123
	v_fma_f32 v49, -v9, v25, v49
	v_fma_f32 v122, -v9, v90, v122
	v_fma_f32 v44, -v10, v25, v44
	v_fma_f32 v74, -v10, v90, v74
	v_fma_f32 v45, -v11, v25, v45
	v_fma_f32 v75, -v11, v90, v75
	v_fma_f32 v50, -v12, v25, v50
	v_fma_f32 v76, -v12, v90, v76
	v_fma_f32 v51, -v13, v25, v51
	v_fma_f32 v77, -v13, v90, v77
	v_fma_f32 v53, -v15, v25, v53
	v_fma_f32 v79, -v15, v90, v79
	v_fma_f32 v54, -v16, v25, v54
	v_fma_f32 v105, -v16, v90, v105
	v_fma_f32 v55, -v17, v25, v55
	ds_read_b128 v[2:5], v14 offset:8192
	v_fma_f32 v114, -v17, v90, v114
	ds_read_b128 v[6:9], v14 offset:8208
	ds_read_b128 v[10:13], v14 offset:8224
	ds_read_b128 v[14:17], v14 offset:8240
	s_waitcnt lgkmcnt(0)
	v_fma_f32 v36, -v14, v26, v36
	v_fma_f32 v104, -v14, v89, v104
	v_fma_f32 v39, -v17, v26, v39
	v_fma_f32 v27, -v5, v26, v27
	v_fma_f32 v91, -v5, v89, v91
	v_fma_f32 v28, -v6, v26, v28
	v_fma_f32 v92, -v6, v89, v92
	v_fma_f32 v29, -v7, v26, v29
	s_nop 0
	v_fma_f32 v93, -v7, v89, v93
	v_fma_f32 v30, -v8, v26, v30
	v_fma_f32 v94, -v8, v89, v94
	v_fma_f32 v31, -v9, v26, v31
	v_fma_f32 v95, -v9, v89, v95
	s_nop 0
	v_add_u32_e32 v14, s51, v58
	v_fma_f32 v32, -v10, v26, v32
	v_fma_f32 v98, -v10, v89, v98
	v_fma_f32 v33, -v11, v26, v33
	v_fma_f32 v97, -v11, v89, v97
	v_fma_f32 v34, -v12, v26, v34
	v_fma_f32 v100, -v12, v89, v100
	v_fma_f32 v35, -v13, v26, v35
	v_fma_f32 v99, -v13, v89, v99
	v_fma_f32 v37, -v15, v26, v37
	v_fma_f32 v103, -v15, v89, v103
	v_fma_f32 v38, -v16, v26, v38
	v_fma_f32 v107, -v16, v89, v107
	ds_read_b128 v[2:5], v14 offset:8256
	v_fma_f32 v106, -v17, v89, v106
	ds_read_b128 v[6:9], v14 offset:8272
	ds_read_b128 v[10:13], v14 offset:8288
	ds_read_b128 v[14:17], v14 offset:8304
	v_mov_b32_e32 v58, 0x180
	s_waitcnt lgkmcnt(0)
	v_fma_f32 v52, -v14, v26, v52
	v_fma_f32 v78, -v14, v89, v78
	v_fma_f32 v40, -v2, v26, v40
	v_fma_f32 v111, -v2, v89, v111
	v_fma_f32 v41, -v3, v26, v41
	v_fma_f32 v110, -v3, v89, v110
	v_fma_f32 v42, -v4, v26, v42
	s_nop 0
	v_add_u32_e32 v14, s51, v58
	v_fma_f32 v113, -v4, v89, v113
	v_fma_f32 v43, -v5, v26, v43
	v_fma_f32 v112, -v5, v89, v112
	v_fma_f32 v46, -v6, v26, v46
	v_fma_f32 v121, -v6, v89, v121
	v_fma_f32 v47, -v7, v26, v47
	v_fma_f32 v120, -v7, v89, v120
	v_fma_f32 v48, -v8, v26, v48
	v_fma_f32 v123, -v8, v89, v123
	v_fma_f32 v49, -v9, v26, v49
	v_fma_f32 v122, -v9, v89, v122
	v_fma_f32 v44, -v10, v26, v44
	v_fma_f32 v74, -v10, v89, v74
	v_fma_f32 v45, -v11, v26, v45
	v_fma_f32 v75, -v11, v89, v75
	v_fma_f32 v50, -v12, v26, v50
	v_fma_f32 v76, -v12, v89, v76
	v_fma_f32 v51, -v13, v26, v51
	v_fma_f32 v77, -v13, v89, v77
	v_fma_f32 v53, -v15, v26, v53
	v_fma_f32 v79, -v15, v89, v79
	v_fma_f32 v54, -v16, v26, v54
	v_fma_f32 v105, -v16, v89, v105
	v_fma_f32 v55, -v17, v26, v55
	ds_read_b128 v[2:5], v14 offset:8208
	v_fma_f32 v114, -v17, v89, v114
	ds_read_b128 v[6:9], v14 offset:8224
	ds_read_b128 v[10:13], v14 offset:8240
	ds_read_b128 v[14:17], v14 offset:8256
	s_waitcnt lgkmcnt(0)
	v_fma_f32 v36, -v10, v27, v36
	v_fma_f32 v104, -v10, v91, v104
	v_fma_f32 v43, -v17, v27, v43
	v_fma_f32 v28, -v2, v27, v28
	v_fma_f32 v92, -v2, v91, v92
	v_fma_f32 v29, -v3, v27, v29
	v_fma_f32 v93, -v3, v91, v93
	v_fma_f32 v30, -v4, v27, v30
	s_nop 0
	v_fma_f32 v94, -v4, v91, v94
	v_fma_f32 v31, -v5, v27, v31
	v_fma_f32 v95, -v5, v91, v95
	v_fma_f32 v32, -v6, v27, v32
	v_fma_f32 v98, -v6, v91, v98
	s_nop 0
	v_add_u32_e32 v10, s51, v58
	v_fma_f32 v33, -v7, v27, v33
	v_fma_f32 v97, -v7, v91, v97
	v_fma_f32 v34, -v8, v27, v34
	v_fma_f32 v100, -v8, v91, v100
	v_fma_f32 v35, -v9, v27, v35
	v_fma_f32 v99, -v9, v91, v99
	v_fma_f32 v37, -v11, v27, v37
	v_fma_f32 v103, -v11, v91, v103
	v_fma_f32 v38, -v12, v27, v38
	v_fma_f32 v107, -v12, v91, v107
	v_fma_f32 v39, -v13, v27, v39
	v_fma_f32 v106, -v13, v91, v106
	ds_read_b128 v[2:5], v10 offset:8272
	ds_read_b128 v[6:9], v10 offset:8288
	ds_read_b128 v[10:13], v10 offset:8304
	v_mov_b32_e32 v58, 0x200
	v_fma_f32 v40, -v14, v27, v40
	v_fma_f32 v111, -v14, v91, v111
	v_fma_f32 v41, -v15, v27, v41
	v_fma_f32 v110, -v15, v91, v110
	v_fma_f32 v42, -v16, v27, v42
	v_fma_f32 v113, -v16, v91, v113
	v_fma_f32 v112, -v17, v91, v112
	s_nop 0
	v_add_u32_e32 v14, s51, v58
	s_waitcnt lgkmcnt(0)
	v_fma_f32 v46, -v2, v27, v46
	v_fma_f32 v121, -v2, v91, v121
	v_fma_f32 v47, -v3, v27, v47
	v_fma_f32 v120, -v3, v91, v120
	v_fma_f32 v48, -v4, v27, v48
	v_fma_f32 v123, -v4, v91, v123
	v_fma_f32 v49, -v5, v27, v49
	v_fma_f32 v122, -v5, v91, v122
	v_fma_f32 v44, -v6, v27, v44
	v_fma_f32 v74, -v6, v91, v74
	v_fma_f32 v45, -v7, v27, v45
	v_fma_f32 v75, -v7, v91, v75
	v_fma_f32 v50, -v8, v27, v50
	v_fma_f32 v76, -v8, v91, v76
	v_fma_f32 v51, -v9, v27, v51
	v_fma_f32 v77, -v9, v91, v77
	v_fma_f32 v52, -v10, v27, v52
	v_fma_f32 v78, -v10, v91, v78
	v_fma_f32 v53, -v11, v27, v53
	v_fma_f32 v79, -v11, v91, v79
	v_fma_f32 v54, -v12, v27, v54
	v_fma_f32 v105, -v12, v91, v105
	v_fma_f32 v55, -v13, v27, v55
	ds_read_b128 v[2:5], v14 offset:8208
	v_fma_f32 v114, -v13, v91, v114
	ds_read_b128 v[6:9], v14 offset:8224
	ds_read_b128 v[10:13], v14 offset:8240
	ds_read_b128 v[14:17], v14 offset:8256
	s_waitcnt lgkmcnt(0)
	v_fma_f32 v36, -v10, v28, v36
	v_fma_f32 v104, -v10, v92, v104
	v_fma_f32 v43, -v17, v28, v43
	v_fma_f32 v29, -v3, v28, v29
	v_fma_f32 v93, -v3, v92, v93
	v_fma_f32 v30, -v4, v28, v30
	v_fma_f32 v94, -v4, v92, v94
	v_fma_f32 v31, -v5, v28, v31
	s_nop 0
	v_fma_f32 v95, -v5, v92, v95
	v_fma_f32 v32, -v6, v28, v32
	v_fma_f32 v98, -v6, v92, v98
	v_fma_f32 v33, -v7, v28, v33
	v_fma_f32 v97, -v7, v92, v97
	s_nop 0
	v_add_u32_e32 v10, s51, v58
	v_fma_f32 v34, -v8, v28, v34
	v_fma_f32 v100, -v8, v92, v100
	v_fma_f32 v35, -v9, v28, v35
	v_fma_f32 v99, -v9, v92, v99
	v_fma_f32 v37, -v11, v28, v37
	v_fma_f32 v103, -v11, v92, v103
	v_fma_f32 v38, -v12, v28, v38
	v_fma_f32 v107, -v12, v92, v107
	v_fma_f32 v39, -v13, v28, v39
	v_fma_f32 v106, -v13, v92, v106
	ds_read_b128 v[2:5], v10 offset:8272
	ds_read_b128 v[6:9], v10 offset:8288
	ds_read_b128 v[10:13], v10 offset:8304
	v_mov_b32_e32 v58, 0x280
	v_fma_f32 v40, -v14, v28, v40
	v_fma_f32 v111, -v14, v92, v111
	v_fma_f32 v41, -v15, v28, v41
	v_fma_f32 v110, -v15, v92, v110
	v_fma_f32 v42, -v16, v28, v42
	v_fma_f32 v113, -v16, v92, v113
	v_fma_f32 v112, -v17, v92, v112
	s_nop 0
	v_add_u32_e32 v14, s51, v58
	s_waitcnt lgkmcnt(0)
	v_fma_f32 v46, -v2, v28, v46
	v_fma_f32 v121, -v2, v92, v121
	v_fma_f32 v47, -v3, v28, v47
	v_fma_f32 v120, -v3, v92, v120
	v_fma_f32 v48, -v4, v28, v48
	v_fma_f32 v123, -v4, v92, v123
	v_fma_f32 v49, -v5, v28, v49
	v_fma_f32 v122, -v5, v92, v122
	v_fma_f32 v44, -v6, v28, v44
	v_fma_f32 v74, -v6, v92, v74
	v_fma_f32 v45, -v7, v28, v45
	v_fma_f32 v75, -v7, v92, v75
	v_fma_f32 v50, -v8, v28, v50
	v_fma_f32 v76, -v8, v92, v76
	v_fma_f32 v51, -v9, v28, v51
	v_fma_f32 v77, -v9, v92, v77
	v_fma_f32 v52, -v10, v28, v52
	v_fma_f32 v78, -v10, v92, v78
	v_fma_f32 v53, -v11, v28, v53
	v_fma_f32 v79, -v11, v92, v79
	v_fma_f32 v54, -v12, v28, v54
	v_fma_f32 v105, -v12, v92, v105
	v_fma_f32 v55, -v13, v28, v55
	ds_read_b128 v[2:5], v14 offset:8208
	v_fma_f32 v114, -v13, v92, v114
	ds_read_b128 v[6:9], v14 offset:8224
	ds_read_b128 v[10:13], v14 offset:8240
	ds_read_b128 v[14:17], v14 offset:8256
	s_waitcnt lgkmcnt(0)
	v_fma_f32 v36, -v10, v29, v36
	v_fma_f32 v104, -v10, v93, v104
	v_fma_f32 v43, -v17, v29, v43
	v_fma_f32 v30, -v4, v29, v30
	v_fma_f32 v94, -v4, v93, v94
	v_fma_f32 v31, -v5, v29, v31
	v_fma_f32 v95, -v5, v93, v95
	v_fma_f32 v32, -v6, v29, v32
	s_nop 0
	v_fma_f32 v98, -v6, v93, v98
	v_fma_f32 v33, -v7, v29, v33
	v_fma_f32 v97, -v7, v93, v97
	v_fma_f32 v34, -v8, v29, v34
	v_fma_f32 v100, -v8, v93, v100
	s_nop 0
	v_add_u32_e32 v10, s51, v58
	v_fma_f32 v35, -v9, v29, v35
	v_fma_f32 v99, -v9, v93, v99
	v_fma_f32 v37, -v11, v29, v37
	v_fma_f32 v103, -v11, v93, v103
	v_fma_f32 v38, -v12, v29, v38
	v_fma_f32 v107, -v12, v93, v107
	v_fma_f32 v39, -v13, v29, v39
	v_fma_f32 v106, -v13, v93, v106
	ds_read_b128 v[2:5], v10 offset:8272
	ds_read_b128 v[6:9], v10 offset:8288
	ds_read_b128 v[10:13], v10 offset:8304
	v_mov_b32_e32 v58, 0x300
	v_fma_f32 v40, -v14, v29, v40
	v_fma_f32 v111, -v14, v93, v111
	v_fma_f32 v41, -v15, v29, v41
	v_fma_f32 v110, -v15, v93, v110
	v_fma_f32 v42, -v16, v29, v42
	v_fma_f32 v113, -v16, v93, v113
	v_fma_f32 v112, -v17, v93, v112
	s_nop 0
	v_add_u32_e32 v14, s51, v58
	s_waitcnt lgkmcnt(0)
	v_fma_f32 v46, -v2, v29, v46
	v_fma_f32 v121, -v2, v93, v121
	v_fma_f32 v47, -v3, v29, v47
	v_fma_f32 v120, -v3, v93, v120
	v_fma_f32 v48, -v4, v29, v48
	v_fma_f32 v123, -v4, v93, v123
	v_fma_f32 v49, -v5, v29, v49
	v_fma_f32 v122, -v5, v93, v122
	v_fma_f32 v44, -v6, v29, v44
	v_fma_f32 v74, -v6, v93, v74
	v_fma_f32 v45, -v7, v29, v45
	v_fma_f32 v75, -v7, v93, v75
	v_fma_f32 v50, -v8, v29, v50
	v_fma_f32 v76, -v8, v93, v76
	v_fma_f32 v51, -v9, v29, v51
	v_fma_f32 v77, -v9, v93, v77
	v_fma_f32 v52, -v10, v29, v52
	v_fma_f32 v78, -v10, v93, v78
	v_fma_f32 v53, -v11, v29, v53
	v_fma_f32 v79, -v11, v93, v79
	v_fma_f32 v54, -v12, v29, v54
	v_fma_f32 v105, -v12, v93, v105
	v_fma_f32 v55, -v13, v29, v55
	ds_read_b128 v[2:5], v14 offset:8208
	v_fma_f32 v114, -v13, v93, v114
	ds_read_b128 v[6:9], v14 offset:8224
	ds_read_b128 v[10:13], v14 offset:8240
	ds_read_b128 v[14:17], v14 offset:8256
	s_waitcnt lgkmcnt(0)
	v_fma_f32 v36, -v10, v30, v36
	v_fma_f32 v104, -v10, v94, v104
	v_fma_f32 v43, -v17, v30, v43
	v_fma_f32 v31, -v5, v30, v31
	v_fma_f32 v95, -v5, v94, v95
	v_fma_f32 v32, -v6, v30, v32
	v_fma_f32 v98, -v6, v94, v98
	v_fma_f32 v33, -v7, v30, v33
	s_nop 0
	v_fma_f32 v97, -v7, v94, v97
	v_fma_f32 v34, -v8, v30, v34
	v_fma_f32 v100, -v8, v94, v100
	v_fma_f32 v35, -v9, v30, v35
	v_fma_f32 v99, -v9, v94, v99
	s_nop 0
	v_add_u32_e32 v10, s51, v58
	v_fma_f32 v37, -v11, v30, v37
	v_fma_f32 v103, -v11, v94, v103
	v_fma_f32 v38, -v12, v30, v38
	v_fma_f32 v107, -v12, v94, v107
	v_fma_f32 v39, -v13, v30, v39
	v_fma_f32 v106, -v13, v94, v106
	ds_read_b128 v[2:5], v10 offset:8272
	ds_read_b128 v[6:9], v10 offset:8288
	ds_read_b128 v[10:13], v10 offset:8304
	v_mov_b32_e32 v58, 0x380
	v_fma_f32 v40, -v14, v30, v40
	v_fma_f32 v111, -v14, v94, v111
	v_fma_f32 v41, -v15, v30, v41
	v_fma_f32 v110, -v15, v94, v110
	v_fma_f32 v42, -v16, v30, v42
	v_fma_f32 v113, -v16, v94, v113
	v_fma_f32 v112, -v17, v94, v112
	s_nop 0
	v_add_u32_e32 v14, s51, v58
	s_waitcnt lgkmcnt(0)
	v_fma_f32 v46, -v2, v30, v46
	v_fma_f32 v121, -v2, v94, v121
	v_fma_f32 v47, -v3, v30, v47
	v_fma_f32 v120, -v3, v94, v120
	v_fma_f32 v48, -v4, v30, v48
	v_fma_f32 v123, -v4, v94, v123
	v_fma_f32 v49, -v5, v30, v49
	v_fma_f32 v122, -v5, v94, v122
	v_fma_f32 v44, -v6, v30, v44
	v_fma_f32 v74, -v6, v94, v74
	v_fma_f32 v45, -v7, v30, v45
	v_fma_f32 v75, -v7, v94, v75
	v_fma_f32 v50, -v8, v30, v50
	v_fma_f32 v76, -v8, v94, v76
	v_fma_f32 v51, -v9, v30, v51
	v_fma_f32 v77, -v9, v94, v77
	v_fma_f32 v52, -v10, v30, v52
	v_fma_f32 v78, -v10, v94, v78
	v_fma_f32 v53, -v11, v30, v53
	v_fma_f32 v79, -v11, v94, v79
	v_fma_f32 v54, -v12, v30, v54
	v_fma_f32 v105, -v12, v94, v105
	v_fma_f32 v55, -v13, v30, v55
	ds_read_b128 v[2:5], v14 offset:8224
	v_fma_f32 v114, -v13, v94, v114
	ds_read_b128 v[6:9], v14 offset:8240
	ds_read_b128 v[10:13], v14 offset:8256
	ds_read_b128 v[14:17], v14 offset:8272
	s_waitcnt lgkmcnt(0)
	v_fma_f32 v49, -v17, v31, v49
	s_nop 0
	v_fma_f32 v36, -v6, v31, v36
	v_fma_f32 v104, -v6, v95, v104
	v_fma_f32 v32, -v2, v31, v32
	v_fma_f32 v98, -v2, v95, v98
	v_fma_f32 v33, -v3, v31, v33
	s_nop 0
	v_add_u32_e32 v6, s51, v58
	v_mov_b32_e32 v58, 0x400
	v_fma_f32 v97, -v3, v95, v97
	v_fma_f32 v34, -v4, v31, v34
	v_fma_f32 v100, -v4, v95, v100
	v_fma_f32 v35, -v5, v31, v35
	v_fma_f32 v99, -v5, v95, v99
	v_fma_f32 v37, -v7, v31, v37
	v_fma_f32 v103, -v7, v95, v103
	v_fma_f32 v38, -v8, v31, v38
	v_fma_f32 v107, -v8, v95, v107
	v_fma_f32 v39, -v9, v31, v39
	v_fma_f32 v106, -v9, v95, v106
	v_fma_f32 v46, -v14, v31, v46
	v_fma_f32 v121, -v14, v95, v121
	ds_read_b128 v[2:5], v6 offset:8288
	ds_read_b128 v[6:9], v6 offset:8304
	v_fma_f32 v40, -v10, v31, v40
	v_fma_f32 v111, -v10, v95, v111
	v_fma_f32 v41, -v11, v31, v41
	v_fma_f32 v110, -v11, v95, v110
	v_fma_f32 v42, -v12, v31, v42
	s_nop 0
	v_add_u32_e32 v14, s51, v58
	v_fma_f32 v113, -v12, v95, v113
	v_fma_f32 v43, -v13, v31, v43
	v_fma_f32 v112, -v13, v95, v112
	v_fma_f32 v47, -v15, v31, v47
	v_fma_f32 v120, -v15, v95, v120
	v_fma_f32 v48, -v16, v31, v48
	v_fma_f32 v123, -v16, v95, v123
	v_fma_f32 v122, -v17, v95, v122
	s_waitcnt lgkmcnt(0)
	v_fma_f32 v44, -v2, v31, v44
	v_fma_f32 v74, -v2, v95, v74
	v_fma_f32 v45, -v3, v31, v45
	v_fma_f32 v75, -v3, v95, v75
	v_fma_f32 v50, -v4, v31, v50
	v_fma_f32 v76, -v4, v95, v76
	v_fma_f32 v51, -v5, v31, v51
	v_fma_f32 v77, -v5, v95, v77
	v_fma_f32 v52, -v6, v31, v52
	v_fma_f32 v78, -v6, v95, v78
	v_fma_f32 v53, -v7, v31, v53
	v_fma_f32 v79, -v7, v95, v79
	v_fma_f32 v54, -v8, v31, v54
	v_fma_f32 v105, -v8, v95, v105
	v_fma_f32 v55, -v9, v31, v55
	ds_read_b128 v[2:5], v14 offset:8224
	v_fma_f32 v114, -v9, v95, v114
	ds_read_b128 v[6:9], v14 offset:8240
	ds_read_b128 v[10:13], v14 offset:8256
	ds_read_b128 v[14:17], v14 offset:8272
	s_waitcnt lgkmcnt(0)
	v_fma_f32 v49, -v17, v32, v49
	s_nop 0
	v_fma_f32 v36, -v6, v32, v36
	v_fma_f32 v104, -v6, v98, v104
	v_fma_f32 v33, -v3, v32, v33
	v_fma_f32 v97, -v3, v98, v97
	v_fma_f32 v34, -v4, v32, v34
	s_nop 0
	v_add_u32_e32 v6, s51, v58
	v_mov_b32_e32 v58, 0x480
	v_fma_f32 v100, -v4, v98, v100
	v_fma_f32 v35, -v5, v32, v35
	v_fma_f32 v99, -v5, v98, v99
	v_fma_f32 v37, -v7, v32, v37
	v_fma_f32 v103, -v7, v98, v103
	v_fma_f32 v38, -v8, v32, v38
	v_fma_f32 v107, -v8, v98, v107
	v_fma_f32 v39, -v9, v32, v39
	v_fma_f32 v106, -v9, v98, v106
	v_fma_f32 v46, -v14, v32, v46
	v_fma_f32 v121, -v14, v98, v121
	ds_read_b128 v[2:5], v6 offset:8288
	ds_read_b128 v[6:9], v6 offset:8304
	v_fma_f32 v40, -v10, v32, v40
	v_fma_f32 v111, -v10, v98, v111
	v_fma_f32 v41, -v11, v32, v41
	v_fma_f32 v110, -v11, v98, v110
	v_fma_f32 v42, -v12, v32, v42
	s_nop 0
	v_add_u32_e32 v14, s51, v58
	v_fma_f32 v113, -v12, v98, v113
	v_fma_f32 v43, -v13, v32, v43
	v_fma_f32 v112, -v13, v98, v112
	v_fma_f32 v47, -v15, v32, v47
	v_fma_f32 v120, -v15, v98, v120
	v_fma_f32 v48, -v16, v32, v48
	v_fma_f32 v123, -v16, v98, v123
	v_fma_f32 v122, -v17, v98, v122
	s_waitcnt lgkmcnt(0)
	v_fma_f32 v44, -v2, v32, v44
	v_fma_f32 v74, -v2, v98, v74
	v_fma_f32 v45, -v3, v32, v45
	v_fma_f32 v75, -v3, v98, v75
	v_fma_f32 v50, -v4, v32, v50
	v_fma_f32 v76, -v4, v98, v76
	v_fma_f32 v51, -v5, v32, v51
	v_fma_f32 v77, -v5, v98, v77
	v_fma_f32 v52, -v6, v32, v52
	v_fma_f32 v78, -v6, v98, v78
	v_fma_f32 v53, -v7, v32, v53
	v_fma_f32 v79, -v7, v98, v79
	v_fma_f32 v54, -v8, v32, v54
	v_fma_f32 v105, -v8, v98, v105
	v_fma_f32 v55, -v9, v32, v55
	ds_read_b128 v[2:5], v14 offset:8224
	v_fma_f32 v114, -v9, v98, v114
	ds_read_b128 v[6:9], v14 offset:8240
	ds_read_b128 v[10:13], v14 offset:8256
	ds_read_b128 v[14:17], v14 offset:8272
	s_waitcnt lgkmcnt(0)
	v_fma_f32 v49, -v17, v33, v49
	s_nop 0
	v_fma_f32 v36, -v6, v33, v36
	v_fma_f32 v104, -v6, v97, v104
	v_fma_f32 v34, -v4, v33, v34
	v_fma_f32 v100, -v4, v97, v100
	v_fma_f32 v35, -v5, v33, v35
	s_nop 0
	v_add_u32_e32 v6, s51, v58
	v_mov_b32_e32 v58, 0x500
	v_fma_f32 v99, -v5, v97, v99
	v_fma_f32 v37, -v7, v33, v37
	v_fma_f32 v103, -v7, v97, v103
	v_fma_f32 v38, -v8, v33, v38
	v_fma_f32 v107, -v8, v97, v107
	v_fma_f32 v39, -v9, v33, v39
	v_fma_f32 v106, -v9, v97, v106
	v_fma_f32 v46, -v14, v33, v46
	v_fma_f32 v121, -v14, v97, v121
	ds_read_b128 v[2:5], v6 offset:8288
	ds_read_b128 v[6:9], v6 offset:8304
	v_fma_f32 v40, -v10, v33, v40
	v_fma_f32 v111, -v10, v97, v111
	v_fma_f32 v41, -v11, v33, v41
	v_fma_f32 v110, -v11, v97, v110
	v_fma_f32 v42, -v12, v33, v42
	s_nop 0
	v_add_u32_e32 v14, s51, v58
	v_fma_f32 v113, -v12, v97, v113
	v_fma_f32 v43, -v13, v33, v43
	v_fma_f32 v112, -v13, v97, v112
	v_fma_f32 v47, -v15, v33, v47
	v_fma_f32 v120, -v15, v97, v120
	v_fma_f32 v48, -v16, v33, v48
	v_fma_f32 v123, -v16, v97, v123
	v_fma_f32 v122, -v17, v97, v122
	s_waitcnt lgkmcnt(0)
	v_fma_f32 v44, -v2, v33, v44
	v_fma_f32 v74, -v2, v97, v74
	v_fma_f32 v45, -v3, v33, v45
	v_fma_f32 v75, -v3, v97, v75
	v_fma_f32 v50, -v4, v33, v50
	v_fma_f32 v76, -v4, v97, v76
	v_fma_f32 v51, -v5, v33, v51
	v_fma_f32 v77, -v5, v97, v77
	v_fma_f32 v52, -v6, v33, v52
	v_fma_f32 v78, -v6, v97, v78
	v_fma_f32 v53, -v7, v33, v53
	v_fma_f32 v79, -v7, v97, v79
	v_fma_f32 v54, -v8, v33, v54
	v_fma_f32 v105, -v8, v97, v105
	v_fma_f32 v55, -v9, v33, v55
	ds_read_b128 v[2:5], v14 offset:8224
	v_fma_f32 v114, -v9, v97, v114
	ds_read_b128 v[6:9], v14 offset:8240
	ds_read_b128 v[10:13], v14 offset:8256
	ds_read_b128 v[14:17], v14 offset:8272
	s_waitcnt lgkmcnt(0)
	v_fma_f32 v49, -v17, v34, v49
	s_nop 0
	v_fma_f32 v36, -v6, v34, v36
	v_fma_f32 v104, -v6, v100, v104
	v_fma_f32 v35, -v5, v34, v35
	v_fma_f32 v99, -v5, v100, v99
	v_fma_f32 v37, -v7, v34, v37
	s_nop 0
	v_add_u32_e32 v6, s51, v58
	v_mov_b32_e32 v58, 0x580
	v_fma_f32 v103, -v7, v100, v103
	v_fma_f32 v38, -v8, v34, v38
	v_fma_f32 v107, -v8, v100, v107
	v_fma_f32 v39, -v9, v34, v39
	v_fma_f32 v106, -v9, v100, v106
	v_fma_f32 v46, -v14, v34, v46
	v_fma_f32 v121, -v14, v100, v121
	ds_read_b128 v[2:5], v6 offset:8288
	ds_read_b128 v[6:9], v6 offset:8304
	v_fma_f32 v40, -v10, v34, v40
	v_fma_f32 v111, -v10, v100, v111
	v_fma_f32 v41, -v11, v34, v41
	v_fma_f32 v110, -v11, v100, v110
	v_fma_f32 v42, -v12, v34, v42
	s_nop 0
	v_add_u32_e32 v14, s51, v58
	v_fma_f32 v113, -v12, v100, v113
	v_fma_f32 v43, -v13, v34, v43
	v_fma_f32 v112, -v13, v100, v112
	v_fma_f32 v47, -v15, v34, v47
	v_fma_f32 v120, -v15, v100, v120
	v_fma_f32 v48, -v16, v34, v48
	v_fma_f32 v123, -v16, v100, v123
	v_fma_f32 v122, -v17, v100, v122
	s_waitcnt lgkmcnt(0)
	v_fma_f32 v44, -v2, v34, v44
	v_fma_f32 v74, -v2, v100, v74
	v_fma_f32 v45, -v3, v34, v45
	v_fma_f32 v75, -v3, v100, v75
	v_fma_f32 v50, -v4, v34, v50
	v_fma_f32 v76, -v4, v100, v76
	v_fma_f32 v51, -v5, v34, v51
	v_fma_f32 v77, -v5, v100, v77
	v_fma_f32 v52, -v6, v34, v52
	v_fma_f32 v78, -v6, v100, v78
	v_fma_f32 v53, -v7, v34, v53
	v_fma_f32 v79, -v7, v100, v79
	v_fma_f32 v54, -v8, v34, v54
	v_fma_f32 v105, -v8, v100, v105
	v_fma_f32 v55, -v9, v34, v55
	ds_read_b128 v[2:5], v14 offset:8240
	v_fma_f32 v114, -v9, v100, v114
	ds_read_b128 v[6:9], v14 offset:8256
	ds_read_b128 v[10:13], v14 offset:8272
	ds_read_b128 v[14:17], v14 offset:8288
	s_waitcnt lgkmcnt(0)
	v_fma_f32 v51, -v17, v35, v51
	s_nop 0
	v_fma_f32 v36, -v2, v35, v36
	v_fma_f32 v104, -v2, v99, v104
	v_fma_f32 v37, -v3, v35, v37
	v_fma_f32 v103, -v3, v99, v103
	v_fma_f32 v38, -v4, v35, v38
	s_nop 0
	v_add_u32_e32 v2, s51, v58
	v_mov_b32_e32 v58, 0x600
	v_fma_f32 v107, -v4, v99, v107
	v_fma_f32 v39, -v5, v35, v39
	v_fma_f32 v106, -v5, v99, v106
	v_fma_f32 v44, -v14, v35, v44
	v_fma_f32 v74, -v14, v99, v74
	ds_read_b128 v[2:5], v2 offset:8304
	v_fma_f32 v40, -v6, v35, v40
	v_fma_f32 v111, -v6, v99, v111
	v_fma_f32 v41, -v7, v35, v41
	v_fma_f32 v110, -v7, v99, v110
	v_fma_f32 v42, -v8, v35, v42
	s_nop 0
	v_add_u32_e32 v14, s51, v58
	v_fma_f32 v113, -v8, v99, v113
	v_fma_f32 v43, -v9, v35, v43
	v_fma_f32 v112, -v9, v99, v112
	v_fma_f32 v46, -v10, v35, v46
	v_fma_f32 v121, -v10, v99, v121
	v_fma_f32 v47, -v11, v35, v47
	v_fma_f32 v120, -v11, v99, v120
	v_fma_f32 v48, -v12, v35, v48
	v_fma_f32 v123, -v12, v99, v123
	v_fma_f32 v49, -v13, v35, v49
	v_fma_f32 v122, -v13, v99, v122
	v_fma_f32 v45, -v15, v35, v45
	v_fma_f32 v75, -v15, v99, v75
	v_fma_f32 v50, -v16, v35, v50
	v_fma_f32 v76, -v16, v99, v76
	v_fma_f32 v77, -v17, v99, v77
	s_waitcnt lgkmcnt(0)
	v_fma_f32 v52, -v2, v35, v52
	v_fma_f32 v78, -v2, v99, v78
	v_fma_f32 v53, -v3, v35, v53
	v_fma_f32 v79, -v3, v99, v79
	v_fma_f32 v54, -v4, v35, v54
	v_fma_f32 v105, -v4, v99, v105
	v_fma_f32 v55, -v5, v35, v55
	ds_read_b128 v[6:9], v14 offset:8240
	v_fma_f32 v114, -v5, v99, v114
	ds_read_b128 v[2:5], v14 offset:8256
	ds_read_b128 v[10:13], v14 offset:8272
	ds_read_b128 v[14:17], v14 offset:8288
	s_waitcnt lgkmcnt(0)
	v_fma_f32 v51, -v17, v36, v51
	s_nop 0
	v_fma_f32 v40, -v2, v36, v40
	v_fma_f32 v111, -v2, v104, v111
	v_fma_f32 v37, -v7, v36, v37
	v_fma_f32 v103, -v7, v104, v103
	v_fma_f32 v41, -v3, v36, v41
	s_nop 0
	v_add_u32_e32 v2, s51, v58
	v_mov_b32_e32 v58, 0x680
	v_fma_f32 v110, -v3, v104, v110
	v_fma_f32 v42, -v4, v36, v42
	v_fma_f32 v113, -v4, v104, v113
	v_fma_f32 v43, -v5, v36, v43
	v_fma_f32 v112, -v5, v104, v112
	v_fma_f32 v44, -v14, v36, v44
	v_fma_f32 v74, -v14, v104, v74
	ds_read_b128 v[2:5], v2 offset:8304
	v_fma_f32 v38, -v8, v36, v38
	v_fma_f32 v107, -v8, v104, v107
	v_fma_f32 v39, -v9, v36, v39
	v_fma_f32 v106, -v9, v104, v106
	v_fma_f32 v46, -v10, v36, v46
	s_nop 0
	v_add_u32_e32 v14, s51, v58
	v_fma_f32 v121, -v10, v104, v121
	v_fma_f32 v47, -v11, v36, v47
	v_fma_f32 v120, -v11, v104, v120
	v_fma_f32 v48, -v12, v36, v48
	v_fma_f32 v123, -v12, v104, v123
	v_fma_f32 v49, -v13, v36, v49
	v_fma_f32 v122, -v13, v104, v122
	v_fma_f32 v45, -v15, v36, v45
	v_fma_f32 v75, -v15, v104, v75
	v_fma_f32 v50, -v16, v36, v50
	v_fma_f32 v76, -v16, v104, v76
	v_fma_f32 v77, -v17, v104, v77
	s_waitcnt lgkmcnt(0)
	v_fma_f32 v52, -v2, v36, v52
	v_fma_f32 v78, -v2, v104, v78
	v_fma_f32 v53, -v3, v36, v53
	v_fma_f32 v79, -v3, v104, v79
	v_fma_f32 v54, -v4, v36, v54
	v_fma_f32 v105, -v4, v104, v105
	v_fma_f32 v55, -v5, v36, v55
	ds_read_b128 v[6:9], v14 offset:8240
	v_fma_f32 v114, -v5, v104, v114
	ds_read_b128 v[2:5], v14 offset:8256
	ds_read_b128 v[10:13], v14 offset:8272
	ds_read_b128 v[14:17], v14 offset:8288
	s_waitcnt lgkmcnt(0)
	v_fma_f32 v51, -v17, v37, v51
	s_nop 0
	v_fma_f32 v40, -v2, v37, v40
	v_fma_f32 v111, -v2, v103, v111
	v_fma_f32 v38, -v8, v37, v38
	v_fma_f32 v107, -v8, v103, v107
	v_fma_f32 v41, -v3, v37, v41
	s_nop 0
	v_add_u32_e32 v2, s51, v58
	v_mov_b32_e32 v58, 0x700
	v_fma_f32 v110, -v3, v103, v110
	v_fma_f32 v42, -v4, v37, v42
	v_fma_f32 v113, -v4, v103, v113
	v_fma_f32 v43, -v5, v37, v43
	v_fma_f32 v112, -v5, v103, v112
	v_fma_f32 v44, -v14, v37, v44
	v_fma_f32 v74, -v14, v103, v74
	ds_read_b128 v[2:5], v2 offset:8304
	v_fma_f32 v39, -v9, v37, v39
	v_fma_f32 v106, -v9, v103, v106
	v_fma_f32 v46, -v10, v37, v46
	v_fma_f32 v121, -v10, v103, v121
	v_fma_f32 v47, -v11, v37, v47
	s_nop 0
	v_add_u32_e32 v14, s51, v58
	v_fma_f32 v120, -v11, v103, v120
	v_fma_f32 v48, -v12, v37, v48
	v_fma_f32 v123, -v12, v103, v123
	v_fma_f32 v49, -v13, v37, v49
	v_fma_f32 v122, -v13, v103, v122
	v_fma_f32 v45, -v15, v37, v45
	v_fma_f32 v75, -v15, v103, v75
	v_fma_f32 v50, -v16, v37, v50
	v_fma_f32 v76, -v16, v103, v76
	v_fma_f32 v77, -v17, v103, v77
	s_waitcnt lgkmcnt(0)
	v_fma_f32 v52, -v2, v37, v52
	v_fma_f32 v78, -v2, v103, v78
	v_fma_f32 v53, -v3, v37, v53
	v_fma_f32 v79, -v3, v103, v79
	v_fma_f32 v54, -v4, v37, v54
	v_fma_f32 v105, -v4, v103, v105
	v_fma_f32 v55, -v5, v37, v55
	ds_read_b128 v[6:9], v14 offset:8240
	v_fma_f32 v114, -v5, v103, v114
	ds_read_b128 v[2:5], v14 offset:8256
	ds_read_b128 v[10:13], v14 offset:8272
	ds_read_b128 v[14:17], v14 offset:8288
	s_waitcnt lgkmcnt(0)
	v_fma_f32 v40, -v2, v38, v40
	v_fma_f32 v111, -v2, v107, v111
	v_fma_f32 v51, -v17, v38, v51
	v_fma_f32 v41, -v3, v38, v41
	v_fma_f32 v110, -v3, v107, v110
	v_fma_f32 v42, -v4, v38, v42
	v_fma_f32 v113, -v4, v107, v113
	v_fma_f32 v43, -v5, v38, v43
	s_nop 0
	v_fma_f32 v112, -v5, v107, v112
	v_fma_f32 v39, -v9, v38, v39
	v_fma_f32 v106, -v9, v107, v106
	v_fma_f32 v44, -v14, v38, v44
	v_fma_f32 v74, -v14, v107, v74
	s_nop 0
	v_add_u32_e32 v2, s51, v58
	ds_read_b128 v[2:5], v2 offset:8304
	s_waitcnt lgkmcnt(0)
	v_fma_f32 v52, -v2, v38, v52
	v_fma_f32 v78, -v2, v107, v78
	v_mov_b32_e32 v2, 0x780
	v_fma_f32 v46, -v10, v38, v46
	v_fma_f32 v121, -v10, v107, v121
	v_fma_f32 v47, -v11, v38, v47
	v_fma_f32 v120, -v11, v107, v120
	v_fma_f32 v48, -v12, v38, v48
	s_nop 0
	v_add_u32_e32 v14, s51, v2
	v_fma_f32 v123, -v12, v107, v123
	v_fma_f32 v49, -v13, v38, v49
	v_fma_f32 v122, -v13, v107, v122
	v_fma_f32 v45, -v15, v38, v45
	v_fma_f32 v75, -v15, v107, v75
	v_fma_f32 v50, -v16, v38, v50
	v_fma_f32 v76, -v16, v107, v76
	v_fma_f32 v77, -v17, v107, v77
	v_fma_f32 v53, -v3, v38, v53
	v_fma_f32 v79, -v3, v107, v79
	v_fma_f32 v54, -v4, v38, v54
	v_fma_f32 v105, -v4, v107, v105
	v_fma_f32 v55, -v5, v38, v55
	ds_read_b128 v[6:9], v14 offset:8256
	v_fma_f32 v114, -v5, v107, v114
	ds_read_b128 v[2:5], v14 offset:8272
	ds_read_b128 v[10:13], v14 offset:8288
	ds_read_b128 v[14:17], v14 offset:8304
	s_waitcnt lgkmcnt(0)
	v_fma_f32 v46, -v2, v39, v46
	v_fma_f32 v121, -v2, v106, v121
	v_mov_b32_e32 v2, 0x800
	v_fma_f32 v40, -v6, v39, v40
	v_fma_f32 v111, -v6, v106, v111
	v_fma_f32 v52, -v14, v39, v52
	v_fma_f32 v78, -v14, v106, v78
	v_fma_f32 v41, -v7, v39, v41
	v_fma_f32 v110, -v7, v106, v110
	v_fma_f32 v42, -v8, v39, v42
	s_nop 0
	v_fma_f32 v113, -v8, v106, v113
	v_fma_f32 v43, -v9, v39, v43
	v_fma_f32 v112, -v9, v106, v112
	v_fma_f32 v47, -v3, v39, v47
	v_fma_f32 v120, -v3, v106, v120
	s_nop 0
	v_add_u32_e32 v14, s51, v2
	v_fma_f32 v48, -v4, v39, v48
	v_fma_f32 v123, -v4, v106, v123
	v_fma_f32 v49, -v5, v39, v49
	v_fma_f32 v122, -v5, v106, v122
	v_fma_f32 v44, -v10, v39, v44
	v_fma_f32 v74, -v10, v106, v74
	v_fma_f32 v45, -v11, v39, v45
	v_fma_f32 v75, -v11, v106, v75
	v_fma_f32 v50, -v12, v39, v50
	v_fma_f32 v76, -v12, v106, v76
	v_fma_f32 v51, -v13, v39, v51
	v_fma_f32 v77, -v13, v106, v77
	v_fma_f32 v53, -v15, v39, v53
	v_fma_f32 v79, -v15, v106, v79
	v_fma_f32 v54, -v16, v39, v54
	v_fma_f32 v105, -v16, v106, v105
	v_fma_f32 v55, -v17, v39, v55
	ds_read_b128 v[2:5], v14 offset:8256
	v_fma_f32 v114, -v17, v106, v114
	ds_read_b128 v[6:9], v14 offset:8272
	ds_read_b128 v[10:13], v14 offset:8288
	ds_read_b128 v[14:17], v14 offset:8304
	s_waitcnt lgkmcnt(0)
	v_mov_b32_e32 v2, 0x880
	v_fma_f32 v41, -v3, v40, v41
	v_fma_f32 v110, -v3, v111, v110
	v_fma_f32 v52, -v14, v40, v52
	v_fma_f32 v78, -v14, v111, v78
	s_nop 0
	v_fma_f32 v42, -v4, v40, v42
	v_fma_f32 v113, -v4, v111, v113
	v_fma_f32 v43, -v5, v40, v43
	v_fma_f32 v112, -v5, v111, v112
	v_fma_f32 v46, -v6, v40, v46
	s_nop 0
	v_add_u32_e32 v14, s51, v2
	v_fma_f32 v121, -v6, v111, v121
	v_fma_f32 v47, -v7, v40, v47
	v_fma_f32 v120, -v7, v111, v120
	v_fma_f32 v48, -v8, v40, v48
	v_fma_f32 v123, -v8, v111, v123
	v_fma_f32 v49, -v9, v40, v49
	v_fma_f32 v122, -v9, v111, v122
	v_fma_f32 v44, -v10, v40, v44
	v_fma_f32 v74, -v10, v111, v74
	v_fma_f32 v45, -v11, v40, v45
	v_fma_f32 v75, -v11, v111, v75
	v_fma_f32 v50, -v12, v40, v50
	v_fma_f32 v76, -v12, v111, v76
	v_fma_f32 v51, -v13, v40, v51
	v_fma_f32 v77, -v13, v111, v77
	v_fma_f32 v53, -v15, v40, v53
	v_fma_f32 v79, -v15, v111, v79
	v_fma_f32 v54, -v16, v40, v54
	v_fma_f32 v105, -v16, v111, v105
	v_fma_f32 v55, -v17, v40, v55
	ds_read_b128 v[2:5], v14 offset:8256
	v_fma_f32 v114, -v17, v111, v114
	ds_read_b128 v[6:9], v14 offset:8272
	ds_read_b128 v[10:13], v14 offset:8288
	ds_read_b128 v[14:17], v14 offset:8304
	s_waitcnt lgkmcnt(0)
	v_mov_b32_e32 v2, 0x900
	v_fma_f32 v42, -v4, v41, v42
	v_fma_f32 v113, -v4, v110, v113
	v_fma_f32 v52, -v14, v41, v52
	v_fma_f32 v78, -v14, v110, v78
	s_nop 0
	v_fma_f32 v43, -v5, v41, v43
	v_fma_f32 v112, -v5, v110, v112
	v_fma_f32 v46, -v6, v41, v46
	v_fma_f32 v121, -v6, v110, v121
	v_fma_f32 v47, -v7, v41, v47
	s_nop 0
	v_add_u32_e32 v14, s51, v2
	v_fma_f32 v120, -v7, v110, v120
	v_fma_f32 v48, -v8, v41, v48
	v_fma_f32 v123, -v8, v110, v123
	v_fma_f32 v49, -v9, v41, v49
	v_fma_f32 v122, -v9, v110, v122
	v_fma_f32 v44, -v10, v41, v44
	v_fma_f32 v74, -v10, v110, v74
	v_fma_f32 v45, -v11, v41, v45
	v_fma_f32 v75, -v11, v110, v75
	v_fma_f32 v50, -v12, v41, v50
	v_fma_f32 v76, -v12, v110, v76
	v_fma_f32 v51, -v13, v41, v51
	v_fma_f32 v77, -v13, v110, v77
	v_fma_f32 v53, -v15, v41, v53
	v_fma_f32 v79, -v15, v110, v79
	v_fma_f32 v54, -v16, v41, v54
	v_fma_f32 v105, -v16, v110, v105
	v_fma_f32 v55, -v17, v41, v55
	ds_read_b128 v[2:5], v14 offset:8256
	v_fma_f32 v114, -v17, v110, v114
	ds_read_b128 v[6:9], v14 offset:8272
	ds_read_b128 v[10:13], v14 offset:8288
	ds_read_b128 v[14:17], v14 offset:8304
	s_waitcnt lgkmcnt(0)
	v_mov_b32_e32 v2, 0x980
	v_fma_f32 v43, -v5, v42, v43
	v_fma_f32 v112, -v5, v113, v112
	v_fma_f32 v44, -v10, v42, v44
	v_fma_f32 v74, -v10, v113, v74
	v_fma_f32 v46, -v6, v42, v46
	v_fma_f32 v121, -v6, v113, v121
	v_fma_f32 v47, -v7, v42, v47
	s_nop 0
	v_fma_f32 v120, -v7, v113, v120
	v_fma_f32 v48, -v8, v42, v48
	v_fma_f32 v123, -v8, v113, v123
	v_fma_f32 v49, -v9, v42, v49
	v_fma_f32 v122, -v9, v113, v122
	s_nop 0
	v_add_u32_e32 v10, s51, v2
	v_fma_f32 v45, -v11, v42, v45
	v_fma_f32 v75, -v11, v113, v75
	v_fma_f32 v50, -v12, v42, v50
	v_fma_f32 v76, -v12, v113, v76
	v_fma_f32 v51, -v13, v42, v51
	v_fma_f32 v77, -v13, v113, v77
	ds_read_b128 v[2:5], v10 offset:8272
	ds_read_b128 v[6:9], v10 offset:8288
	ds_read_b128 v[10:13], v10 offset:8304
	v_fma_f32 v52, -v14, v42, v52
	v_fma_f32 v78, -v14, v113, v78
	s_waitcnt lgkmcnt(0)
	v_fma_f32 v46, -v2, v43, v46
	v_fma_f32 v121, -v2, v112, v121
	v_mov_b32_e32 v2, 0xa00
	v_fma_f32 v53, -v15, v42, v53
	v_fma_f32 v79, -v15, v113, v79
	v_fma_f32 v54, -v16, v42, v54
	v_fma_f32 v105, -v16, v113, v105
	v_fma_f32 v55, -v17, v42, v55
	v_fma_f32 v114, -v17, v113, v114
	v_fma_f32 v52, -v10, v43, v52
	v_fma_f32 v78, -v10, v112, v78
	v_fma_f32 v47, -v3, v43, v47
	v_fma_f32 v120, -v3, v112, v120
	v_fma_f32 v48, -v4, v43, v48
	v_fma_f32 v123, -v4, v112, v123
	v_fma_f32 v49, -v5, v43, v49
	s_nop 0
	v_add_u32_e32 v10, s51, v2
	v_fma_f32 v122, -v5, v112, v122
	v_fma_f32 v44, -v6, v43, v44
	v_fma_f32 v74, -v6, v112, v74
	v_fma_f32 v45, -v7, v43, v45
	v_fma_f32 v75, -v7, v112, v75
	v_fma_f32 v50, -v8, v43, v50
	v_fma_f32 v76, -v8, v112, v76
	v_fma_f32 v51, -v9, v43, v51
	v_fma_f32 v77, -v9, v112, v77
	v_fma_f32 v53, -v11, v43, v53
	v_fma_f32 v79, -v11, v112, v79
	v_fma_f32 v54, -v12, v43, v54
	v_fma_f32 v105, -v12, v112, v105
	ds_read_b128 v[2:5], v10 offset:8272
	v_fma_f32 v55, -v13, v43, v55
	v_fma_f32 v114, -v13, v112, v114
	ds_read_b128 v[6:9], v10 offset:8288
	ds_read_b128 v[10:13], v10 offset:8304
	s_waitcnt lgkmcnt(0)
	v_mov_b32_e32 v2, 0xa80
	v_fma_f32 v47, -v3, v46, v47
	v_fma_f32 v120, -v3, v121, v120
	v_fma_f32 v52, -v10, v46, v52
	v_fma_f32 v78, -v10, v121, v78
	s_nop 0
	v_fma_f32 v48, -v4, v46, v48
	v_fma_f32 v123, -v4, v121, v123
	v_fma_f32 v49, -v5, v46, v49
	v_fma_f32 v122, -v5, v121, v122
	v_fma_f32 v44, -v6, v46, v44
	s_nop 0
	v_add_u32_e32 v10, s51, v2
	v_fma_f32 v74, -v6, v121, v74
	v_fma_f32 v45, -v7, v46, v45
	v_fma_f32 v75, -v7, v121, v75
	v_fma_f32 v50, -v8, v46, v50
	v_fma_f32 v76, -v8, v121, v76
	v_fma_f32 v51, -v9, v46, v51
	v_fma_f32 v77, -v9, v121, v77
	v_fma_f32 v53, -v11, v46, v53
	v_fma_f32 v79, -v11, v121, v79
	v_fma_f32 v54, -v12, v46, v54
	v_fma_f32 v105, -v12, v121, v105
	ds_read_b128 v[2:5], v10 offset:8272
	v_fma_f32 v55, -v13, v46, v55
	v_fma_f32 v114, -v13, v121, v114
	ds_read_b128 v[6:9], v10 offset:8288
	ds_read_b128 v[10:13], v10 offset:8304
	s_waitcnt lgkmcnt(0)
	v_mov_b32_e32 v2, 0xb00
	v_fma_f32 v48, -v4, v47, v48
	v_fma_f32 v123, -v4, v120, v123
	v_fma_f32 v52, -v10, v47, v52
	v_fma_f32 v78, -v10, v120, v78
	s_nop 0
	v_fma_f32 v49, -v5, v47, v49
	v_fma_f32 v122, -v5, v120, v122
	v_fma_f32 v44, -v6, v47, v44
	v_fma_f32 v74, -v6, v120, v74
	v_fma_f32 v45, -v7, v47, v45
	s_nop 0
	v_add_u32_e32 v10, s51, v2
	ds_read_b128 v[2:5], v10 offset:8272
	v_fma_f32 v75, -v7, v120, v75
	v_fma_f32 v50, -v8, v47, v50
	v_fma_f32 v76, -v8, v120, v76
	v_fma_f32 v51, -v9, v47, v51
	v_fma_f32 v77, -v9, v120, v77
	ds_read_b128 v[6:9], v10 offset:8288
	s_waitcnt lgkmcnt(0)
	v_mov_b32_e32 v2, 0xb80
	v_fma_f32 v53, -v11, v47, v53
	v_fma_f32 v79, -v11, v120, v79
	v_fma_f32 v54, -v12, v47, v54
	v_fma_f32 v105, -v12, v120, v105
	v_fma_f32 v55, -v13, v47, v55
	v_fma_f32 v114, -v13, v120, v114
	ds_read_b128 v[10:13], v10 offset:8304
	v_fma_f32 v49, -v5, v48, v49
	v_fma_f32 v122, -v5, v123, v122
	v_fma_f32 v44, -v6, v48, v44
	v_fma_f32 v74, -v6, v123, v74
	v_fma_f32 v45, -v7, v48, v45
	v_fma_f32 v75, -v7, v123, v75
	v_fma_f32 v50, -v8, v48, v50
	s_nop 0
	v_fma_f32 v76, -v8, v123, v76
	v_fma_f32 v51, -v9, v48, v51
	v_fma_f32 v77, -v9, v123, v77
	s_waitcnt lgkmcnt(0)
	v_fma_f32 v52, -v10, v48, v52
	v_fma_f32 v78, -v10, v123, v78
	v_add_u32_e32 v6, s51, v2
	ds_read_b128 v[2:5], v6 offset:8288
	ds_read_b128 v[6:9], v6 offset:8304
	s_waitcnt lgkmcnt(0)
	v_fma_f32 v44, -v2, v49, v44
	v_fma_f32 v74, -v2, v122, v74
	v_mov_b32_e32 v2, 0xc00
	v_fma_f32 v52, -v6, v49, v52
	v_fma_f32 v78, -v6, v122, v78
	v_fma_f32 v53, -v11, v48, v53
	v_fma_f32 v79, -v11, v123, v79
	v_fma_f32 v54, -v12, v48, v54
	v_fma_f32 v105, -v12, v123, v105
	v_fma_f32 v55, -v13, v48, v55
	s_nop 0
	v_add_u32_e32 v6, s51, v2
	v_fma_f32 v114, -v13, v123, v114
	v_fma_f32 v45, -v3, v49, v45
	v_fma_f32 v75, -v3, v122, v75
	v_fma_f32 v50, -v4, v49, v50
	v_fma_f32 v76, -v4, v122, v76
	v_fma_f32 v51, -v5, v49, v51
	v_fma_f32 v77, -v5, v122, v77
	ds_read_b128 v[2:5], v6 offset:8288
	v_fma_f32 v53, -v7, v49, v53
	v_fma_f32 v79, -v7, v122, v79
	v_fma_f32 v54, -v8, v49, v54
	v_fma_f32 v105, -v8, v122, v105
	v_fma_f32 v55, -v9, v49, v55
	v_fma_f32 v114, -v9, v122, v114
	ds_read_b128 v[6:9], v6 offset:8304
	s_waitcnt lgkmcnt(0)
	v_mov_b32_e32 v2, 0xc80
	v_fma_f32 v45, -v3, v44, v45
	v_fma_f32 v75, -v3, v74, v75
	v_fma_f32 v52, -v6, v44, v52
	v_fma_f32 v78, -v6, v74, v78
	v_fma_f32 v50, -v4, v44, v50
	v_fma_f32 v76, -v4, v74, v76
	v_fma_f32 v51, -v5, v44, v51
	s_nop 0
	v_fma_f32 v77, -v5, v74, v77
	v_fma_f32 v53, -v7, v44, v53
	v_fma_f32 v79, -v7, v74, v79
	v_fma_f32 v54, -v8, v44, v54
	v_fma_f32 v105, -v8, v74, v105
	s_nop 0
	v_add_u32_e32 v6, s51, v2
	ds_read_b128 v[2:5], v6 offset:8288
	v_fma_f32 v55, -v9, v44, v55
	v_fma_f32 v114, -v9, v74, v114
	ds_read_b128 v[6:9], v6 offset:8304
	s_waitcnt lgkmcnt(0)
	v_mov_b32_e32 v2, 0xd00
	v_fma_f32 v50, -v4, v45, v50
	v_fma_f32 v76, -v4, v75, v76
	v_fma_f32 v52, -v6, v45, v52
	v_fma_f32 v78, -v6, v75, v78
	v_fma_f32 v51, -v5, v45, v51
	v_fma_f32 v77, -v5, v75, v77
	v_fma_f32 v53, -v7, v45, v53
	s_nop 0
	v_fma_f32 v79, -v7, v75, v79
	v_fma_f32 v54, -v8, v45, v54
	v_fma_f32 v105, -v8, v75, v105
	v_fma_f32 v55, -v9, v45, v55
	v_fma_f32 v114, -v9, v75, v114
	s_nop 0
	v_add_u32_e32 v6, s51, v2
	ds_read_b128 v[2:5], v6 offset:8288
	ds_read_b128 v[10:13], v6 offset:8304
	s_waitcnt lgkmcnt(0)
	v_mov_b32_e32 v2, 0xd80
	v_fma_f32 v51, -v5, v50, v51
	v_fma_f32 v77, -v5, v76, v77
	v_fma_f32 v52, -v10, v50, v52
	v_fma_f32 v78, -v10, v76, v78
	v_fma_f32 v53, -v11, v50, v53
	v_fma_f32 v79, -v11, v76, v79
	v_fma_f32 v54, -v12, v50, v54
	s_nop 0
	v_fma_f32 v105, -v12, v76, v105
	v_fma_f32 v55, -v13, v50, v55
	v_fma_f32 v114, -v13, v76, v114
	s_nop 0
	v_add_u32_e32 v2, s51, v2
	ds_read_b128 v[2:5], v2 offset:8304
	s_waitcnt lgkmcnt(0)
	v_fma_f32 v52, -v2, v51, v52
	v_fma_f32 v78, -v2, v77, v78
	v_mov_b32_e32 v2, 0xe00
	v_fma_f32 v53, -v3, v51, v53
	v_fma_f32 v79, -v3, v77, v79
	v_fma_f32 v54, -v4, v51, v54
	v_fma_f32 v105, -v4, v77, v105
	v_fma_f32 v55, -v5, v51, v55
	s_nop 0
	v_add_u32_e32 v2, s51, v2
	ds_read_b128 v[6:9], v2 offset:8304
	v_mov_b32_e32 v2, 0xe80
	s_waitcnt lgkmcnt(0)
; __global__ void __launch_bounds__(NWAVES * 64, 2) mega_fwd(Args args) {
;     ...
;     for (int unit = gw; unit < NB * NH * gdn::NCH; unit += NGW) gdn::pre_unit(unit, P, (const unsigned short*)(ws + WS_PB), in[14], in[15], in[16], REC, L + RING_OFF + wave * 16384, lane);
	v_fma_f32 v53, -v7, v52, v53
	v_fma_f32 v79, -v7, v78, v79
	v_fma_f32 v54, -v8, v52, v54
	v_fma_f32 v105, -v8, v78, v105
	v_fma_f32 v114, -v5, v77, v114
	v_fma_f32 v55, -v9, v52, v55
	v_add_u32_e32 v8, s51, v56
	v_fma_f32 v114, -v9, v78, v114
	s_nop 0
	v_add_u32_e32 v2, s51, v2
	ds_read_b128 v[10:13], v2 offset:8304
	v_mov_b32_e32 v2, 0xf00
	s_waitcnt lgkmcnt(0)
	v_fma_f32 v54, -v12, v53, v54
	v_fma_f32 v105, -v12, v79, v105
	v_fma_f32 v55, -v13, v53, v55
	v_fma_f32 v114, -v13, v79, v114
	s_nop 0
	s_nop 0
	v_add_u32_e32 v2, s51, v2
	ds_read_b128 v[2:5], v2 offset:8304
	s_waitcnt lgkmcnt(0)
	v_lshlrev_b64 v[2:3], 2, v[22:23]
	v_fma_f32 v55, -v5, v54, v55
	v_fma_f32 v114, -v5, v105, v114
	v_lshl_add_u64 v[4:5], s[2:3], 0, v[2:3]
	flat_store_dword v[4:5], v24
	v_lshlrev_b64 v[4:5], 2, v[22:23]
	v_lshl_add_u64 v[6:7], s[2:3], 0, v[4:5]
	s_add_u32 s2, s0, 0x4800
	s_addc_u32 s3, s1, 0
	v_lshl_add_u64 v[2:3], s[2:3], 0, v[2:3]
	flat_store_dword v[6:7], v25 offset:256
	flat_store_dword v[6:7], v26 offset:512
	flat_store_dword v[6:7], v27 offset:768
	flat_store_dword v[6:7], v28 offset:1024
	flat_store_dword v[6:7], v29 offset:1280
	flat_store_dword v[6:7], v30 offset:1536
	flat_store_dword v[6:7], v31 offset:1792
	flat_store_dword v[6:7], v32 offset:2048
	flat_store_dword v[6:7], v33 offset:2304
	flat_store_dword v[6:7], v34 offset:2560
	flat_store_dword v[6:7], v35 offset:2816
	flat_store_dword v[6:7], v36 offset:3072
	flat_store_dword v[6:7], v37 offset:3328
	flat_store_dword v[6:7], v38 offset:3584
	flat_store_dword v[6:7], v39 offset:3840
	flat_store_dword v[2:3], v40
	v_lshl_add_u64 v[2:3], s[2:3], 0, v[4:5]
	flat_store_dword v[2:3], v41 offset:256
	flat_store_dword v[2:3], v42 offset:512
	flat_store_dword v[2:3], v43 offset:768
	flat_store_dword v[2:3], v46 offset:1024
	flat_store_dword v[2:3], v47 offset:1280
	flat_store_dword v[2:3], v48 offset:1536
	flat_store_dword v[2:3], v49 offset:1792
	flat_store_dword v[2:3], v44 offset:2048
	flat_store_dword v[2:3], v45 offset:2304
	flat_store_dword v[2:3], v50 offset:2560
	flat_store_dword v[2:3], v51 offset:2816
	flat_store_dword v[2:3], v52 offset:3072
	flat_store_dword v[2:3], v53 offset:3328
	flat_store_dword v[2:3], v54 offset:3584
	flat_store_dword v[2:3], v55 offset:3840
	v_bfe_u32 v2, v22, 2, 1
	s_mov_b32 s2, 0x7ffffe
	v_and_or_b32 v2, v21, s2, v2
	v_and_b32_e32 v3, 6, v87
	v_and_b32_e32 v4, 8, v22
	v_lshl_add_u32 v2, v2, 9, s51
	v_add3_u32 v2, v2, v4, v3
	v_cvt_pk_bf16_f32 v3, -v88, s0
	s_waitcnt lgkmcnt(0)
	ds_write_b16 v2, v3
	v_cvt_pk_bf16_f32 v3, -v90, s0
	ds_write_b16 v2, v3 offset:16
	v_cvt_pk_bf16_f32 v3, -v89, s0
	ds_write_b16 v2, v3 offset:32
	v_cvt_pk_bf16_f32 v3, -v91, s0
	ds_write_b16 v2, v3 offset:48
	v_cvt_pk_bf16_f32 v3, -v92, s0
	ds_write_b16 v2, v3 offset:64
	v_cvt_pk_bf16_f32 v3, -v93, s0
	ds_write_b16 v2, v3 offset:80
	v_cvt_pk_bf16_f32 v3, -v94, s0
	ds_write_b16 v2, v3 offset:96
	v_cvt_pk_bf16_f32 v3, -v95, s0
	ds_write_b16 v2, v3 offset:112
	v_cvt_pk_bf16_f32 v3, -v98, s0
	ds_write_b16 v2, v3 offset:128
	v_cvt_pk_bf16_f32 v3, -v97, s0
	ds_write_b16 v2, v3 offset:144
	v_cvt_pk_bf16_f32 v3, -v100, s0
	ds_write_b16 v2, v3 offset:160
	v_cvt_pk_bf16_f32 v3, -v99, s0
	ds_write_b16 v2, v3 offset:176
	v_cvt_pk_bf16_f32 v3, -v104, s0
	ds_write_b16 v2, v3 offset:192
	v_cvt_pk_bf16_f32 v3, -v103, s0
	ds_write_b16 v2, v3 offset:208
	v_cvt_pk_bf16_f32 v3, -v107, s0
	ds_write_b16 v2, v3 offset:224
	v_cvt_pk_bf16_f32 v3, -v106, s0
	ds_write_b16 v2, v3 offset:240
	v_cvt_pk_bf16_f32 v3, -v111, s0
	ds_write_b16 v2, v3 offset:256
	v_cvt_pk_bf16_f32 v3, -v110, s0
	ds_write_b16 v2, v3 offset:272
	v_cvt_pk_bf16_f32 v3, -v113, s0
	ds_write_b16 v2, v3 offset:288
	v_cvt_pk_bf16_f32 v3, -v112, s0
	ds_write_b16 v2, v3 offset:304
	v_cvt_pk_bf16_f32 v3, -v121, s0
	ds_write_b16 v2, v3 offset:320
	v_cvt_pk_bf16_f32 v3, -v120, s0
	ds_write_b16 v2, v3 offset:336
	v_cvt_pk_bf16_f32 v3, -v123, s0
	ds_write_b16 v2, v3 offset:352
	v_cvt_pk_bf16_f32 v3, -v122, s0
	ds_write_b16 v2, v3 offset:368
	v_cvt_pk_bf16_f32 v3, -v74, s0
	ds_write_b16 v2, v3 offset:384
	v_cvt_pk_bf16_f32 v3, -v75, s0
	ds_write_b16 v2, v3 offset:400
	v_cvt_pk_bf16_f32 v3, -v76, s0
	ds_write_b16 v2, v3 offset:416
	v_cvt_pk_bf16_f32 v3, -v77, s0
	ds_write_b16 v2, v3 offset:432
	v_cvt_pk_bf16_f32 v3, -v78, s0
	ds_write_b16 v2, v3 offset:448
	v_cvt_pk_bf16_f32 v3, -v79, s0
	ds_write_b16 v2, v3 offset:464
	v_cvt_pk_bf16_f32 v3, -v105, s0
	ds_write_b16 v2, v3 offset:480
	v_cvt_pk_bf16_f32 v3, -v114, s0
	ds_write_b16 v2, v3 offset:496
	s_waitcnt lgkmcnt(0)
	ds_read_b128 v[2:5], v8
	v_lshl_add_u64 v[6:7], s[0:1], 0, v[56:57]
	v_readlane_b32 s3, v245, 63
	s_add_i32 s76, s76, s3
	s_add_i32 s10, s10, s11
	s_waitcnt lgkmcnt(0)
	flat_store_dwordx4 v[6:7], v[2:5]
	ds_read_b128 v[2:5], v8 offset:1024
	s_mul_i32 s2, s3, 0x5a00
	s_add_u32 s0, s0, s2
	s_mul_hi_i32 s2, s3, 0x5a00
	s_addc_u32 s1, s1, s2
	s_waitcnt lgkmcnt(0)
	flat_store_dwordx4 v[6:7], v[2:5] offset:1024
	ds_read_b128 v[2:5], v8 offset:2048
	s_cmpk_gt_i32 s76, 0xfff
	s_waitcnt lgkmcnt(0)
	flat_store_dwordx4 v[6:7], v[2:5] offset:2048
	ds_read_b128 v[2:5], v8 offset:3072
	s_waitcnt lgkmcnt(0)
	flat_store_dwordx4 v[6:7], v[2:5] offset:3072
	s_waitcnt lgkmcnt(0)
	s_cbranch_scc1 .LBB0_1077
